# B0 fragment LDS reads moved from phase 1 to phase 8 of previous K-iteration (5 GEMM copies), epilogue temps renamed to v250-255; static prio + no setprio flips
# speedup vs baseline: 1.0521x; 1.0068x over previous
; __device__ __forceinline__ f32x4 zero4() { float z = 0.f; asm volatile("" : "+v"(z)); return (f32x4){z, z, z, z}; }
; #define G_STAGE(bufoff, gbase) do { _Pragma("unroll") for (int _i = 0; _i < 2; ++_i) \
;     __builtin_amdgcn_global_load_lds((const unsigned*)((const char*)(gbase) + voff[_i]), (GLAS unsigned*)(lds + (bufoff) + ldsw + _i * 8192), 16, 0, 0); } while (0)
; #define G_WAIT_V(n) asm volatile("s_waitcnt vmcnt(" #n ")" ::: "memory")
; __device__ __forceinline__ void gemm_phase(const Params& p, int l, const bf16_t* __restrict__ A, const bf16_t* __restrict__ Bt, int M, int N, int K,
;                            int epi, bf16_t* __restrict__ outp, char* smem, int wvi) {
;     ...
;   for (int i = 0; i < 2; ++i) { int R, C; stage_rc(tidx * 16 + i * 8192, R, C); voff[i] = (unsigned)(R * K + C) * 2u; }
;   const size_t kstep = (size_t)(GBK * 2), hstep = (size_t)GHALF * K * 2, tstep = 2 * hstep;
;   const unsigned ldsw = (unsigned)wid * 1024u;
;   const int aoff = lds_byte(wr * 64 + fr, fq * 8), boff = lds_byte(wc * 32 + fr, fq * 8);
;   constexpr int HTB = GHT * 2;
;     ...
;   const int nM = M / GBM, nN = N / GBM, nwg = nM * nN;
;   auto tile_of = [&](int Lw, int& pm_, int& pn_) {
;     int wgid = Lw;
;     { const int q = nwg / GNXCD, r = nwg % GNXCD, xcd = wgid % GNXCD, off = wgid / GNXCD; wgid = (xcd < r ? xcd * (q + 1) : r * (q + 1) + (xcd - r) * q) + off; }
;     const int nig = GWGM * nN, gid = wgid / nig, fm = gid * GWGM, gsz = min(nM - fm, GWGM);
;     pm_ = fm + ((wgid % nig) % gsz); pn_ = (wgid % nig) / gsz;
;   };
;   int Lw = blockIdx.x;
;   if (Lw < nwg) {
;     int pm, pn; tile_of(Lw, pm, pn);
;     const char* cA = (const char*)A + (size_t)pm * tstep;
;     const char* cB = (const char*)Bt + (size_t)pn * tstep;
;     f32x4 acc[2][2][4][2];
; #pragma unroll
;     for (int a = 0; a < 2; ++a)
; #pragma unroll
;       for (int b = 0; b < 2; ++b)
; #pragma unroll
;         for (int m = 0; m < 4; ++m)
; #pragma unroll
;           for (int n = 0; n < 2; ++n) acc[a][b][m][n] = zero4();
;     bf16x8 At[4][2], B0[2][2], B1[2][2];
;     G_STAGE(G_SB(0, 0), cB); G_STAGE(G_SA(0, 0), cA); G_STAGE(G_SB(0, 1), cB + hstep); G_STAGE(G_SA(0, 1), cA + hstep);
;     if (wr == 1) G_BAR;
;     G_WAIT_V(4); G_BAR;
;     G_STAGE(G_SB(1, 0), cB + kstep); G_STAGE(G_SA(1, 0), cA + kstep); G_STAGE(G_SB(1, 1), cB + hstep + kstep);
;     G_WAIT_V(6); G_BAR;
.LBB0_116:
	v_lshl_add_u64 v[34:35], s[2:3], 0, v[176:177]
	v_mov_b32_e32 v129, v177
	v_lshl_add_u64 v[38:39], s[2:3], 0, v[128:129]
	v_lshl_add_u64 v[34:35], v[34:35], 0, s[64:65]
	s_add_i32 m0, s22, 0x18000
	v_lshl_add_u64 v[46:47], s[10:11], 0, v[176:177]
	s_waitcnt vmcnt(4)
	s_barrier
	global_load_lds_dwordx4 v[34:35], off
	v_lshl_add_u64 v[34:35], v[38:39], 0, s[64:65]
	s_add_i32 m0, s22, 0x1a000
	s_add_i32 s0, s22, 0x8000
	s_add_i32 s1, s22, 0xa000
	v_lshl_add_u64 v[50:51], s[10:11], 0, v[128:129]
	global_load_lds_dwordx4 v[34:35], off
	v_lshl_add_u64 v[34:35], v[46:47], 0, s[64:65]
	s_mov_b32 m0, s0
	s_add_u32 s2, s2, 0xb0080
	global_load_lds_dwordx4 v[34:35], off
	v_lshl_add_u64 v[34:35], v[50:51], 0, s[64:65]
	s_mov_b32 m0, s1
	s_addc_u32 s3, s3, 0
	global_load_lds_dwordx4 v[34:35], off
	v_lshl_add_u64 v[34:35], s[2:3], 0, v[176:177]
	s_add_i32 m0, s22, 0x1c000
	v_and_b32_e32 v131, 15, v130
	global_load_lds_dwordx4 v[34:35], off
	v_lshl_add_u64 v[34:35], s[2:3], 0, v[128:129]
	s_add_i32 m0, s22, 0x1e000
	v_readlane_b32 s2, v248, 10
	global_load_lds_dwordx4 v[34:35], off
	s_nop 0
	v_or_b32_e32 v136, s2, v131
	v_lshlrev_b32_e32 v137, 6, v136
	v_and_b32_e32 v142, 48, v130
	s_movk_i32 s2, 0x3c0
	v_lshlrev_b32_e32 v143, 2, v136
	v_and_or_b32 v137, v137, s2, v142
	v_and_b32_e32 v143, 32, v143
	v_readlane_b32 s2, v248, 11
	v_lshlrev_b32_e32 v130, 2, v130
	v_lshl_or_b32 v131, v131, 6, v142
	v_bitop3_b32 v144, v137, s2, v143 bitop3:0xde
	v_and_b32_e32 v130, 32, v130
	v_readlane_b32 s2, v248, 12
	s_sext_i32_i8 s30, s4
	s_movk_i32 s4, 0xb00
	v_bitop3_b32 v137, v131, s2, v130 bitop3:0xde
	v_readlane_b32 s2, v248, 15
	v_mov_b32_e32 v143, v177
	v_readlane_b32 s3, v248, 16
	v_lshrrev_b32_e32 v133, 1, v133
	v_mul_lo_u32 v132, v132, s4
	s_mov_b32 s5, 0xb000
	v_lshl_add_u64 v[130:131], s[2:3], 0, v[142:143]
	v_mad_u64_u32 v[132:133], s[2:3], v133, s5, v[132:133]
	v_or_b32_e32 v132, v132, v140
	v_lshrrev_b32_e32 v140, 1, v134
	v_mul_lo_u32 v134, v135, s4
	v_mad_u64_u32 v[134:135], s[2:3], v140, s5, v[134:135]
	s_waitcnt vmcnt(6)
	v_or_b32_e32 v134, v134, v138
	v_add_lshl_u32 v132, v132, v141, 1
	v_mov_b32_e32 v133, v177
	s_mov_b64 s[6:7], 0xb0080
	v_add_lshl_u32 v134, v134, v139, 1
	v_mov_b32_e32 v135, v177
	v_mov_b32_e32 v21, v20
	v_mov_b32_e32 v22, v20
	v_mov_b32_e32 v23, v20
	v_mov_b32_e32 v29, v28
	v_mov_b32_e32 v30, v28
	v_mov_b32_e32 v31, v28
	v_mov_b32_e32 v13, v12
	v_mov_b32_e32 v14, v12
	v_mov_b32_e32 v15, v12
	v_mov_b32_e32 v25, v24
	v_mov_b32_e32 v26, v24
	v_mov_b32_e32 v27, v24
	v_mov_b32_e32 v5, v4
	v_mov_b32_e32 v6, v4
	v_mov_b32_e32 v7, v4
	v_mov_b32_e32 v17, v16
	v_mov_b32_e32 v18, v16
	v_mov_b32_e32 v19, v16
	v_mov_b32_e32 v1, v0
	v_mov_b32_e32 v2, v0
	v_mov_b32_e32 v3, v0
	v_mov_b32_e32 v9, v8
	v_mov_b32_e32 v10, v8
	v_mov_b32_e32 v11, v8
	v_mov_b32_e32 v81, v80
	v_mov_b32_e32 v82, v80
	v_mov_b32_e32 v83, v80
	v_mov_b32_e32 v93, v92
	v_mov_b32_e32 v94, v92
	v_mov_b32_e32 v95, v92
	v_mov_b32_e32 v65, v64
	v_mov_b32_e32 v66, v64
	v_mov_b32_e32 v67, v64
	v_mov_b32_e32 v85, v84
	v_mov_b32_e32 v86, v84
	v_mov_b32_e32 v87, v84
	v_mov_b32_e32 v53, v52
	v_mov_b32_e32 v54, v52
	v_mov_b32_e32 v55, v52
	v_mov_b32_e32 v77, v76
	v_mov_b32_e32 v78, v76
	v_mov_b32_e32 v79, v76
	v_mov_b32_e32 v41, v40
	v_mov_b32_e32 v42, v40
	v_mov_b32_e32 v43, v40
	v_mov_b32_e32 v61, v60
	v_mov_b32_e32 v62, v60
	v_mov_b32_e32 v63, v60
	v_mov_b32_e32 v69, v68
	v_mov_b32_e32 v70, v68
	v_mov_b32_e32 v71, v68
	v_mov_b32_e32 v89, v88
	v_mov_b32_e32 v90, v88
	v_mov_b32_e32 v91, v88
	v_mov_b32_e32 v49, v48
	v_mov_b32_e32 v50, v48
	v_mov_b32_e32 v51, v48
	v_mov_b32_e32 v73, v72
	v_mov_b32_e32 v74, v72
	v_mov_b32_e32 v75, v72
	v_mov_b32_e32 v37, v36
	v_mov_b32_e32 v38, v36
	v_mov_b32_e32 v39, v36
	v_mov_b32_e32 v57, v56
	v_mov_b32_e32 v58, v56
	v_mov_b32_e32 v59, v56
	v_mov_b32_e32 v33, v32
	v_mov_b32_e32 v34, v32
	v_mov_b32_e32 v35, v32
	v_mov_b32_e32 v45, v44
	v_mov_b32_e32 v46, v44
	v_mov_b32_e32 v47, v44
	v_mov_b32_e32 v121, v120
	v_mov_b32_e32 v122, v120
	v_mov_b32_e32 v123, v120
	v_mov_b32_e32 v125, v124
	v_mov_b32_e32 v126, v124
	v_mov_b32_e32 v127, v124
	v_mov_b32_e32 v113, v112
	v_mov_b32_e32 v114, v112
	v_mov_b32_e32 v115, v112
	v_mov_b32_e32 v117, v116
	v_mov_b32_e32 v118, v116
	v_mov_b32_e32 v119, v116
	v_mov_b32_e32 v105, v104
	v_mov_b32_e32 v106, v104
	v_mov_b32_e32 v107, v104
	v_mov_b32_e32 v109, v108
	v_mov_b32_e32 v110, v108
	v_mov_b32_e32 v111, v108
	v_mov_b32_e32 v97, v96
	v_mov_b32_e32 v98, v96
	v_mov_b32_e32 v99, v96
	v_mov_b32_e32 v101, v100
	v_mov_b32_e32 v102, v100
	v_mov_b32_e32 v103, v100
	v_lshl_add_u64 v[132:133], v[132:133], 0, s[6:7]
	v_lshl_add_u64 v[134:135], v[134:135], 0, s[6:7]
	v_add_u32_e32 v138, 0, v144
	v_readlane_b32 s26, v248, 0
	s_mov_b32 s28, s29
	s_mov_b32 s27, s30
	s_barrier
	v_add_u32_e32 v139, 0x10000, v137
	ds_read_b128 v[140:143], v139
	ds_read_b128 v[144:147], v139 offset:1024
	ds_read_b128 v[148:151], v139 offset:2048
	ds_read_b128 v[152:155], v139 offset:3072
	s_branch .LBB0_118

; #define G_STAGE(bufoff, gbase) do { _Pragma("unroll") for (int _i = 0; _i < 2; ++_i) \
;     __builtin_amdgcn_global_load_lds((const unsigned*)((const char*)(gbase) + voff[_i]), (GLAS unsigned*)(lds + (bufoff) + ldsw + _i * 8192), 16, 0, 0); } while (0)
; #define G_LDA(dst, b, h) do { _Pragma("unroll") for (int m = 0; m < 4; ++m) _Pragma("unroll") for (int k = 0; k < 2; ++k) \
;     dst[m][k] = *(const GLAS bf16x8*)(lds + G_SA(b, h) + aoff + m * 2048 + k * 1024); } while (0)
; #define G_LDB(dst, b, h) do { _Pragma("unroll") for (int n = 0; n < 2; ++n) _Pragma("unroll") for (int k = 0; k < 2; ++k) \
;     dst[n][k] = *(const GLAS bf16x8*)(lds + G_SB(b, h) + boff + n * 2048 + k * 1024); } while (0)
; #define G_MMA(ai, bj, At_, Bt_) do { __builtin_amdgcn_s_setprio(1); \
;     _Pragma("unroll") for (int m = 0; m < 4; ++m) _Pragma("unroll") for (int n = 0; n < 2; ++n) _Pragma("unroll") for (int k = 0; k < 2; ++k) \
;       acc[ai][bj][m][n] = __builtin_amdgcn_mfma_f32_16x16x32_bf16(Bt_[n][k], At_[m][k], acc[ai][bj][m][n], 0, 0, 0); \
;     __builtin_amdgcn_s_setprio(0); } while (0)
; #define G_WAIT_V(n) asm volatile("s_waitcnt vmcnt(" #n ")" ::: "memory")
; #define G_WAIT_L(n) asm volatile("s_waitcnt lgkmcnt(" #n ")" ::: "memory")
; #define G_BAR __builtin_amdgcn_s_barrier()
; __device__ __forceinline__ void gemm_phase(const Params& p, int l, const bf16_t* __restrict__ A, const bf16_t* __restrict__ Bt, int M, int N, int K,
;                            int epi, bf16_t* __restrict__ outp, char* smem, int wvi) {
;     ...
;       for (int t = 0; t < nt; t += 2) {
;         const bool lastt = (t == nt - 2);
;         const char* a1 = cA + (size_t)(t + 1) * kstep;
;         const char* a2 = lastt ? nA : cA + (size_t)(t + 2) * kstep; const char* b2 = lastt ? nB : cB + (size_t)(t + 2) * kstep;
;         const char* a3 = a2 + kstep; const char* b3 = b2 + kstep;
;         G_LDB(B0, 0, 0); G_SCHED; G_LDA(At, 0, 0); G_STAGE(G_SA(1, 1), a1 + hstep);
;         G_WAIT_L(8); G_BAR; G_WAIT_L(0); G_MMA(0, 0, At, B0); G_BAR; G_SCHED;
;         G_LDB(B1, 0, 1); G_STAGE(G_SB(0, 0), b2);
;         G_BAR; G_WAIT_L(0); G_MMA(0, 1, At, B1); G_BAR;
;         G_LDA(At, 0, 1); G_STAGE(G_SA(0, 0), a2);
;         G_BAR; G_WAIT_L(0); G_MMA(1, 0, At, B0); G_BAR; G_SCHED;
;         G_STAGE(G_SB(0, 1), b2 + hstep);
;         G_WAIT_V(6); G_BAR; G_MMA(1, 1, At, B1); G_BAR;
.LBB0_121:
	s_add_u32 s2, s10, 0x100
	s_addc_u32 s3, s11, 0
	s_add_i32 s34, 0, 0x10000
	s_cmp_eq_u32 s67, 40
	s_cselect_b32 s15, s5, s3
	s_cselect_b32 s14, s4, s2
	s_cselect_b32 s13, s53, s63
	s_cselect_b32 s12, s31, s55
	v_lshl_add_u64 v[190:191], s[10:11], 0, v[132:133]
	s_add_i32 m0, s22, 0xc000
	ds_read_b128 v[156:159], v138
	ds_read_b128 v[160:163], v138 offset:1024
	ds_read_b128 v[164:167], v138 offset:2048
	ds_read_b128 v[168:171], v138 offset:3072
	ds_read_b128 v[172:175], v138 offset:4096
	ds_read_b128 v[182:185], v138 offset:5120
	ds_read_b128 v[186:189], v138 offset:6144
	ds_read_b128 v[214:217], v138 offset:7168
	global_load_lds_dwordx4 v[190:191], off
	v_lshl_add_u64 v[190:191], s[10:11], 0, v[134:135]
	s_add_i32 m0, s22, 0xe000
	s_nop 0
	global_load_lds_dwordx4 v[190:191], off
	s_waitcnt lgkmcnt(8)
	s_barrier
	s_waitcnt lgkmcnt(0)
	s_waitcnt lgkmcnt(0)
	v_mfma_f32_16x16x32_bf16 v[20:23], v[140:143], v[156:159], v[20:23]
	v_mfma_f32_16x16x32_bf16 v[28:31], v[148:151], v[156:159], v[28:31]
	v_mfma_f32_16x16x32_bf16 v[12:15], v[140:143], v[164:167], v[12:15]
	v_mfma_f32_16x16x32_bf16 v[24:27], v[148:151], v[164:167], v[24:27]
	v_mfma_f32_16x16x32_bf16 v[4:7], v[140:143], v[172:175], v[4:7]
	v_mfma_f32_16x16x32_bf16 v[16:19], v[148:151], v[172:175], v[16:19]
	v_mfma_f32_16x16x32_bf16 v[0:3], v[140:143], v[186:189], v[0:3]
	v_mfma_f32_16x16x32_bf16 v[8:11], v[148:151], v[186:189], v[8:11]
	v_mfma_f32_16x16x32_bf16 v[20:23], v[144:147], v[160:163], v[20:23]
	v_mfma_f32_16x16x32_bf16 v[28:31], v[152:155], v[160:163], v[28:31]
	v_mfma_f32_16x16x32_bf16 v[12:15], v[144:147], v[168:171], v[12:15]
	v_mfma_f32_16x16x32_bf16 v[24:27], v[152:155], v[168:171], v[24:27]
	v_mfma_f32_16x16x32_bf16 v[4:7], v[144:147], v[182:185], v[4:7]
	v_mfma_f32_16x16x32_bf16 v[16:19], v[152:155], v[182:185], v[16:19]
	v_mfma_f32_16x16x32_bf16 v[0:3], v[144:147], v[214:217], v[0:3]
	v_mfma_f32_16x16x32_bf16 v[8:11], v[152:155], v[214:217], v[8:11]
	s_barrier
	s_add_i32 s35, 0, 0x14000
	s_add_i32 s10, s34, s58
	v_add_u32_e32 v139, s35, v137
	v_lshl_add_u64 v[190:191], s[12:13], 0, v[176:177]
	s_mov_b32 m0, s10
	ds_read_b128 v[218:221], v139
	ds_read_b128 v[222:225], v139 offset:1024
	ds_read_b128 v[226:229], v139 offset:2048
	ds_read_b128 v[230:233], v139 offset:3072
	global_load_lds_dwordx4 v[190:191], off
	v_lshl_add_u64 v[234:235], s[12:13], 0, v[128:129]
	s_add_i32 m0, s10, 0x2000
	s_nop 0
	global_load_lds_dwordx4 v[234:235], off
	s_barrier
	s_waitcnt lgkmcnt(0)
	s_waitcnt lgkmcnt(0)
	v_mfma_f32_16x16x32_bf16 v[80:83], v[218:221], v[156:159], v[80:83]
	v_mfma_f32_16x16x32_bf16 v[92:95], v[226:229], v[156:159], v[92:95]
	v_mfma_f32_16x16x32_bf16 v[64:67], v[218:221], v[164:167], v[64:67]
	v_mfma_f32_16x16x32_bf16 v[84:87], v[226:229], v[164:167], v[84:87]
	v_mfma_f32_16x16x32_bf16 v[52:55], v[218:221], v[172:175], v[52:55]
	v_mfma_f32_16x16x32_bf16 v[76:79], v[226:229], v[172:175], v[76:79]
	v_mfma_f32_16x16x32_bf16 v[40:43], v[218:221], v[186:189], v[40:43]
	v_mfma_f32_16x16x32_bf16 v[60:63], v[226:229], v[186:189], v[60:63]
	v_mfma_f32_16x16x32_bf16 v[80:83], v[222:225], v[160:163], v[80:83]
	v_mfma_f32_16x16x32_bf16 v[92:95], v[230:233], v[160:163], v[92:95]
	v_mfma_f32_16x16x32_bf16 v[64:67], v[222:225], v[168:171], v[64:67]
	v_mfma_f32_16x16x32_bf16 v[84:87], v[230:233], v[168:171], v[84:87]
	v_mfma_f32_16x16x32_bf16 v[52:55], v[222:225], v[182:185], v[52:55]
	v_mfma_f32_16x16x32_bf16 v[76:79], v[230:233], v[182:185], v[76:79]
	v_mfma_f32_16x16x32_bf16 v[40:43], v[222:225], v[214:217], v[40:43]
	v_mfma_f32_16x16x32_bf16 v[60:63], v[230:233], v[214:217], v[60:63]
	s_mov_b32 m0, s22
	v_lshl_add_u64 v[236:237], s[14:15], 0, v[176:177]
	s_barrier
	ds_read_b128 v[156:159], v138 offset:16384
	ds_read_b128 v[160:163], v138 offset:17408
	ds_read_b128 v[164:167], v138 offset:18432
	ds_read_b128 v[168:171], v138 offset:19456
	ds_read_b128 v[172:175], v138 offset:20480
	ds_read_b128 v[182:185], v138 offset:21504
	ds_read_b128 v[186:189], v138 offset:22528
	ds_read_b128 v[214:217], v138 offset:23552
	global_load_lds_dwordx4 v[236:237], off
	v_lshl_add_u64 v[238:239], s[14:15], 0, v[128:129]
	s_mov_b32 m0, s23
	s_nop 0
	global_load_lds_dwordx4 v[238:239], off
	s_barrier
	s_waitcnt lgkmcnt(0)
	s_waitcnt lgkmcnt(0)
	v_mfma_f32_16x16x32_bf16 v[68:71], v[140:143], v[156:159], v[68:71]
	v_mfma_f32_16x16x32_bf16 v[88:91], v[148:151], v[156:159], v[88:91]
	v_mfma_f32_16x16x32_bf16 v[48:51], v[140:143], v[164:167], v[48:51]
	v_mfma_f32_16x16x32_bf16 v[72:75], v[148:151], v[164:167], v[72:75]
	v_mfma_f32_16x16x32_bf16 v[36:39], v[140:143], v[172:175], v[36:39]
	v_mfma_f32_16x16x32_bf16 v[56:59], v[148:151], v[172:175], v[56:59]
	v_mfma_f32_16x16x32_bf16 v[32:35], v[140:143], v[186:189], v[32:35]
	v_mfma_f32_16x16x32_bf16 v[44:47], v[148:151], v[186:189], v[44:47]
	v_mfma_f32_16x16x32_bf16 v[68:71], v[144:147], v[160:163], v[68:71]
	v_mfma_f32_16x16x32_bf16 v[88:91], v[152:155], v[160:163], v[88:91]
	v_mfma_f32_16x16x32_bf16 v[48:51], v[144:147], v[168:171], v[48:51]
	v_mfma_f32_16x16x32_bf16 v[72:75], v[152:155], v[168:171], v[72:75]
	v_mfma_f32_16x16x32_bf16 v[36:39], v[144:147], v[182:185], v[36:39]
	v_mfma_f32_16x16x32_bf16 v[56:59], v[152:155], v[182:185], v[56:59]
	v_mfma_f32_16x16x32_bf16 v[32:35], v[144:147], v[214:217], v[32:35]
	v_mfma_f32_16x16x32_bf16 v[44:47], v[152:155], v[214:217], v[44:47]
	s_barrier
	s_add_u32 s10, s12, 0xb0000
	s_addc_u32 s11, s13, 0
	s_add_i32 s34, s35, s58
	v_lshl_add_u64 v[140:141], s[10:11], 0, v[176:177]
	s_mov_b32 m0, s34
	s_nop 0
	global_load_lds_dwordx4 v[140:141], off
	v_lshl_add_u64 v[140:141], s[10:11], 0, v[128:129]
	s_add_i32 m0, s34, 0x2000
	s_nop 0
	global_load_lds_dwordx4 v[140:141], off
	s_waitcnt vmcnt(6)
	s_barrier
; #define G_STAGE(bufoff, gbase) do { _Pragma("unroll") for (int _i = 0; _i < 2; ++_i) \
;     __builtin_amdgcn_global_load_lds((const unsigned*)((const char*)(gbase) + voff[_i]), (GLAS unsigned*)(lds + (bufoff) + ldsw + _i * 8192), 16, 0, 0); } while (0)
; #define G_LDA(dst, b, h) do { _Pragma("unroll") for (int m = 0; m < 4; ++m) _Pragma("unroll") for (int k = 0; k < 2; ++k) \
;     dst[m][k] = *(const GLAS bf16x8*)(lds + G_SA(b, h) + aoff + m * 2048 + k * 1024); } while (0)
; #define G_LDB(dst, b, h) do { _Pragma("unroll") for (int n = 0; n < 2; ++n) _Pragma("unroll") for (int k = 0; k < 2; ++k) \
;     dst[n][k] = *(const GLAS bf16x8*)(lds + G_SB(b, h) + boff + n * 2048 + k * 1024); } while (0)
; #define G_MMA(ai, bj, At_, Bt_) do { __builtin_amdgcn_s_setprio(1); \
;     _Pragma("unroll") for (int m = 0; m < 4; ++m) _Pragma("unroll") for (int n = 0; n < 2; ++n) _Pragma("unroll") for (int k = 0; k < 2; ++k) \
;       acc[ai][bj][m][n] = __builtin_amdgcn_mfma_f32_16x16x32_bf16(Bt_[n][k], At_[m][k], acc[ai][bj][m][n], 0, 0, 0); \
;     __builtin_amdgcn_s_setprio(0); } while (0)
; #define G_WAIT_V(n) asm volatile("s_waitcnt vmcnt(" #n ")" ::: "memory")
; #define G_WAIT_L(n) asm volatile("s_waitcnt lgkmcnt(" #n ")" ::: "memory")
; #define G_BAR __builtin_amdgcn_s_barrier()
; #define G_SCHED __builtin_amdgcn_sched_barrier(0)
; __device__ __forceinline__ void gemm_phase(const Params& p, int l, const bf16_t* __restrict__ A, const bf16_t* __restrict__ Bt, int M, int N, int K,
;                            int epi, bf16_t* __restrict__ outp, char* smem, int wvi) {
;     ...
;         G_WAIT_V(6); G_BAR; G_MMA(1, 1, At, B1); G_BAR;
;         G_LDB(B0, 1, 0); G_SCHED; G_LDA(At, 1, 0); G_STAGE(G_SA(0, 1), a2 + hstep);
;         G_WAIT_L(8); G_BAR; G_WAIT_L(0); G_MMA(0, 0, At, B0); G_BAR; G_SCHED;
;         G_LDB(B1, 1, 1); G_STAGE(G_SB(1, 0), b3);
;         G_BAR; G_WAIT_L(0); G_MMA(0, 1, At, B1); G_BAR;
;         G_LDA(At, 1, 1); G_STAGE(G_SA(1, 0), a3);
;         G_BAR; G_WAIT_L(0); G_MMA(1, 0, At, B0); G_BAR; G_SCHED;
	v_mfma_f32_16x16x32_bf16 v[120:123], v[218:221], v[156:159], v[120:123]
	v_mfma_f32_16x16x32_bf16 v[124:127], v[226:229], v[156:159], v[124:127]
	v_mfma_f32_16x16x32_bf16 v[112:115], v[218:221], v[164:167], v[112:115]
	v_mfma_f32_16x16x32_bf16 v[116:119], v[226:229], v[164:167], v[116:119]
	v_mfma_f32_16x16x32_bf16 v[104:107], v[218:221], v[172:175], v[104:107]
	v_mfma_f32_16x16x32_bf16 v[108:111], v[226:229], v[172:175], v[108:111]
	v_mfma_f32_16x16x32_bf16 v[96:99], v[218:221], v[186:189], v[96:99]
	v_mfma_f32_16x16x32_bf16 v[100:103], v[226:229], v[186:189], v[100:103]
	v_mfma_f32_16x16x32_bf16 v[120:123], v[222:225], v[160:163], v[120:123]
	v_mfma_f32_16x16x32_bf16 v[124:127], v[230:233], v[160:163], v[124:127]
	v_mfma_f32_16x16x32_bf16 v[112:115], v[222:225], v[168:171], v[112:115]
	v_mfma_f32_16x16x32_bf16 v[116:119], v[230:233], v[168:171], v[116:119]
	v_mfma_f32_16x16x32_bf16 v[104:107], v[222:225], v[182:185], v[104:107]
	v_mfma_f32_16x16x32_bf16 v[108:111], v[230:233], v[182:185], v[108:111]
	v_mfma_f32_16x16x32_bf16 v[96:99], v[222:225], v[214:217], v[96:99]
	v_mfma_f32_16x16x32_bf16 v[100:103], v[230:233], v[214:217], v[100:103]
	s_add_i32 s34, 0, 0x18000
	v_add_u32_e32 v139, s34, v137
	s_barrier
	ds_read_b128 v[140:143], v139
	ds_read_b128 v[144:147], v139 offset:1024
	ds_read_b128 v[148:151], v139 offset:2048
	ds_read_b128 v[152:155], v139 offset:3072
	s_add_u32 s10, s14, 0xb0000
	s_addc_u32 s11, s15, 0
	s_mov_b32 m0, s24
	v_lshl_add_u64 v[218:219], s[10:11], 0, v[176:177]
	ds_read_b128 v[156:159], v138 offset:32768
	ds_read_b128 v[160:163], v138 offset:33792
	ds_read_b128 v[164:167], v138 offset:34816
	ds_read_b128 v[168:171], v138 offset:35840
	ds_read_b128 v[172:175], v138 offset:36864
	ds_read_b128 v[182:185], v138 offset:37888
	ds_read_b128 v[186:189], v138 offset:38912
	ds_read_b128 v[214:217], v138 offset:39936
	global_load_lds_dwordx4 v[218:219], off
	v_lshl_add_u64 v[218:219], s[10:11], 0, v[128:129]
	s_mov_b32 m0, s25
	s_nop 0
	global_load_lds_dwordx4 v[218:219], off
	s_waitcnt lgkmcnt(8)
	s_barrier
	s_waitcnt lgkmcnt(0)
	s_waitcnt lgkmcnt(0)
	v_mfma_f32_16x16x32_bf16 v[20:23], v[140:143], v[156:159], v[20:23]
	v_mfma_f32_16x16x32_bf16 v[28:31], v[148:151], v[156:159], v[28:31]
	v_mfma_f32_16x16x32_bf16 v[12:15], v[140:143], v[164:167], v[12:15]
	v_mfma_f32_16x16x32_bf16 v[24:27], v[148:151], v[164:167], v[24:27]
	v_mfma_f32_16x16x32_bf16 v[4:7], v[140:143], v[172:175], v[4:7]
	v_mfma_f32_16x16x32_bf16 v[16:19], v[148:151], v[172:175], v[16:19]
	v_mfma_f32_16x16x32_bf16 v[0:3], v[140:143], v[186:189], v[0:3]
	v_mfma_f32_16x16x32_bf16 v[8:11], v[148:151], v[186:189], v[8:11]
	v_mfma_f32_16x16x32_bf16 v[20:23], v[144:147], v[160:163], v[20:23]
	v_mfma_f32_16x16x32_bf16 v[28:31], v[152:155], v[160:163], v[28:31]
	v_mfma_f32_16x16x32_bf16 v[12:15], v[144:147], v[168:171], v[12:15]
	v_mfma_f32_16x16x32_bf16 v[24:27], v[152:155], v[168:171], v[24:27]
	v_mfma_f32_16x16x32_bf16 v[4:7], v[144:147], v[182:185], v[4:7]
	v_mfma_f32_16x16x32_bf16 v[16:19], v[152:155], v[182:185], v[16:19]
	v_mfma_f32_16x16x32_bf16 v[0:3], v[144:147], v[214:217], v[0:3]
	v_mfma_f32_16x16x32_bf16 v[8:11], v[152:155], v[214:217], v[8:11]
	s_barrier
	s_add_i32 s14, 0, 0x1c000
	s_add_i32 s10, s34, s58
	v_add_u32_e32 v139, s14, v137
	v_lshl_add_u64 v[190:191], v[190:191], 0, s[64:65]
	s_mov_b32 m0, s10
	ds_read_b128 v[218:221], v139
	ds_read_b128 v[222:225], v139 offset:1024
	ds_read_b128 v[226:229], v139 offset:2048
	ds_read_b128 v[230:233], v139 offset:3072
	global_load_lds_dwordx4 v[190:191], off
	v_lshl_add_u64 v[190:191], v[234:235], 0, s[64:65]
	s_add_i32 m0, s10, 0x2000
	s_nop 0
	global_load_lds_dwordx4 v[190:191], off
	s_barrier
	s_waitcnt lgkmcnt(0)
	s_waitcnt lgkmcnt(0)
	v_mfma_f32_16x16x32_bf16 v[80:83], v[218:221], v[156:159], v[80:83]
	v_mfma_f32_16x16x32_bf16 v[92:95], v[226:229], v[156:159], v[92:95]
	v_mfma_f32_16x16x32_bf16 v[64:67], v[218:221], v[164:167], v[64:67]
	v_mfma_f32_16x16x32_bf16 v[84:87], v[226:229], v[164:167], v[84:87]
	v_mfma_f32_16x16x32_bf16 v[52:55], v[218:221], v[172:175], v[52:55]
	v_mfma_f32_16x16x32_bf16 v[76:79], v[226:229], v[172:175], v[76:79]
	v_mfma_f32_16x16x32_bf16 v[40:43], v[218:221], v[186:189], v[40:43]
	v_mfma_f32_16x16x32_bf16 v[60:63], v[226:229], v[186:189], v[60:63]
	v_mfma_f32_16x16x32_bf16 v[80:83], v[222:225], v[160:163], v[80:83]
	v_mfma_f32_16x16x32_bf16 v[92:95], v[230:233], v[160:163], v[92:95]
	v_mfma_f32_16x16x32_bf16 v[64:67], v[222:225], v[168:171], v[64:67]
	v_mfma_f32_16x16x32_bf16 v[84:87], v[230:233], v[168:171], v[84:87]
	v_mfma_f32_16x16x32_bf16 v[52:55], v[222:225], v[182:185], v[52:55]
	v_mfma_f32_16x16x32_bf16 v[76:79], v[230:233], v[182:185], v[76:79]
	v_mfma_f32_16x16x32_bf16 v[40:43], v[222:225], v[214:217], v[40:43]
	v_mfma_f32_16x16x32_bf16 v[60:63], v[230:233], v[214:217], v[60:63]
	s_mov_b32 m0, s0
	v_lshl_add_u64 v[190:191], v[236:237], 0, s[64:65]
	s_barrier
	ds_read_b128 v[156:159], v138 offset:49152
	ds_read_b128 v[160:163], v138 offset:50176
	ds_read_b128 v[164:167], v138 offset:51200
	ds_read_b128 v[168:171], v138 offset:52224
	ds_read_b128 v[172:175], v138 offset:53248
	ds_read_b128 v[182:185], v138 offset:54272
	ds_read_b128 v[186:189], v138 offset:55296
	ds_read_b128 v[214:217], v138 offset:56320
	global_load_lds_dwordx4 v[190:191], off
	v_lshl_add_u64 v[190:191], v[238:239], 0, s[64:65]
	s_mov_b32 m0, s1
	s_nop 0
	global_load_lds_dwordx4 v[190:191], off
	s_waitcnt vmcnt(10)
	s_barrier
; __device__ __forceinline__ u32x4 mk4(unsigned a, unsigned b, unsigned c, unsigned d) { return (u32x4){a, b, c, d}; }
; #define G_STAGE(bufoff, gbase) do { _Pragma("unroll") for (int _i = 0; _i < 2; ++_i) \
;     __builtin_amdgcn_global_load_lds((const unsigned*)((const char*)(gbase) + voff[_i]), (GLAS unsigned*)(lds + (bufoff) + ldsw + _i * 8192), 16, 0, 0); } while (0)
; #define G_MMA(ai, bj, At_, Bt_) do { __builtin_amdgcn_s_setprio(1); \
;     _Pragma("unroll") for (int m = 0; m < 4; ++m) _Pragma("unroll") for (int n = 0; n < 2; ++n) _Pragma("unroll") for (int k = 0; k < 2; ++k) \
;       acc[ai][bj][m][n] = __builtin_amdgcn_mfma_f32_16x16x32_bf16(Bt_[n][k], At_[m][k], acc[ai][bj][m][n], 0, 0, 0); \
;     __builtin_amdgcn_s_setprio(0); } while (0)
; #define G_WAIT_V(n) asm volatile("s_waitcnt vmcnt(" #n ")" ::: "memory")
; #define G_WAIT_L(n) asm volatile("s_waitcnt lgkmcnt(" #n ")" ::: "memory")
; #define G_BAR __builtin_amdgcn_s_barrier()
; #define G_SCHED __builtin_amdgcn_sched_barrier(0)
; __device__ __forceinline__ void gemm_phase(const Params& p, int l, const bf16_t* __restrict__ A, const bf16_t* __restrict__ Bt, int M, int N, int K,
;                            int epi, bf16_t* __restrict__ outp, char* smem, int wvi) {
;     ...
;         G_BAR; G_WAIT_L(0); G_MMA(1, 0, At, B0); G_BAR; G_SCHED;
;         G_STAGE(G_SB(1, 1), b3 + hstep);
;         G_WAIT_V(6); G_BAR; G_MMA(1, 1, At, B1); G_BAR;
;       }
;       const int brow = pm * GBM, bcol = pn * GBM;
;     const int r0 = brow + wr * 64 + fr;
;     if (epi == EPI_PLAIN) {
; #pragma unroll
;       for (int ai = 0; ai < 2; ++ai)
; #pragma unroll
;         for (int m = 0; m < 4; ++m) {
;           bf16_t* rp = outp + (size_t)(r0 + ai * GHALF + m * 16) * N + bcol + wc * 32 + fq * 8;
; #pragma unroll
;           for (int bj = 0; bj < 2; ++bj) {
;             const f32x4 v0 = acc[ai][bj][m][0], v1 = acc[ai][bj][m][1];
;             *reinterpret_cast<u32x4*>(rp + bj * GHALF) = mk4(pk2(v0[0], v0[1]), pk2(v0[2], v0[3]), pk2(v1[0], v1[1]), pk2(v1[2], v1[3]));
	s_waitcnt lgkmcnt(0)
	s_waitcnt lgkmcnt(0)
	v_mfma_f32_16x16x32_bf16 v[68:71], v[140:143], v[156:159], v[68:71]
	v_mfma_f32_16x16x32_bf16 v[88:91], v[148:151], v[156:159], v[88:91]
	v_mfma_f32_16x16x32_bf16 v[48:51], v[140:143], v[164:167], v[48:51]
	v_mfma_f32_16x16x32_bf16 v[72:75], v[148:151], v[164:167], v[72:75]
	v_mfma_f32_16x16x32_bf16 v[36:39], v[140:143], v[172:175], v[36:39]
	v_mfma_f32_16x16x32_bf16 v[56:59], v[148:151], v[172:175], v[56:59]
	v_mfma_f32_16x16x32_bf16 v[32:35], v[140:143], v[186:189], v[32:35]
	v_mfma_f32_16x16x32_bf16 v[44:47], v[148:151], v[186:189], v[44:47]
	v_mfma_f32_16x16x32_bf16 v[68:71], v[144:147], v[160:163], v[68:71]
	v_mfma_f32_16x16x32_bf16 v[88:91], v[152:155], v[160:163], v[88:91]
	v_mfma_f32_16x16x32_bf16 v[48:51], v[144:147], v[168:171], v[48:51]
	v_mfma_f32_16x16x32_bf16 v[72:75], v[152:155], v[168:171], v[72:75]
	v_mfma_f32_16x16x32_bf16 v[36:39], v[144:147], v[182:185], v[36:39]
	v_mfma_f32_16x16x32_bf16 v[56:59], v[152:155], v[182:185], v[56:59]
	v_mfma_f32_16x16x32_bf16 v[32:35], v[144:147], v[214:217], v[32:35]
	v_mfma_f32_16x16x32_bf16 v[44:47], v[152:155], v[214:217], v[44:47]
	s_barrier
	s_add_u32 s10, s12, 0xb0080
	s_addc_u32 s11, s13, 0
	s_add_i32 s12, s14, s58
	v_lshl_add_u64 v[140:141], s[10:11], 0, v[176:177]
	s_mov_b32 m0, s12
	s_nop 0
	global_load_lds_dwordx4 v[140:141], off
	v_lshl_add_u64 v[140:141], s[10:11], 0, v[128:129]
	s_add_i32 m0, s12, 0x2000
	s_nop 0
	global_load_lds_dwordx4 v[140:141], off
	v_add_u32_e32 v139, 0x10000, v137
	ds_read_b128 v[140:143], v139
	ds_read_b128 v[144:147], v139 offset:1024
	ds_read_b128 v[148:151], v139 offset:2048
	ds_read_b128 v[152:155], v139 offset:3072
	s_waitcnt vmcnt(6)
	s_barrier
	v_mfma_f32_16x16x32_bf16 v[120:123], v[218:221], v[156:159], v[120:123]
	v_mfma_f32_16x16x32_bf16 v[124:127], v[226:229], v[156:159], v[124:127]
	v_mfma_f32_16x16x32_bf16 v[112:115], v[218:221], v[164:167], v[112:115]
	v_mfma_f32_16x16x32_bf16 v[116:119], v[226:229], v[164:167], v[116:119]
	v_mfma_f32_16x16x32_bf16 v[104:107], v[218:221], v[172:175], v[104:107]
	v_mfma_f32_16x16x32_bf16 v[108:111], v[226:229], v[172:175], v[108:111]
	v_mfma_f32_16x16x32_bf16 v[96:99], v[218:221], v[186:189], v[96:99]
	v_mfma_f32_16x16x32_bf16 v[100:103], v[226:229], v[186:189], v[100:103]
	v_mfma_f32_16x16x32_bf16 v[120:123], v[222:225], v[160:163], v[120:123]
	v_mfma_f32_16x16x32_bf16 v[124:127], v[230:233], v[160:163], v[124:127]
	v_mfma_f32_16x16x32_bf16 v[112:115], v[222:225], v[168:171], v[112:115]
	v_mfma_f32_16x16x32_bf16 v[116:119], v[230:233], v[168:171], v[116:119]
	v_mfma_f32_16x16x32_bf16 v[104:107], v[222:225], v[182:185], v[104:107]
	v_mfma_f32_16x16x32_bf16 v[108:111], v[230:233], v[182:185], v[108:111]
	v_mfma_f32_16x16x32_bf16 v[96:99], v[222:225], v[214:217], v[96:99]
	v_mfma_f32_16x16x32_bf16 v[100:103], v[230:233], v[214:217], v[100:103]
	s_add_i32 s67, s67, 2
	s_add_u32 s55, s55, 0x100
	s_addc_u32 s63, s63, 0
	s_cmp_gt_u32 s67, 41
	s_mov_b64 s[10:11], s[2:3]
	s_barrier
	s_cbranch_scc0 .LBB0_121
	s_lshl_b32 s2, s30, 8
	v_lshl_add_u32 v250, s29, 8, v136
	s_ashr_i32 s3, s2, 31
	v_ashrrev_i32_e32 v251, 31, v250
	v_lshl_add_u64 v[252:253], s[2:3], 1, v[130:131]
	v_lshlrev_b64 v[254:255], 11, v[250:251]
	v_lshl_add_u64 v[254:255], v[252:253], 0, v[254:255]
	v_cvt_pk_bf16_f32 v20, v20, v21
	v_cvt_pk_bf16_f32 v21, v22, v23
	v_cvt_pk_bf16_f32 v22, v28, v29
	v_cvt_pk_bf16_f32 v23, v30, v31
	global_store_dwordx4 v[254:255], v[20:23], off
	v_cvt_pk_bf16_f32 v12, v12, v13
	v_cvt_pk_bf16_f32 v13, v14, v15
	v_cvt_pk_bf16_f32 v20, v80, v81
	v_cvt_pk_bf16_f32 v21, v82, v83
	v_cvt_pk_bf16_f32 v22, v92, v93
	v_cvt_pk_bf16_f32 v23, v94, v95
	global_store_dwordx4 v[254:255], v[20:23], off offset:256
	v_cvt_pk_bf16_f32 v14, v24, v25
	v_cvt_pk_bf16_f32 v15, v26, v27
	v_or_b32_e32 v20, 16, v250
	v_ashrrev_i32_e32 v21, 31, v20
	v_lshlrev_b64 v[20:21], 11, v[20:21]
	v_lshl_add_u64 v[20:21], v[252:253], 0, v[20:21]
	global_store_dwordx4 v[20:21], v[12:15], off
	v_cvt_pk_bf16_f32 v4, v4, v5
	v_cvt_pk_bf16_f32 v5, v6, v7
	v_cvt_pk_bf16_f32 v12, v64, v65
	v_cvt_pk_bf16_f32 v13, v66, v67
	v_cvt_pk_bf16_f32 v14, v84, v85
	v_cvt_pk_bf16_f32 v15, v86, v87
	global_store_dwordx4 v[20:21], v[12:15], off offset:256
	v_cvt_pk_bf16_f32 v6, v16, v17
	v_cvt_pk_bf16_f32 v7, v18, v19
	v_or_b32_e32 v12, 32, v250
	v_ashrrev_i32_e32 v13, 31, v12
	v_lshlrev_b64 v[12:13], 11, v[12:13]
	v_lshl_add_u64 v[12:13], v[252:253], 0, v[12:13]
	global_store_dwordx4 v[12:13], v[4:7], off
	v_cvt_pk_bf16_f32 v0, v0, v1
	v_cvt_pk_bf16_f32 v1, v2, v3
	v_cvt_pk_bf16_f32 v4, v52, v53
	v_cvt_pk_bf16_f32 v5, v54, v55
	v_cvt_pk_bf16_f32 v6, v76, v77
	v_cvt_pk_bf16_f32 v7, v78, v79
	global_store_dwordx4 v[12:13], v[4:7], off offset:256
	v_cvt_pk_bf16_f32 v2, v8, v9
	v_cvt_pk_bf16_f32 v3, v10, v11
	v_or_b32_e32 v4, 48, v250
	v_ashrrev_i32_e32 v5, 31, v4
	v_lshlrev_b64 v[4:5], 11, v[4:5]
	v_lshl_add_u64 v[4:5], v[252:253], 0, v[4:5]
	global_store_dwordx4 v[4:5], v[0:3], off
	s_mov_b64 s[2:3], 0x40000
	v_readlane_b32 s63, v244, 19
	v_cvt_pk_bf16_f32 v0, v40, v41
	v_cvt_pk_bf16_f32 v1, v42, v43
	v_cvt_pk_bf16_f32 v2, v60, v61
	v_cvt_pk_bf16_f32 v3, v62, v63
	global_store_dwordx4 v[4:5], v[0:3], off offset:256
	v_lshl_add_u64 v[4:5], v[254:255], 0, s[2:3]
	s_mov_b32 s2, 0x40000
	v_add_co_u32_e32 v6, vcc, s2, v254
	v_cvt_pk_bf16_f32 v0, v68, v69
; __device__ __forceinline__ u32x4 mk4(unsigned a, unsigned b, unsigned c, unsigned d) { return (u32x4){a, b, c, d}; }
; __device__ __forceinline__ f32x4 zero4() { float z = 0.f; asm volatile("" : "+v"(z)); return (f32x4){z, z, z, z}; }
; __device__ __forceinline__ void gemm_phase(const Params& p, int l, const bf16_t* __restrict__ A, const bf16_t* __restrict__ Bt, int M, int N, int K,
;                            int epi, bf16_t* __restrict__ outp, char* smem, int wvi) {
;     ...
;           bf16_t* rp = outp + (size_t)(r0 + ai * GHALF + m * 16) * N + bcol + wc * 32 + fq * 8;
; #pragma unroll
;           for (int bj = 0; bj < 2; ++bj) {
;             const f32x4 v0 = acc[ai][bj][m][0], v1 = acc[ai][bj][m][1];
;             *reinterpret_cast<u32x4*>(rp + bj * GHALF) = mk4(pk2(v0[0], v0[1]), pk2(v0[2], v0[3]), pk2(v1[0], v1[1]), pk2(v1[2], v1[3]));
;           }
;         }
;     ...
;       if (!has_next) break;
; #pragma unroll
;       for (int a = 0; a < 2; ++a)
; #pragma unroll
;         for (int b = 0; b < 2; ++b)
; #pragma unroll
;           for (int m = 0; m < 4; ++m)
; #pragma unroll
;             for (int n = 0; n < 2; ++n) acc[a][b][m][n] = zero4();
;       Lw = Ln; pm = npm; pn = npn; cA = nA; cB = nB;
	v_cvt_pk_bf16_f32 v1, v70, v71
	v_cvt_pk_bf16_f32 v2, v88, v89
	v_cvt_pk_bf16_f32 v3, v90, v91
	v_addc_co_u32_e32 v7, vcc, 0, v255, vcc
	global_store_dwordx4 v[6:7], v[0:3], off
	s_mov_b64 s[2:3], 0x48000
	v_readlane_b32 s67, v244, 20
	v_cvt_pk_bf16_f32 v0, v120, v121
	v_cvt_pk_bf16_f32 v1, v122, v123
	v_cvt_pk_bf16_f32 v2, v124, v125
	v_cvt_pk_bf16_f32 v3, v126, v127
	global_store_dwordx4 v[4:5], v[0:3], off offset:256
	v_lshl_add_u64 v[4:5], v[254:255], 0, s[2:3]
	s_mov_b32 s2, 0x48000
	v_add_co_u32_e32 v6, vcc, s2, v254
	v_cvt_pk_bf16_f32 v0, v48, v49
	v_cvt_pk_bf16_f32 v1, v50, v51
	v_cvt_pk_bf16_f32 v2, v72, v73
	v_cvt_pk_bf16_f32 v3, v74, v75
	v_addc_co_u32_e32 v7, vcc, 0, v255, vcc
	global_store_dwordx4 v[6:7], v[0:3], off
	s_mov_b64 s[2:3], 0x50000
	s_movk_i32 s53, 0x440
	v_cvt_pk_bf16_f32 v0, v112, v113
	v_cvt_pk_bf16_f32 v1, v114, v115
	v_cvt_pk_bf16_f32 v2, v116, v117
	v_cvt_pk_bf16_f32 v3, v118, v119
	global_store_dwordx4 v[4:5], v[0:3], off offset:256
	v_lshl_add_u64 v[4:5], v[254:255], 0, s[2:3]
	s_mov_b32 s2, 0x50000
	v_add_co_u32_e32 v6, vcc, s2, v254
	v_cvt_pk_bf16_f32 v0, v36, v37
	v_cvt_pk_bf16_f32 v1, v38, v39
	v_cvt_pk_bf16_f32 v2, v56, v57
	v_cvt_pk_bf16_f32 v3, v58, v59
	v_addc_co_u32_e32 v7, vcc, 0, v255, vcc
	global_store_dwordx4 v[6:7], v[0:3], off
	s_mov_b64 s[2:3], 0x58000
	v_readlane_b32 s55, v244, 31
	v_cvt_pk_bf16_f32 v0, v104, v105
	v_cvt_pk_bf16_f32 v1, v106, v107
	v_cvt_pk_bf16_f32 v2, v108, v109
	v_cvt_pk_bf16_f32 v3, v110, v111
	global_store_dwordx4 v[4:5], v[0:3], off offset:256
	v_lshl_add_u64 v[4:5], v[254:255], 0, s[2:3]
	s_mov_b32 s2, 0x58000
	v_add_co_u32_e32 v6, vcc, s2, v254
	v_cvt_pk_bf16_f32 v0, v32, v33
	v_cvt_pk_bf16_f32 v1, v34, v35
	v_cvt_pk_bf16_f32 v2, v44, v45
	v_cvt_pk_bf16_f32 v3, v46, v47
	v_addc_co_u32_e32 v7, vcc, 0, v255, vcc
	global_store_dwordx4 v[6:7], v[0:3], off
	s_mov_b64 s[2:3], -1
	s_and_b64 vcc, exec, s[8:9]
	v_cvt_pk_bf16_f32 v0, v96, v97
	v_cvt_pk_bf16_f32 v1, v98, v99
	v_cvt_pk_bf16_f32 v2, v100, v101
	v_cvt_pk_bf16_f32 v3, v102, v103
	global_store_dwordx4 v[4:5], v[0:3], off offset:256
	s_cbranch_vccz .LBB0_117
	v_mov_b32_e32 v20, v177
	v_mov_b32_e32 v28, v177
	v_mov_b32_e32 v12, v177
	v_mov_b32_e32 v24, v177
	v_mov_b32_e32 v4, v177
	v_mov_b32_e32 v16, v177
	v_mov_b32_e32 v0, v177
	v_mov_b32_e32 v8, v177
	v_mov_b32_e32 v80, v177
	v_mov_b32_e32 v92, v177
	v_mov_b32_e32 v64, v177
	v_mov_b32_e32 v84, v177
	v_mov_b32_e32 v52, v177
	v_mov_b32_e32 v76, v177
	v_mov_b32_e32 v40, v177
	v_mov_b32_e32 v60, v177
	v_mov_b32_e32 v68, v177
	v_mov_b32_e32 v88, v177
	v_mov_b32_e32 v48, v177
	v_mov_b32_e32 v72, v177
	v_mov_b32_e32 v36, v177
	v_mov_b32_e32 v56, v177
	v_mov_b32_e32 v32, v177
	v_mov_b32_e32 v44, v177
	v_mov_b32_e32 v120, v177
	v_mov_b32_e32 v124, v177
	v_mov_b32_e32 v112, v177
	v_mov_b32_e32 v116, v177
	v_mov_b32_e32 v104, v177
	v_mov_b32_e32 v108, v177
	v_mov_b32_e32 v96, v177
	v_mov_b32_e32 v100, v177
	s_nop 0
	v_mov_b32_e32 v21, v20
	v_mov_b32_e32 v22, v20
	v_mov_b32_e32 v23, v20
	v_mov_b32_e32 v29, v28
	v_mov_b32_e32 v30, v28
	v_mov_b32_e32 v31, v28
	v_mov_b32_e32 v13, v12
	v_mov_b32_e32 v14, v12
	v_mov_b32_e32 v15, v12
	v_mov_b32_e32 v25, v24
	v_mov_b32_e32 v26, v24
	v_mov_b32_e32 v27, v24
	v_mov_b32_e32 v5, v4
	v_mov_b32_e32 v6, v4
	v_mov_b32_e32 v7, v4
	v_mov_b32_e32 v17, v16
	v_mov_b32_e32 v18, v16
	v_mov_b32_e32 v19, v16
	s_nop 0
	v_mov_b32_e32 v1, v0
	v_mov_b32_e32 v2, v0
	v_mov_b32_e32 v3, v0
	v_mov_b32_e32 v9, v8
	v_mov_b32_e32 v10, v8
	v_mov_b32_e32 v11, v8
	v_mov_b32_e32 v81, v80
	v_mov_b32_e32 v82, v80
	v_mov_b32_e32 v83, v80
	v_mov_b32_e32 v93, v92
	v_mov_b32_e32 v94, v92
	v_mov_b32_e32 v95, v92
	v_mov_b32_e32 v65, v64
	v_mov_b32_e32 v66, v64
	v_mov_b32_e32 v67, v64
	v_mov_b32_e32 v85, v84
	v_mov_b32_e32 v86, v84
	v_mov_b32_e32 v87, v84
	s_nop 0
	v_mov_b32_e32 v53, v52
	v_mov_b32_e32 v54, v52
	v_mov_b32_e32 v55, v52
	v_mov_b32_e32 v77, v76
	v_mov_b32_e32 v78, v76
	v_mov_b32_e32 v79, v76
	v_mov_b32_e32 v41, v40
	v_mov_b32_e32 v42, v40
	v_mov_b32_e32 v43, v40
	v_mov_b32_e32 v61, v60
	v_mov_b32_e32 v62, v60
	v_mov_b32_e32 v63, v60
	v_mov_b32_e32 v69, v68
	v_mov_b32_e32 v70, v68
	v_mov_b32_e32 v71, v68
	v_mov_b32_e32 v89, v88
	v_mov_b32_e32 v90, v88
	v_mov_b32_e32 v91, v88
	s_nop 0
	v_mov_b32_e32 v49, v48
	v_mov_b32_e32 v50, v48
	v_mov_b32_e32 v51, v48
	v_mov_b32_e32 v73, v72
	v_mov_b32_e32 v74, v72
	v_mov_b32_e32 v75, v72
	v_mov_b32_e32 v37, v36
	v_mov_b32_e32 v38, v36
	v_mov_b32_e32 v39, v36
	v_mov_b32_e32 v57, v56
	v_mov_b32_e32 v58, v56
	v_mov_b32_e32 v59, v56
	v_mov_b32_e32 v33, v32
	v_mov_b32_e32 v34, v32
	v_mov_b32_e32 v35, v32
	v_mov_b32_e32 v45, v44
	v_mov_b32_e32 v46, v44
	v_mov_b32_e32 v47, v44
	s_nop 0
	v_mov_b32_e32 v121, v120
	v_mov_b32_e32 v122, v120
	v_mov_b32_e32 v123, v120
	v_mov_b32_e32 v125, v124
	v_mov_b32_e32 v126, v124
	v_mov_b32_e32 v127, v124
	v_mov_b32_e32 v113, v112
	v_mov_b32_e32 v114, v112
	v_mov_b32_e32 v115, v112
	v_mov_b32_e32 v117, v116
	v_mov_b32_e32 v118, v116
	v_mov_b32_e32 v119, v116
	v_mov_b32_e32 v105, v104
	v_mov_b32_e32 v106, v104
	v_mov_b32_e32 v107, v104
	v_mov_b32_e32 v109, v108
	v_mov_b32_e32 v110, v108
	v_mov_b32_e32 v111, v108
	s_mov_b64 s[2:3], 0
	v_mov_b32_e32 v97, v96
	v_mov_b32_e32 v98, v96
	v_mov_b32_e32 v99, v96
	v_mov_b32_e32 v101, v100
	v_mov_b32_e32 v102, v100
	v_mov_b32_e32 v103, v100
	s_branch .LBB0_117

; __device__ __forceinline__ f32x4 zero4() { float z = 0.f; asm volatile("" : "+v"(z)); return (f32x4){z, z, z, z}; }
; #define G_STAGE(bufoff, gbase) do { _Pragma("unroll") for (int _i = 0; _i < 2; ++_i) \
;     __builtin_amdgcn_global_load_lds((const unsigned*)((const char*)(gbase) + voff[_i]), (GLAS unsigned*)(lds + (bufoff) + ldsw + _i * 8192), 16, 0, 0); } while (0)
; #define G_WAIT_V(n) asm volatile("s_waitcnt vmcnt(" #n ")" ::: "memory")
; __device__ __forceinline__ void gemm_phase(const Params& p, int l, const bf16_t* __restrict__ A, const bf16_t* __restrict__ Bt, int M, int N, int K,
;                            int epi, bf16_t* __restrict__ outp, char* smem, int wvi) {
;     ...
;   for (int i = 0; i < 2; ++i) { int R, C; stage_rc(tidx * 16 + i * 8192, R, C); voff[i] = (unsigned)(R * K + C) * 2u; }
;   const size_t kstep = (size_t)(GBK * 2), hstep = (size_t)GHALF * K * 2, tstep = 2 * hstep;
;   const unsigned ldsw = (unsigned)wid * 1024u;
;   const int aoff = lds_byte(wr * 64 + fr, fq * 8), boff = lds_byte(wc * 32 + fr, fq * 8);
;   constexpr int HTB = GHT * 2;
;     ...
;   const int nM = M / GBM, nN = N / GBM, nwg = nM * nN;
;   auto tile_of = [&](int Lw, int& pm_, int& pn_) {
;     int wgid = Lw;
;     { const int q = nwg / GNXCD, r = nwg % GNXCD, xcd = wgid % GNXCD, off = wgid / GNXCD; wgid = (xcd < r ? xcd * (q + 1) : r * (q + 1) + (xcd - r) * q) + off; }
;     const int nig = GWGM * nN, gid = wgid / nig, fm = gid * GWGM, gsz = min(nM - fm, GWGM);
;     pm_ = fm + ((wgid % nig) % gsz); pn_ = (wgid % nig) / gsz;
;   };
;   int Lw = blockIdx.x;
;   if (Lw < nwg) {
;     int pm, pn; tile_of(Lw, pm, pn);
;     const char* cA = (const char*)A + (size_t)pm * tstep;
;     const char* cB = (const char*)Bt + (size_t)pn * tstep;
;     f32x4 acc[2][2][4][2];
; #pragma unroll
;     for (int a = 0; a < 2; ++a)
; #pragma unroll
;       for (int b = 0; b < 2; ++b)
; #pragma unroll
;         for (int m = 0; m < 4; ++m)
; #pragma unroll
;           for (int n = 0; n < 2; ++n) acc[a][b][m][n] = zero4();
;     bf16x8 At[4][2], B0[2][2], B1[2][2];
;     G_STAGE(G_SB(0, 0), cB); G_STAGE(G_SA(0, 0), cA); G_STAGE(G_SB(0, 1), cB + hstep); G_STAGE(G_SA(0, 1), cA + hstep);
;     if (wr == 1) G_BAR;
;     G_WAIT_V(4); G_BAR;
;     G_STAGE(G_SB(1, 0), cB + kstep); G_STAGE(G_SA(1, 0), cA + kstep); G_STAGE(G_SB(1, 1), cB + hstep + kstep);
;     G_WAIT_V(6); G_BAR;
.LBB0_315:
	v_lshl_add_u64 v[2:3], s[2:3], 0, v[176:177]
	v_mov_b32_e32 v129, v177
	v_lshl_add_u64 v[6:7], s[2:3], 0, v[128:129]
	v_lshl_add_u64 v[2:3], v[2:3], 0, s[64:65]
	s_add_i32 m0, s17, 0x18000
	v_lshl_add_u64 v[10:11], s[10:11], 0, v[176:177]
	s_waitcnt vmcnt(4)
	s_barrier
	global_load_lds_dwordx4 v[2:3], off
	v_lshl_add_u64 v[2:3], v[6:7], 0, s[64:65]
	s_add_i32 m0, s17, 0x1a000
	s_add_i32 s30, s17, 0x8000
	s_add_i32 s31, s17, 0xa000
	v_lshl_add_u64 v[14:15], s[10:11], 0, v[128:129]
	global_load_lds_dwordx4 v[2:3], off
	v_lshl_add_u64 v[2:3], v[10:11], 0, s[64:65]
	s_mov_b32 m0, s30
	s_add_u32 s2, s2, 0x40080
	global_load_lds_dwordx4 v[2:3], off
	v_lshl_add_u64 v[2:3], v[14:15], 0, s[64:65]
	s_mov_b32 m0, s31
	s_addc_u32 s3, s3, 0
	global_load_lds_dwordx4 v[2:3], off
	v_lshl_add_u64 v[2:3], s[2:3], 0, v[176:177]
	s_add_i32 m0, s17, 0x1c000
	v_and_b32_e32 v131, 15, v130
	global_load_lds_dwordx4 v[2:3], off
	v_lshl_add_u64 v[2:3], s[2:3], 0, v[128:129]
	s_add_i32 m0, s17, 0x1e000
	v_readlane_b32 s1, v248, 10
	global_load_lds_dwordx4 v[2:3], off
	s_nop 0
	v_or_b32_e32 v138, s1, v131
	v_lshlrev_b32_e32 v133, 13, v133
	v_lshlrev_b32_e32 v134, 13, v134
	v_lshlrev_b32_e32 v139, 6, v138
	v_and_b32_e32 v142, 48, v130
	s_movk_i32 s1, 0x3c0
	v_lshlrev_b32_e32 v143, 2, v138
	v_and_b32_e32 v133, 0x7fffc000, v133
	v_and_b32_e32 v134, 0x7fffc000, v134
	v_and_or_b32 v139, v139, s1, v142
	v_and_b32_e32 v143, 32, v143
	v_readlane_b32 s1, v248, 11
	v_lshlrev_b32_e32 v130, 2, v130
	v_readlane_b32 s2, v248, 21
	v_lshl_add_u32 v132, v132, 10, v133
	v_lshl_add_u32 v134, v135, 10, v134
	v_bitop3_b32 v144, v139, s1, v143 bitop3:0xde
	v_lshl_or_b32 v131, v131, 6, v142
	v_and_b32_e32 v130, 32, v130
	v_readlane_b32 s1, v248, 12
	s_waitcnt vmcnt(6)
	v_mov_b32_e32 v143, v177
	v_readlane_b32 s3, v248, 22
	v_or_b32_e32 v132, v132, v140
	v_or_b32_e32 v134, v134, v136
	v_bitop3_b32 v139, v131, s1, v130 bitop3:0xde
	v_lshl_add_u64 v[130:131], s[2:3], 0, v[142:143]
	v_add_lshl_u32 v132, v132, v141, 1
	v_mov_b32_e32 v133, v177
	s_mov_b64 s[2:3], 0x40080
	v_add_lshl_u32 v134, v134, v137, 1
	v_mov_b32_e32 v135, v177
	s_sext_i32_i16 s0, s4
	v_mov_b32_e32 v121, v120
	v_mov_b32_e32 v122, v120
	v_mov_b32_e32 v123, v120
	v_mov_b32_e32 v125, v124
	v_mov_b32_e32 v126, v124
	v_mov_b32_e32 v127, v124
	v_mov_b32_e32 v105, v104
	v_mov_b32_e32 v106, v104
	v_mov_b32_e32 v107, v104
	v_mov_b32_e32 v109, v108
	v_mov_b32_e32 v110, v108
	v_mov_b32_e32 v111, v108
	v_mov_b32_e32 v89, v88
	v_mov_b32_e32 v90, v88
	v_mov_b32_e32 v91, v88
	v_mov_b32_e32 v93, v92
	v_mov_b32_e32 v94, v92
	v_mov_b32_e32 v95, v92
	v_mov_b32_e32 v73, v72
	v_mov_b32_e32 v74, v72
	v_mov_b32_e32 v75, v72
	v_mov_b32_e32 v77, v76
	v_mov_b32_e32 v78, v76
	v_mov_b32_e32 v79, v76
	v_mov_b32_e32 v113, v112
	v_mov_b32_e32 v114, v112
	v_mov_b32_e32 v115, v112
	v_mov_b32_e32 v117, v116
	v_mov_b32_e32 v118, v116
	v_mov_b32_e32 v119, v116
	v_mov_b32_e32 v97, v96
	v_mov_b32_e32 v98, v96
	v_mov_b32_e32 v99, v96
	v_mov_b32_e32 v101, v100
	v_mov_b32_e32 v102, v100
	v_mov_b32_e32 v103, v100
	v_mov_b32_e32 v81, v80
	v_mov_b32_e32 v82, v80
	v_mov_b32_e32 v83, v80
	v_mov_b32_e32 v85, v84
	v_mov_b32_e32 v86, v84
	v_mov_b32_e32 v87, v84
	v_mov_b32_e32 v65, v64
	v_mov_b32_e32 v66, v64
	v_mov_b32_e32 v67, v64
	v_mov_b32_e32 v69, v68
	v_mov_b32_e32 v70, v68
	v_mov_b32_e32 v71, v68
	v_mov_b32_e32 v57, v56
	v_mov_b32_e32 v58, v56
	v_mov_b32_e32 v59, v56
	v_mov_b32_e32 v61, v60
	v_mov_b32_e32 v62, v60
	v_mov_b32_e32 v63, v60
	v_mov_b32_e32 v41, v40
	v_mov_b32_e32 v42, v40
	v_mov_b32_e32 v43, v40
	v_mov_b32_e32 v45, v44
	v_mov_b32_e32 v46, v44
	v_mov_b32_e32 v47, v44
	v_mov_b32_e32 v25, v24
	v_mov_b32_e32 v26, v24
	v_mov_b32_e32 v27, v24
	v_mov_b32_e32 v29, v28
	v_mov_b32_e32 v30, v28
	v_mov_b32_e32 v31, v28
	v_mov_b32_e32 v9, v8
	v_mov_b32_e32 v10, v8
	v_mov_b32_e32 v11, v8
	v_mov_b32_e32 v13, v12
	v_mov_b32_e32 v14, v12
	v_mov_b32_e32 v15, v12
	v_mov_b32_e32 v49, v48
	v_mov_b32_e32 v50, v48
	v_mov_b32_e32 v51, v48
	v_mov_b32_e32 v53, v52
	v_mov_b32_e32 v54, v52
	v_mov_b32_e32 v55, v52
	v_mov_b32_e32 v33, v32
	v_mov_b32_e32 v34, v32
	v_mov_b32_e32 v35, v32
	v_mov_b32_e32 v37, v36
	v_mov_b32_e32 v38, v36
	v_mov_b32_e32 v39, v36
	v_mov_b32_e32 v17, v16
	v_mov_b32_e32 v18, v16
	v_mov_b32_e32 v19, v16
	v_mov_b32_e32 v21, v20
	v_mov_b32_e32 v22, v20
	v_mov_b32_e32 v23, v20
	v_mov_b32_e32 v1, v0
	v_mov_b32_e32 v2, v0
	v_mov_b32_e32 v3, v0
	v_mov_b32_e32 v5, v4
	v_mov_b32_e32 v6, v4
	v_mov_b32_e32 v7, v4
	v_lshl_add_u64 v[132:133], v[132:133], 0, s[2:3]
	v_lshl_add_u64 v[134:135], v[134:135], 0, s[2:3]
	v_add_u32_e32 v140, 0, v144
	v_readlane_b32 s20, v248, 0
	s_barrier
	v_add_u32_e32 v136, 0x10000, v139
	ds_read_b128 v[142:145], v136
	ds_read_b128 v[146:149], v136 offset:1024
	ds_read_b128 v[150:153], v136 offset:2048
	ds_read_b128 v[154:157], v136 offset:3072
	s_branch .LBB0_317

; #define G_STAGE(bufoff, gbase) do { _Pragma("unroll") for (int _i = 0; _i < 2; ++_i) \
;     __builtin_amdgcn_global_load_lds((const unsigned*)((const char*)(gbase) + voff[_i]), (GLAS unsigned*)(lds + (bufoff) + ldsw + _i * 8192), 16, 0, 0); } while (0)
; #define G_LDA(dst, b, h) do { _Pragma("unroll") for (int m = 0; m < 4; ++m) _Pragma("unroll") for (int k = 0; k < 2; ++k) \
;     dst[m][k] = *(const GLAS bf16x8*)(lds + G_SA(b, h) + aoff + m * 2048 + k * 1024); } while (0)
; #define G_LDB(dst, b, h) do { _Pragma("unroll") for (int n = 0; n < 2; ++n) _Pragma("unroll") for (int k = 0; k < 2; ++k) \
;     dst[n][k] = *(const GLAS bf16x8*)(lds + G_SB(b, h) + boff + n * 2048 + k * 1024); } while (0)
; #define G_MMA(ai, bj, At_, Bt_) do { __builtin_amdgcn_s_setprio(1); \
;     _Pragma("unroll") for (int m = 0; m < 4; ++m) _Pragma("unroll") for (int n = 0; n < 2; ++n) _Pragma("unroll") for (int k = 0; k < 2; ++k) \
;       acc[ai][bj][m][n] = __builtin_amdgcn_mfma_f32_16x16x32_bf16(Bt_[n][k], At_[m][k], acc[ai][bj][m][n], 0, 0, 0); \
;     __builtin_amdgcn_s_setprio(0); } while (0)
; #define G_WAIT_V(n) asm volatile("s_waitcnt vmcnt(" #n ")" ::: "memory")
; #define G_WAIT_L(n) asm volatile("s_waitcnt lgkmcnt(" #n ")" ::: "memory")
; #define G_BAR __builtin_amdgcn_s_barrier()
; __device__ __forceinline__ void gemm_phase(const Params& p, int l, const bf16_t* __restrict__ A, const bf16_t* __restrict__ Bt, int M, int N, int K,
;                            int epi, bf16_t* __restrict__ outp, char* smem, int wvi) {
;     ...
;       for (int t = 0; t < nt; t += 2) {
;         const bool lastt = (t == nt - 2);
;         const char* a1 = cA + (size_t)(t + 1) * kstep;
;         const char* a2 = lastt ? nA : cA + (size_t)(t + 2) * kstep; const char* b2 = lastt ? nB : cB + (size_t)(t + 2) * kstep;
;         const char* a3 = a2 + kstep; const char* b3 = b2 + kstep;
;         G_LDB(B0, 0, 0); G_SCHED; G_LDA(At, 0, 0); G_STAGE(G_SA(1, 1), a1 + hstep);
;         G_WAIT_L(8); G_BAR; G_WAIT_L(0); G_MMA(0, 0, At, B0); G_BAR; G_SCHED;
;         G_LDB(B1, 0, 1); G_STAGE(G_SB(0, 0), b2);
;         G_BAR; G_WAIT_L(0); G_MMA(0, 1, At, B1); G_BAR;
;         G_LDA(At, 0, 1); G_STAGE(G_SA(0, 0), a2);
;         G_BAR; G_WAIT_L(0); G_MMA(1, 0, At, B0); G_BAR; G_SCHED;
;         G_STAGE(G_SB(0, 1), b2 + hstep);
;         G_WAIT_V(6); G_BAR; G_MMA(1, 1, At, B1); G_BAR;
.LBB0_320:
	s_add_u32 s2, s10, 0x100
	s_addc_u32 s3, s11, 0
	s_add_i32 s23, 0, 0x10000
	s_cmp_eq_u32 s22, 12
	s_cselect_b32 s29, s9, s3
	s_cselect_b32 s28, s8, s2
	s_cselect_b32 s93, s5, s21
	s_cselect_b32 s92, s1, s7
	v_lshl_add_u64 v[136:137], s[10:11], 0, v[132:133]
	s_add_i32 m0, s17, 0xc000
	ds_read_b128 v[158:161], v140
	ds_read_b128 v[162:165], v140 offset:1024
	ds_read_b128 v[166:169], v140 offset:2048
	ds_read_b128 v[170:173], v140 offset:3072
	ds_read_b128 v[182:185], v140 offset:4096
	ds_read_b128 v[186:189], v140 offset:5120
	ds_read_b128 v[214:217], v140 offset:6144
	ds_read_b128 v[218:221], v140 offset:7168
	global_load_lds_dwordx4 v[136:137], off
	v_lshl_add_u64 v[136:137], s[10:11], 0, v[134:135]
	s_add_i32 m0, s17, 0xe000
	s_nop 0
	global_load_lds_dwordx4 v[136:137], off
	s_waitcnt lgkmcnt(8)
	s_barrier
	s_waitcnt lgkmcnt(0)
	s_waitcnt lgkmcnt(0)
	v_mfma_f32_16x16x32_bf16 v[120:123], v[142:145], v[158:161], v[120:123]
	v_mfma_f32_16x16x32_bf16 v[124:127], v[150:153], v[158:161], v[124:127]
	v_mfma_f32_16x16x32_bf16 v[104:107], v[142:145], v[166:169], v[104:107]
	v_mfma_f32_16x16x32_bf16 v[108:111], v[150:153], v[166:169], v[108:111]
	v_mfma_f32_16x16x32_bf16 v[88:91], v[142:145], v[182:185], v[88:91]
	v_mfma_f32_16x16x32_bf16 v[92:95], v[150:153], v[182:185], v[92:95]
	v_mfma_f32_16x16x32_bf16 v[72:75], v[142:145], v[214:217], v[72:75]
	v_mfma_f32_16x16x32_bf16 v[76:79], v[150:153], v[214:217], v[76:79]
	v_mfma_f32_16x16x32_bf16 v[120:123], v[146:149], v[162:165], v[120:123]
	v_mfma_f32_16x16x32_bf16 v[124:127], v[154:157], v[162:165], v[124:127]
	v_mfma_f32_16x16x32_bf16 v[104:107], v[146:149], v[170:173], v[104:107]
	v_mfma_f32_16x16x32_bf16 v[108:111], v[154:157], v[170:173], v[108:111]
	v_mfma_f32_16x16x32_bf16 v[88:91], v[146:149], v[186:189], v[88:91]
	v_mfma_f32_16x16x32_bf16 v[92:95], v[154:157], v[186:189], v[92:95]
	v_mfma_f32_16x16x32_bf16 v[72:75], v[146:149], v[218:221], v[72:75]
	v_mfma_f32_16x16x32_bf16 v[76:79], v[154:157], v[218:221], v[76:79]
	s_barrier
	s_add_i32 s24, 0, 0x14000
	v_add_u32_e32 v136, s24, v139
	s_add_i32 s10, s23, s58
	ds_read_b128 v[222:225], v136
	ds_read_b128 v[226:229], v136 offset:1024
	ds_read_b128 v[230:233], v136 offset:2048
	ds_read_b128 v[234:237], v136 offset:3072
	v_lshl_add_u64 v[136:137], s[92:93], 0, v[176:177]
	s_mov_b32 m0, s10
	v_lshl_add_u64 v[174:175], s[92:93], 0, v[128:129]
	global_load_lds_dwordx4 v[136:137], off
	s_add_i32 m0, s10, 0x2000
	s_nop 0
	global_load_lds_dwordx4 v[174:175], off
	s_barrier
	s_waitcnt lgkmcnt(0)
	s_waitcnt lgkmcnt(0)
	v_mfma_f32_16x16x32_bf16 v[112:115], v[222:225], v[158:161], v[112:115]
	v_mfma_f32_16x16x32_bf16 v[116:119], v[230:233], v[158:161], v[116:119]
	v_mfma_f32_16x16x32_bf16 v[96:99], v[222:225], v[166:169], v[96:99]
	v_mfma_f32_16x16x32_bf16 v[100:103], v[230:233], v[166:169], v[100:103]
	v_mfma_f32_16x16x32_bf16 v[80:83], v[222:225], v[182:185], v[80:83]
	v_mfma_f32_16x16x32_bf16 v[84:87], v[230:233], v[182:185], v[84:87]
	v_mfma_f32_16x16x32_bf16 v[64:67], v[222:225], v[214:217], v[64:67]
	v_mfma_f32_16x16x32_bf16 v[68:71], v[230:233], v[214:217], v[68:71]
	v_mfma_f32_16x16x32_bf16 v[112:115], v[226:229], v[162:165], v[112:115]
	v_mfma_f32_16x16x32_bf16 v[116:119], v[234:237], v[162:165], v[116:119]
	v_mfma_f32_16x16x32_bf16 v[96:99], v[226:229], v[170:173], v[96:99]
	v_mfma_f32_16x16x32_bf16 v[100:103], v[234:237], v[170:173], v[100:103]
	v_mfma_f32_16x16x32_bf16 v[80:83], v[226:229], v[186:189], v[80:83]
	v_mfma_f32_16x16x32_bf16 v[84:87], v[234:237], v[186:189], v[84:87]
	v_mfma_f32_16x16x32_bf16 v[64:67], v[226:229], v[218:221], v[64:67]
	v_mfma_f32_16x16x32_bf16 v[68:71], v[234:237], v[218:221], v[68:71]
	s_mov_b32 m0, s17
	v_lshl_add_u64 v[190:191], s[28:29], 0, v[176:177]
	s_barrier
	ds_read_b128 v[158:161], v140 offset:16384
	ds_read_b128 v[162:165], v140 offset:17408
	ds_read_b128 v[166:169], v140 offset:18432
	ds_read_b128 v[170:173], v140 offset:19456
	ds_read_b128 v[182:185], v140 offset:20480
	ds_read_b128 v[186:189], v140 offset:21504
	ds_read_b128 v[214:217], v140 offset:22528
	ds_read_b128 v[218:221], v140 offset:23552
	global_load_lds_dwordx4 v[190:191], off
	v_lshl_add_u64 v[238:239], s[28:29], 0, v[128:129]
	s_mov_b32 m0, s89
	s_nop 0
	global_load_lds_dwordx4 v[238:239], off
	s_barrier
	s_waitcnt lgkmcnt(0)
	s_waitcnt lgkmcnt(0)
	v_mfma_f32_16x16x32_bf16 v[56:59], v[142:145], v[158:161], v[56:59]
	v_mfma_f32_16x16x32_bf16 v[60:63], v[150:153], v[158:161], v[60:63]
	v_mfma_f32_16x16x32_bf16 v[40:43], v[142:145], v[166:169], v[40:43]
	v_mfma_f32_16x16x32_bf16 v[44:47], v[150:153], v[166:169], v[44:47]
	v_mfma_f32_16x16x32_bf16 v[24:27], v[142:145], v[182:185], v[24:27]
	v_mfma_f32_16x16x32_bf16 v[28:31], v[150:153], v[182:185], v[28:31]
	v_mfma_f32_16x16x32_bf16 v[8:11], v[142:145], v[214:217], v[8:11]
	v_mfma_f32_16x16x32_bf16 v[12:15], v[150:153], v[214:217], v[12:15]
	v_mfma_f32_16x16x32_bf16 v[56:59], v[146:149], v[162:165], v[56:59]
	v_mfma_f32_16x16x32_bf16 v[60:63], v[154:157], v[162:165], v[60:63]
	v_mfma_f32_16x16x32_bf16 v[40:43], v[146:149], v[170:173], v[40:43]
	v_mfma_f32_16x16x32_bf16 v[44:47], v[154:157], v[170:173], v[44:47]
	v_mfma_f32_16x16x32_bf16 v[24:27], v[146:149], v[186:189], v[24:27]
	v_mfma_f32_16x16x32_bf16 v[28:31], v[154:157], v[186:189], v[28:31]
	v_mfma_f32_16x16x32_bf16 v[8:11], v[146:149], v[218:221], v[8:11]
	v_mfma_f32_16x16x32_bf16 v[12:15], v[154:157], v[218:221], v[12:15]
	s_barrier
	s_add_u32 s10, s92, 0x40000
	s_addc_u32 s11, s93, 0
	s_add_i32 s23, s24, s58
	v_lshl_add_u64 v[142:143], s[10:11], 0, v[176:177]
	s_mov_b32 m0, s23
	s_nop 0
	global_load_lds_dwordx4 v[142:143], off
	v_lshl_add_u64 v[142:143], s[10:11], 0, v[128:129]
	s_add_i32 m0, s23, 0x2000
	s_nop 0
	global_load_lds_dwordx4 v[142:143], off
	s_waitcnt vmcnt(6)
	s_barrier
; #define G_STAGE(bufoff, gbase) do { _Pragma("unroll") for (int _i = 0; _i < 2; ++_i) \
;     __builtin_amdgcn_global_load_lds((const unsigned*)((const char*)(gbase) + voff[_i]), (GLAS unsigned*)(lds + (bufoff) + ldsw + _i * 8192), 16, 0, 0); } while (0)
; #define G_LDA(dst, b, h) do { _Pragma("unroll") for (int m = 0; m < 4; ++m) _Pragma("unroll") for (int k = 0; k < 2; ++k) \
;     dst[m][k] = *(const GLAS bf16x8*)(lds + G_SA(b, h) + aoff + m * 2048 + k * 1024); } while (0)
; #define G_LDB(dst, b, h) do { _Pragma("unroll") for (int n = 0; n < 2; ++n) _Pragma("unroll") for (int k = 0; k < 2; ++k) \
;     dst[n][k] = *(const GLAS bf16x8*)(lds + G_SB(b, h) + boff + n * 2048 + k * 1024); } while (0)
; #define G_MMA(ai, bj, At_, Bt_) do { __builtin_amdgcn_s_setprio(1); \
;     _Pragma("unroll") for (int m = 0; m < 4; ++m) _Pragma("unroll") for (int n = 0; n < 2; ++n) _Pragma("unroll") for (int k = 0; k < 2; ++k) \
;       acc[ai][bj][m][n] = __builtin_amdgcn_mfma_f32_16x16x32_bf16(Bt_[n][k], At_[m][k], acc[ai][bj][m][n], 0, 0, 0); \
;     __builtin_amdgcn_s_setprio(0); } while (0)
; #define G_WAIT_V(n) asm volatile("s_waitcnt vmcnt(" #n ")" ::: "memory")
; #define G_WAIT_L(n) asm volatile("s_waitcnt lgkmcnt(" #n ")" ::: "memory")
; #define G_BAR __builtin_amdgcn_s_barrier()
; #define G_SCHED __builtin_amdgcn_sched_barrier(0)
; __device__ __forceinline__ void gemm_phase(const Params& p, int l, const bf16_t* __restrict__ A, const bf16_t* __restrict__ Bt, int M, int N, int K,
;                            int epi, bf16_t* __restrict__ outp, char* smem, int wvi) {
;     ...
;         G_WAIT_V(6); G_BAR; G_MMA(1, 1, At, B1); G_BAR;
;         G_LDB(B0, 1, 0); G_SCHED; G_LDA(At, 1, 0); G_STAGE(G_SA(0, 1), a2 + hstep);
;         G_WAIT_L(8); G_BAR; G_WAIT_L(0); G_MMA(0, 0, At, B0); G_BAR; G_SCHED;
;         G_LDB(B1, 1, 1); G_STAGE(G_SB(1, 0), b3);
;         G_BAR; G_WAIT_L(0); G_MMA(0, 1, At, B1); G_BAR;
;         G_LDA(At, 1, 1); G_STAGE(G_SA(1, 0), a3);
;         G_BAR; G_WAIT_L(0); G_MMA(1, 0, At, B0); G_BAR; G_SCHED;
	v_mfma_f32_16x16x32_bf16 v[48:51], v[222:225], v[158:161], v[48:51]
	v_mfma_f32_16x16x32_bf16 v[52:55], v[230:233], v[158:161], v[52:55]
	v_mfma_f32_16x16x32_bf16 v[32:35], v[222:225], v[166:169], v[32:35]
	v_mfma_f32_16x16x32_bf16 v[36:39], v[230:233], v[166:169], v[36:39]
	v_mfma_f32_16x16x32_bf16 v[16:19], v[222:225], v[182:185], v[16:19]
	v_mfma_f32_16x16x32_bf16 v[20:23], v[230:233], v[182:185], v[20:23]
	v_mfma_f32_16x16x32_bf16 v[0:3], v[222:225], v[214:217], v[0:3]
	v_mfma_f32_16x16x32_bf16 v[4:7], v[230:233], v[214:217], v[4:7]
	v_mfma_f32_16x16x32_bf16 v[48:51], v[226:229], v[162:165], v[48:51]
	v_mfma_f32_16x16x32_bf16 v[52:55], v[234:237], v[162:165], v[52:55]
	v_mfma_f32_16x16x32_bf16 v[32:35], v[226:229], v[170:173], v[32:35]
	v_mfma_f32_16x16x32_bf16 v[36:39], v[234:237], v[170:173], v[36:39]
	v_mfma_f32_16x16x32_bf16 v[16:19], v[226:229], v[186:189], v[16:19]
	v_mfma_f32_16x16x32_bf16 v[20:23], v[234:237], v[186:189], v[20:23]
	v_mfma_f32_16x16x32_bf16 v[0:3], v[226:229], v[218:221], v[0:3]
	v_mfma_f32_16x16x32_bf16 v[4:7], v[234:237], v[218:221], v[4:7]
	s_add_i32 s23, 0, 0x18000
	v_add_u32_e32 v141, s23, v139
	s_barrier
	ds_read_b128 v[142:145], v141
	ds_read_b128 v[146:149], v141 offset:1024
	ds_read_b128 v[150:153], v141 offset:2048
	ds_read_b128 v[154:157], v141 offset:3072
	s_add_u32 s10, s28, 0x40000
	s_addc_u32 s11, s29, 0
	s_mov_b32 m0, s88
	v_lshl_add_u64 v[222:223], s[10:11], 0, v[176:177]
	ds_read_b128 v[158:161], v140 offset:32768
	ds_read_b128 v[162:165], v140 offset:33792
	ds_read_b128 v[166:169], v140 offset:34816
	ds_read_b128 v[170:173], v140 offset:35840
	ds_read_b128 v[182:185], v140 offset:36864
	ds_read_b128 v[186:189], v140 offset:37888
	ds_read_b128 v[214:217], v140 offset:38912
	ds_read_b128 v[218:221], v140 offset:39936
	global_load_lds_dwordx4 v[222:223], off
	v_lshl_add_u64 v[222:223], s[10:11], 0, v[128:129]
	s_mov_b32 m0, s55
	s_nop 0
	global_load_lds_dwordx4 v[222:223], off
	s_waitcnt lgkmcnt(8)
	s_barrier
	s_waitcnt lgkmcnt(0)
	s_waitcnt lgkmcnt(0)
	v_mfma_f32_16x16x32_bf16 v[120:123], v[142:145], v[158:161], v[120:123]
	v_mfma_f32_16x16x32_bf16 v[124:127], v[150:153], v[158:161], v[124:127]
	v_mfma_f32_16x16x32_bf16 v[104:107], v[142:145], v[166:169], v[104:107]
	v_mfma_f32_16x16x32_bf16 v[108:111], v[150:153], v[166:169], v[108:111]
	v_mfma_f32_16x16x32_bf16 v[88:91], v[142:145], v[182:185], v[88:91]
	v_mfma_f32_16x16x32_bf16 v[92:95], v[150:153], v[182:185], v[92:95]
	v_mfma_f32_16x16x32_bf16 v[72:75], v[142:145], v[214:217], v[72:75]
	v_mfma_f32_16x16x32_bf16 v[76:79], v[150:153], v[214:217], v[76:79]
	v_mfma_f32_16x16x32_bf16 v[120:123], v[146:149], v[162:165], v[120:123]
	v_mfma_f32_16x16x32_bf16 v[124:127], v[154:157], v[162:165], v[124:127]
	v_mfma_f32_16x16x32_bf16 v[104:107], v[146:149], v[170:173], v[104:107]
	v_mfma_f32_16x16x32_bf16 v[108:111], v[154:157], v[170:173], v[108:111]
	v_mfma_f32_16x16x32_bf16 v[88:91], v[146:149], v[186:189], v[88:91]
	v_mfma_f32_16x16x32_bf16 v[92:95], v[154:157], v[186:189], v[92:95]
	v_mfma_f32_16x16x32_bf16 v[72:75], v[146:149], v[218:221], v[72:75]
	v_mfma_f32_16x16x32_bf16 v[76:79], v[154:157], v[218:221], v[76:79]
	s_barrier
	s_add_i32 s24, 0, 0x1c000
	s_add_i32 s10, s23, s58
	v_add_u32_e32 v141, s24, v139
	v_lshl_add_u64 v[136:137], v[136:137], 0, s[64:65]
	s_mov_b32 m0, s10
	ds_read_b128 v[222:225], v141
	ds_read_b128 v[226:229], v141 offset:1024
	ds_read_b128 v[230:233], v141 offset:2048
	ds_read_b128 v[234:237], v141 offset:3072
	global_load_lds_dwordx4 v[136:137], off
	v_lshl_add_u64 v[136:137], v[174:175], 0, s[64:65]
	s_add_i32 m0, s10, 0x2000
	s_nop 0
	global_load_lds_dwordx4 v[136:137], off
	s_barrier
	s_waitcnt lgkmcnt(0)
	s_waitcnt lgkmcnt(0)
	v_mfma_f32_16x16x32_bf16 v[112:115], v[222:225], v[158:161], v[112:115]
	v_mfma_f32_16x16x32_bf16 v[116:119], v[230:233], v[158:161], v[116:119]
	v_mfma_f32_16x16x32_bf16 v[96:99], v[222:225], v[166:169], v[96:99]
	v_mfma_f32_16x16x32_bf16 v[100:103], v[230:233], v[166:169], v[100:103]
	v_mfma_f32_16x16x32_bf16 v[80:83], v[222:225], v[182:185], v[80:83]
	v_mfma_f32_16x16x32_bf16 v[84:87], v[230:233], v[182:185], v[84:87]
	v_mfma_f32_16x16x32_bf16 v[64:67], v[222:225], v[214:217], v[64:67]
	v_mfma_f32_16x16x32_bf16 v[68:71], v[230:233], v[214:217], v[68:71]
	v_mfma_f32_16x16x32_bf16 v[112:115], v[226:229], v[162:165], v[112:115]
	v_mfma_f32_16x16x32_bf16 v[116:119], v[234:237], v[162:165], v[116:119]
	v_mfma_f32_16x16x32_bf16 v[96:99], v[226:229], v[170:173], v[96:99]
	v_mfma_f32_16x16x32_bf16 v[100:103], v[234:237], v[170:173], v[100:103]
	v_mfma_f32_16x16x32_bf16 v[80:83], v[226:229], v[186:189], v[80:83]
	v_mfma_f32_16x16x32_bf16 v[84:87], v[234:237], v[186:189], v[84:87]
	v_mfma_f32_16x16x32_bf16 v[64:67], v[226:229], v[218:221], v[64:67]
	v_mfma_f32_16x16x32_bf16 v[68:71], v[234:237], v[218:221], v[68:71]
	s_mov_b32 m0, s30
	v_lshl_add_u64 v[136:137], v[190:191], 0, s[64:65]
	s_barrier
	ds_read_b128 v[158:161], v140 offset:49152
	ds_read_b128 v[162:165], v140 offset:50176
	ds_read_b128 v[166:169], v140 offset:51200
	ds_read_b128 v[170:173], v140 offset:52224
	ds_read_b128 v[182:185], v140 offset:53248
	ds_read_b128 v[186:189], v140 offset:54272
	ds_read_b128 v[214:217], v140 offset:55296
	ds_read_b128 v[218:221], v140 offset:56320
	global_load_lds_dwordx4 v[136:137], off
	v_lshl_add_u64 v[136:137], v[238:239], 0, s[64:65]
	s_mov_b32 m0, s31
	s_nop 0
	global_load_lds_dwordx4 v[136:137], off
	s_waitcnt vmcnt(10)
	s_barrier
; __device__ __forceinline__ u32x4 mk4(unsigned a, unsigned b, unsigned c, unsigned d) { return (u32x4){a, b, c, d}; }
; __device__ __forceinline__ float silu_f(float x) { return x * __builtin_amdgcn_rcpf(1.f + __expf(-x)); }
; #define G_STAGE(bufoff, gbase) do { _Pragma("unroll") for (int _i = 0; _i < 2; ++_i) \
;     __builtin_amdgcn_global_load_lds((const unsigned*)((const char*)(gbase) + voff[_i]), (GLAS unsigned*)(lds + (bufoff) + ldsw + _i * 8192), 16, 0, 0); } while (0)
; #define G_WAIT_V(n) asm volatile("s_waitcnt vmcnt(" #n ")" ::: "memory")
; #define G_WAIT_L(n) asm volatile("s_waitcnt lgkmcnt(" #n ")" ::: "memory")
; __device__ __forceinline__ void gemm_phase(const Params& p, int l, const bf16_t* __restrict__ A, const bf16_t* __restrict__ Bt, int M, int N, int K,
;                            int epi, bf16_t* __restrict__ outp, char* smem, int wvi) {
;     ...
;         G_BAR; G_WAIT_L(0); G_MMA(1, 0, At, B0); G_BAR; G_SCHED;
;         G_STAGE(G_SB(1, 1), b3 + hstep);
;         G_WAIT_V(6); G_BAR; G_MMA(1, 1, At, B1); G_BAR;
;       }
;       const int brow = pm * GBM, bcol = pn * GBM;
;     const int r0 = brow + wr * 64 + fr;
;     if (epi == EPI_PLAIN) {
; #pragma unroll
;       for (int ai = 0; ai < 2; ++ai)
; #pragma unroll
;         for (int m = 0; m < 4; ++m) {
;           bf16_t* rp = outp + (size_t)(r0 + ai * GHALF + m * 16) * N + bcol + wc * 32 + fq * 8;
; #pragma unroll
;           for (int bj = 0; bj < 2; ++bj) {
;             const f32x4 v0 = acc[ai][bj][m][0], v1 = acc[ai][bj][m][1];
;             *reinterpret_cast<u32x4*>(rp + bj * GHALF) = mk4(pk2(v0[0], v0[1]), pk2(v0[2], v0[3]), pk2(v1[0], v1[1]), pk2(v1[2], v1[3]));
;           }
;         }
;     } else if (epi == EPI_SWIGLU) {
; #pragma unroll
;       for (int ai = 0; ai < 2; ++ai)
; #pragma unroll
;         for (int m = 0; m < 4; ++m) {
;           bf16_t* rp = outp + (size_t)(r0 + ai * GHALF + m * 16) * DFF + pn * 128 + wc * 32 + fq * 8;
;           unsigned pk[4];
; #pragma unroll
;           for (int bj = 0; bj < 2; ++bj) {
;             const f32x4 g = acc[ai][bj][m][0], u = acc[ai][bj][m][1];
;             const float o0 = silu_f(g[0]) * u[0], o1 = silu_f(g[1]) * u[1], o2 = silu_f(g[2]) * u[2], o3 = silu_f(g[3]) * u[3];
;             pk[2 * bj] = pk2(o0, o1); pk[2 * bj + 1] = pk2(o2, o3);
;           }
;           *reinterpret_cast<u32x4*>(rp) = mk4(pk[0], pk[1], pk[2], pk[3]);
	s_waitcnt lgkmcnt(0)
	s_waitcnt lgkmcnt(0)
	v_mfma_f32_16x16x32_bf16 v[56:59], v[142:145], v[158:161], v[56:59]
	v_mfma_f32_16x16x32_bf16 v[60:63], v[150:153], v[158:161], v[60:63]
	v_mfma_f32_16x16x32_bf16 v[40:43], v[142:145], v[166:169], v[40:43]
	v_mfma_f32_16x16x32_bf16 v[44:47], v[150:153], v[166:169], v[44:47]
	v_mfma_f32_16x16x32_bf16 v[24:27], v[142:145], v[182:185], v[24:27]
	v_mfma_f32_16x16x32_bf16 v[28:31], v[150:153], v[182:185], v[28:31]
	v_mfma_f32_16x16x32_bf16 v[8:11], v[142:145], v[214:217], v[8:11]
	v_mfma_f32_16x16x32_bf16 v[12:15], v[150:153], v[214:217], v[12:15]
	v_mfma_f32_16x16x32_bf16 v[56:59], v[146:149], v[162:165], v[56:59]
	v_mfma_f32_16x16x32_bf16 v[60:63], v[154:157], v[162:165], v[60:63]
	v_mfma_f32_16x16x32_bf16 v[40:43], v[146:149], v[170:173], v[40:43]
	v_mfma_f32_16x16x32_bf16 v[44:47], v[154:157], v[170:173], v[44:47]
	v_mfma_f32_16x16x32_bf16 v[24:27], v[146:149], v[186:189], v[24:27]
	v_mfma_f32_16x16x32_bf16 v[28:31], v[154:157], v[186:189], v[28:31]
	v_mfma_f32_16x16x32_bf16 v[8:11], v[146:149], v[218:221], v[8:11]
	v_mfma_f32_16x16x32_bf16 v[12:15], v[154:157], v[218:221], v[12:15]
	s_barrier
	s_add_u32 s10, s92, 0x40080
	s_addc_u32 s11, s93, 0
	s_add_i32 s23, s24, s58
	v_lshl_add_u64 v[136:137], s[10:11], 0, v[176:177]
	s_mov_b32 m0, s23
	s_nop 0
	global_load_lds_dwordx4 v[136:137], off
	v_lshl_add_u64 v[136:137], s[10:11], 0, v[128:129]
	s_add_i32 m0, s23, 0x2000
	s_nop 0
	global_load_lds_dwordx4 v[136:137], off
	v_add_u32_e32 v136, 0x10000, v139
	ds_read_b128 v[142:145], v136
	ds_read_b128 v[146:149], v136 offset:1024
	ds_read_b128 v[150:153], v136 offset:2048
	ds_read_b128 v[154:157], v136 offset:3072
	s_waitcnt vmcnt(6)
	s_barrier
	v_mfma_f32_16x16x32_bf16 v[48:51], v[222:225], v[158:161], v[48:51]
	v_mfma_f32_16x16x32_bf16 v[52:55], v[230:233], v[158:161], v[52:55]
	v_mfma_f32_16x16x32_bf16 v[32:35], v[222:225], v[166:169], v[32:35]
	v_mfma_f32_16x16x32_bf16 v[36:39], v[230:233], v[166:169], v[36:39]
	v_mfma_f32_16x16x32_bf16 v[16:19], v[222:225], v[182:185], v[16:19]
	v_mfma_f32_16x16x32_bf16 v[20:23], v[230:233], v[182:185], v[20:23]
	v_mfma_f32_16x16x32_bf16 v[0:3], v[222:225], v[214:217], v[0:3]
	v_mfma_f32_16x16x32_bf16 v[4:7], v[230:233], v[214:217], v[4:7]
	v_mfma_f32_16x16x32_bf16 v[48:51], v[226:229], v[162:165], v[48:51]
	v_mfma_f32_16x16x32_bf16 v[52:55], v[234:237], v[162:165], v[52:55]
	v_mfma_f32_16x16x32_bf16 v[32:35], v[226:229], v[170:173], v[32:35]
	v_mfma_f32_16x16x32_bf16 v[36:39], v[234:237], v[170:173], v[36:39]
	v_mfma_f32_16x16x32_bf16 v[16:19], v[226:229], v[186:189], v[16:19]
	v_mfma_f32_16x16x32_bf16 v[20:23], v[234:237], v[186:189], v[20:23]
	v_mfma_f32_16x16x32_bf16 v[0:3], v[226:229], v[218:221], v[0:3]
	v_mfma_f32_16x16x32_bf16 v[4:7], v[234:237], v[218:221], v[4:7]
	s_add_i32 s22, s22, 2
	s_add_u32 s7, s7, 0x100
	s_addc_u32 s21, s21, 0
	s_cmp_gt_u32 s22, 13
	s_mov_b64 s[10:11], s[2:3]
	s_barrier
	s_cbranch_scc0 .LBB0_320
	v_mul_f32_e32 v252, 0xbfb8aa3b, v120
	v_mul_f32_e32 v253, 0xbfb8aa3b, v121
	v_exp_f32_e32 v252, v252
	v_exp_f32_e32 v253, v253
	s_lshl_b32 s0, s0, 7
	s_ashr_i32 s1, s0, 31
	v_add_f32_e32 v252, 1.0, v252
	v_add_f32_e32 v253, 1.0, v253
	v_rcp_f32_e32 v252, v252
	v_rcp_f32_e32 v253, v253
	v_lshl_add_u32 v141, s16, 8, v138
	v_lshl_add_u64 v[136:137], s[0:1], 1, v[130:131]
	s_movk_i32 s2, 0x1600
	v_pk_mul_f32 v[120:121], v[120:121], v[252:253]
	s_and_b64 vcc, exec, s[14:15]
	v_pk_mul_f32 v[120:121], v[124:125], v[120:121]
	v_mul_f32_e32 v124, 0xbfb8aa3b, v122
	v_mul_f32_e32 v125, 0xbfb8aa3b, v123
	v_exp_f32_e32 v124, v124
	v_exp_f32_e32 v125, v125
	v_cvt_pk_bf16_f32 v120, v120, v121
	v_add_f32_e32 v124, 1.0, v124
	v_add_f32_e32 v125, 1.0, v125
	v_rcp_f32_e32 v124, v124
	v_rcp_f32_e32 v125, v125
	s_nop 0
	v_pk_mul_f32 v[122:123], v[122:123], v[124:125]
	s_nop 0
	v_pk_mul_f32 v[122:123], v[126:127], v[122:123]
	s_nop 0
	v_cvt_pk_bf16_f32 v121, v122, v123
	v_mul_f32_e32 v122, 0xbfb8aa3b, v112
	v_mul_f32_e32 v123, 0xbfb8aa3b, v113
	v_exp_f32_e32 v122, v122
	v_exp_f32_e32 v123, v123
	v_add_f32_e32 v122, 1.0, v122
	v_add_f32_e32 v123, 1.0, v123
	v_rcp_f32_e32 v122, v122
	v_rcp_f32_e32 v123, v123
	s_nop 0
	v_pk_mul_f32 v[112:113], v[112:113], v[122:123]
	s_nop 0
	v_pk_mul_f32 v[112:113], v[116:117], v[112:113]
	v_mul_f32_e32 v116, 0xbfb8aa3b, v114
	v_mul_f32_e32 v117, 0xbfb8aa3b, v115
	v_exp_f32_e32 v116, v116
	v_exp_f32_e32 v117, v117
	v_cvt_pk_bf16_f32 v122, v112, v113
	v_mad_i64_i32 v[112:113], s[0:1], v141, s2, v[136:137]
	v_add_f32_e32 v116, 1.0, v116
	v_add_f32_e32 v117, 1.0, v117
	v_rcp_f32_e32 v116, v116
	v_rcp_f32_e32 v117, v117
	s_nop 0
	v_pk_mul_f32 v[114:115], v[114:115], v[116:117]
	s_nop 0
	v_pk_mul_f32 v[114:115], v[118:119], v[114:115]
	s_nop 0
	v_cvt_pk_bf16_f32 v123, v114, v115
	global_store_dwordx4 v[112:113], v[120:123], off
	v_mul_f32_e32 v112, 0xbfb8aa3b, v104
	v_mul_f32_e32 v113, 0xbfb8aa3b, v105
	v_exp_f32_e32 v112, v112
	v_exp_f32_e32 v113, v113
	v_or_b32_e32 v114, 16, v141
	v_add_f32_e32 v112, 1.0, v112
	v_add_f32_e32 v113, 1.0, v113
	v_rcp_f32_e32 v112, v112
	v_rcp_f32_e32 v113, v113
	s_nop 0
	v_pk_mul_f32 v[104:105], v[104:105], v[112:113]
	s_nop 0
	v_pk_mul_f32 v[104:105], v[108:109], v[104:105]
	v_mul_f32_e32 v108, 0xbfb8aa3b, v106
	v_mul_f32_e32 v109, 0xbfb8aa3b, v107
	v_exp_f32_e32 v108, v108
	v_exp_f32_e32 v109, v109
	v_cvt_pk_bf16_f32 v104, v104, v105
	v_add_f32_e32 v108, 1.0, v108
	v_add_f32_e32 v109, 1.0, v109
	v_rcp_f32_e32 v108, v108
	v_rcp_f32_e32 v109, v109
	s_nop 0
	v_pk_mul_f32 v[106:107], v[106:107], v[108:109]
	s_nop 0
	v_pk_mul_f32 v[106:107], v[110:111], v[106:107]
	s_nop 0
	v_cvt_pk_bf16_f32 v105, v106, v107
; __device__ __forceinline__ u32x4 mk4(unsigned a, unsigned b, unsigned c, unsigned d) { return (u32x4){a, b, c, d}; }
; __device__ __forceinline__ float silu_f(float x) { return x * __builtin_amdgcn_rcpf(1.f + __expf(-x)); }
; __device__ __forceinline__ void gemm_phase(const Params& p, int l, const bf16_t* __restrict__ A, const bf16_t* __restrict__ Bt, int M, int N, int K,
;                            int epi, bf16_t* __restrict__ outp, char* smem, int wvi) {
;     ...
;     } else if (epi == EPI_SWIGLU) {
; #pragma unroll
;       for (int ai = 0; ai < 2; ++ai)
; #pragma unroll
;         for (int m = 0; m < 4; ++m) {
;           bf16_t* rp = outp + (size_t)(r0 + ai * GHALF + m * 16) * DFF + pn * 128 + wc * 32 + fq * 8;
;           unsigned pk[4];
; #pragma unroll
;           for (int bj = 0; bj < 2; ++bj) {
;             const f32x4 g = acc[ai][bj][m][0], u = acc[ai][bj][m][1];
;             const float o0 = silu_f(g[0]) * u[0], o1 = silu_f(g[1]) * u[1], o2 = silu_f(g[2]) * u[2], o3 = silu_f(g[3]) * u[3];
;             pk[2 * bj] = pk2(o0, o1); pk[2 * bj + 1] = pk2(o2, o3);
;           }
;           *reinterpret_cast<u32x4*>(rp) = mk4(pk[0], pk[1], pk[2], pk[3]);
;         }
	v_mul_f32_e32 v106, 0xbfb8aa3b, v96
	v_mul_f32_e32 v107, 0xbfb8aa3b, v97
	v_exp_f32_e32 v106, v106
	v_exp_f32_e32 v107, v107
	v_add_f32_e32 v106, 1.0, v106
	v_add_f32_e32 v107, 1.0, v107
	v_rcp_f32_e32 v106, v106
	v_rcp_f32_e32 v107, v107
	s_nop 0
	v_pk_mul_f32 v[96:97], v[96:97], v[106:107]
	s_nop 0
	v_pk_mul_f32 v[96:97], v[100:101], v[96:97]
	v_mul_f32_e32 v100, 0xbfb8aa3b, v98
	v_mul_f32_e32 v101, 0xbfb8aa3b, v99
	v_exp_f32_e32 v100, v100
	v_exp_f32_e32 v101, v101
	v_cvt_pk_bf16_f32 v106, v96, v97
	v_mad_i64_i32 v[96:97], s[0:1], v114, s2, v[136:137]
	v_add_f32_e32 v100, 1.0, v100
	v_add_f32_e32 v101, 1.0, v101
	v_rcp_f32_e32 v100, v100
	v_rcp_f32_e32 v101, v101
	s_nop 0
	v_pk_mul_f32 v[98:99], v[98:99], v[100:101]
	s_nop 0
	v_pk_mul_f32 v[98:99], v[102:103], v[98:99]
	s_nop 0
	v_cvt_pk_bf16_f32 v107, v98, v99
	global_store_dwordx4 v[96:97], v[104:107], off
	v_mul_f32_e32 v96, 0xbfb8aa3b, v88
	v_mul_f32_e32 v97, 0xbfb8aa3b, v89
	v_exp_f32_e32 v96, v96
	v_exp_f32_e32 v97, v97
	v_or_b32_e32 v98, 32, v141
	v_add_f32_e32 v96, 1.0, v96
	v_add_f32_e32 v97, 1.0, v97
	v_rcp_f32_e32 v96, v96
	v_rcp_f32_e32 v97, v97
	s_nop 0
	v_pk_mul_f32 v[88:89], v[88:89], v[96:97]
	s_nop 0
	v_pk_mul_f32 v[88:89], v[92:93], v[88:89]
	v_mul_f32_e32 v92, 0xbfb8aa3b, v90
	v_mul_f32_e32 v93, 0xbfb8aa3b, v91
	v_exp_f32_e32 v92, v92
	v_exp_f32_e32 v93, v93
	v_cvt_pk_bf16_f32 v88, v88, v89
	v_add_f32_e32 v92, 1.0, v92
	v_add_f32_e32 v93, 1.0, v93
	v_rcp_f32_e32 v92, v92
	v_rcp_f32_e32 v93, v93
	s_nop 0
	v_pk_mul_f32 v[90:91], v[90:91], v[92:93]
	s_nop 0
	v_pk_mul_f32 v[90:91], v[94:95], v[90:91]
	s_nop 0
	v_cvt_pk_bf16_f32 v89, v90, v91
	v_mul_f32_e32 v90, 0xbfb8aa3b, v80
	v_mul_f32_e32 v91, 0xbfb8aa3b, v81
	v_exp_f32_e32 v90, v90
	v_exp_f32_e32 v91, v91
	v_add_f32_e32 v90, 1.0, v90
	v_add_f32_e32 v91, 1.0, v91
	v_rcp_f32_e32 v90, v90
	v_rcp_f32_e32 v91, v91
	s_nop 0
	v_pk_mul_f32 v[80:81], v[80:81], v[90:91]
	s_nop 0
	v_pk_mul_f32 v[80:81], v[84:85], v[80:81]
	v_mul_f32_e32 v84, 0xbfb8aa3b, v82
	v_mul_f32_e32 v85, 0xbfb8aa3b, v83
	v_exp_f32_e32 v84, v84
	v_exp_f32_e32 v85, v85
	v_cvt_pk_bf16_f32 v90, v80, v81
	v_mad_i64_i32 v[80:81], s[0:1], v98, s2, v[136:137]
	v_add_f32_e32 v84, 1.0, v84
	v_add_f32_e32 v85, 1.0, v85
	v_rcp_f32_e32 v84, v84
	v_rcp_f32_e32 v85, v85
	s_nop 0
	v_pk_mul_f32 v[82:83], v[82:83], v[84:85]
	s_nop 0
	v_pk_mul_f32 v[82:83], v[86:87], v[82:83]
	s_nop 0
	v_cvt_pk_bf16_f32 v91, v82, v83
	global_store_dwordx4 v[80:81], v[88:91], off
	v_mul_f32_e32 v80, 0xbfb8aa3b, v72
	v_mul_f32_e32 v81, 0xbfb8aa3b, v73
	v_exp_f32_e32 v80, v80
	v_exp_f32_e32 v81, v81
	v_or_b32_e32 v82, 48, v141
	v_add_f32_e32 v80, 1.0, v80
	v_add_f32_e32 v81, 1.0, v81
	v_rcp_f32_e32 v80, v80
	v_rcp_f32_e32 v81, v81
	s_nop 0
	v_pk_mul_f32 v[72:73], v[72:73], v[80:81]
	s_nop 0
	v_pk_mul_f32 v[72:73], v[76:77], v[72:73]
	v_mul_f32_e32 v76, 0xbfb8aa3b, v74
	v_mul_f32_e32 v77, 0xbfb8aa3b, v75
	v_exp_f32_e32 v76, v76
	v_exp_f32_e32 v77, v77
	v_cvt_pk_bf16_f32 v72, v72, v73
	v_add_f32_e32 v76, 1.0, v76
	v_add_f32_e32 v77, 1.0, v77
	v_rcp_f32_e32 v76, v76
	v_rcp_f32_e32 v77, v77
	s_nop 0
	v_pk_mul_f32 v[74:75], v[74:75], v[76:77]
	s_nop 0
	v_pk_mul_f32 v[74:75], v[78:79], v[74:75]
	s_nop 0
	v_cvt_pk_bf16_f32 v73, v74, v75
	v_mul_f32_e32 v74, 0xbfb8aa3b, v64
	v_mul_f32_e32 v75, 0xbfb8aa3b, v65
	v_exp_f32_e32 v74, v74
	v_exp_f32_e32 v75, v75
	v_add_f32_e32 v74, 1.0, v74
	v_add_f32_e32 v75, 1.0, v75
	v_rcp_f32_e32 v74, v74
	v_rcp_f32_e32 v75, v75
	s_nop 0
	v_pk_mul_f32 v[64:65], v[64:65], v[74:75]
	s_nop 0
	v_pk_mul_f32 v[64:65], v[68:69], v[64:65]
	v_mul_f32_e32 v68, 0xbfb8aa3b, v66
	v_mul_f32_e32 v69, 0xbfb8aa3b, v67
	v_exp_f32_e32 v68, v68
	v_exp_f32_e32 v69, v69
	v_cvt_pk_bf16_f32 v74, v64, v65
	v_mad_i64_i32 v[64:65], s[0:1], v82, s2, v[136:137]
	v_add_f32_e32 v68, 1.0, v68
	v_add_f32_e32 v69, 1.0, v69
	v_rcp_f32_e32 v68, v68
	v_rcp_f32_e32 v69, v69
	s_nop 0
	v_pk_mul_f32 v[66:67], v[66:67], v[68:69]
	s_nop 0
	v_pk_mul_f32 v[66:67], v[70:71], v[66:67]
	s_nop 0
	v_cvt_pk_bf16_f32 v75, v66, v67
	global_store_dwordx4 v[64:65], v[72:75], off
	v_mul_f32_e32 v64, 0xbfb8aa3b, v56
	v_mul_f32_e32 v65, 0xbfb8aa3b, v57
	v_exp_f32_e32 v64, v64
	v_exp_f32_e32 v65, v65
	v_add_u32_e32 v66, 0x80, v141
	v_add_f32_e32 v64, 1.0, v64
	v_add_f32_e32 v65, 1.0, v65
	v_rcp_f32_e32 v64, v64
	v_rcp_f32_e32 v65, v65
	s_nop 0
	v_pk_mul_f32 v[56:57], v[56:57], v[64:65]
	s_nop 0
	v_pk_mul_f32 v[56:57], v[60:61], v[56:57]
	v_mul_f32_e32 v60, 0xbfb8aa3b, v58
	v_mul_f32_e32 v61, 0xbfb8aa3b, v59
	v_exp_f32_e32 v60, v60
	v_exp_f32_e32 v61, v61
	v_cvt_pk_bf16_f32 v56, v56, v57
	v_add_f32_e32 v60, 1.0, v60
	v_add_f32_e32 v61, 1.0, v61
	v_rcp_f32_e32 v60, v60
	v_rcp_f32_e32 v61, v61
	s_nop 0
	v_pk_mul_f32 v[58:59], v[58:59], v[60:61]
	s_nop 0
	v_pk_mul_f32 v[58:59], v[62:63], v[58:59]
	s_nop 0
	v_cvt_pk_bf16_f32 v57, v58, v59
	v_mul_f32_e32 v58, 0xbfb8aa3b, v48
	v_mul_f32_e32 v59, 0xbfb8aa3b, v49
	v_exp_f32_e32 v58, v58
	v_exp_f32_e32 v59, v59
	v_add_f32_e32 v58, 1.0, v58
	v_add_f32_e32 v59, 1.0, v59
	v_rcp_f32_e32 v58, v58
	v_rcp_f32_e32 v59, v59
	s_nop 0
	v_pk_mul_f32 v[48:49], v[48:49], v[58:59]
	s_nop 0
	v_pk_mul_f32 v[48:49], v[52:53], v[48:49]
	v_mul_f32_e32 v52, 0xbfb8aa3b, v50
	v_mul_f32_e32 v53, 0xbfb8aa3b, v51
	v_exp_f32_e32 v52, v52
	v_exp_f32_e32 v53, v53
	v_cvt_pk_bf16_f32 v58, v48, v49
	v_mad_i64_i32 v[48:49], s[0:1], v66, s2, v[136:137]
	v_add_f32_e32 v52, 1.0, v52
	v_add_f32_e32 v53, 1.0, v53
	v_rcp_f32_e32 v52, v52
	v_rcp_f32_e32 v53, v53
	s_nop 0
	v_pk_mul_f32 v[50:51], v[50:51], v[52:53]
	s_nop 0
	v_pk_mul_f32 v[50:51], v[54:55], v[50:51]
	s_nop 0
	v_cvt_pk_bf16_f32 v59, v50, v51
; __device__ __forceinline__ u32x4 mk4(unsigned a, unsigned b, unsigned c, unsigned d) { return (u32x4){a, b, c, d}; }
; __device__ __forceinline__ float silu_f(float x) { return x * __builtin_amdgcn_rcpf(1.f + __expf(-x)); }
; __device__ __forceinline__ void gemm_phase(const Params& p, int l, const bf16_t* __restrict__ A, const bf16_t* __restrict__ Bt, int M, int N, int K,
;                            int epi, bf16_t* __restrict__ outp, char* smem, int wvi) {
;     ...
;     } else if (epi == EPI_SWIGLU) {
; #pragma unroll
;       for (int ai = 0; ai < 2; ++ai)
; #pragma unroll
;         for (int m = 0; m < 4; ++m) {
;           bf16_t* rp = outp + (size_t)(r0 + ai * GHALF + m * 16) * DFF + pn * 128 + wc * 32 + fq * 8;
;           unsigned pk[4];
; #pragma unroll
;           for (int bj = 0; bj < 2; ++bj) {
;             const f32x4 g = acc[ai][bj][m][0], u = acc[ai][bj][m][1];
;             const float o0 = silu_f(g[0]) * u[0], o1 = silu_f(g[1]) * u[1], o2 = silu_f(g[2]) * u[2], o3 = silu_f(g[3]) * u[3];
;             pk[2 * bj] = pk2(o0, o1); pk[2 * bj + 1] = pk2(o2, o3);
;           }
;           *reinterpret_cast<u32x4*>(rp) = mk4(pk[0], pk[1], pk[2], pk[3]);
;         }
	global_store_dwordx4 v[48:49], v[56:59], off
	v_mul_f32_e32 v48, 0xbfb8aa3b, v40
	v_mul_f32_e32 v49, 0xbfb8aa3b, v41
	v_exp_f32_e32 v48, v48
	v_exp_f32_e32 v49, v49
	v_add_u32_e32 v50, 0x90, v141
	v_add_f32_e32 v48, 1.0, v48
	v_add_f32_e32 v49, 1.0, v49
	v_rcp_f32_e32 v48, v48
	v_rcp_f32_e32 v49, v49
	s_nop 0
	v_pk_mul_f32 v[40:41], v[40:41], v[48:49]
	s_nop 0
	v_pk_mul_f32 v[40:41], v[44:45], v[40:41]
	v_mul_f32_e32 v44, 0xbfb8aa3b, v42
	v_mul_f32_e32 v45, 0xbfb8aa3b, v43
	v_exp_f32_e32 v44, v44
	v_exp_f32_e32 v45, v45
	v_cvt_pk_bf16_f32 v40, v40, v41
	v_add_f32_e32 v44, 1.0, v44
	v_add_f32_e32 v45, 1.0, v45
	v_rcp_f32_e32 v44, v44
	v_rcp_f32_e32 v45, v45
	s_nop 0
	v_pk_mul_f32 v[42:43], v[42:43], v[44:45]
	s_nop 0
	v_pk_mul_f32 v[42:43], v[46:47], v[42:43]
	s_nop 0
	v_cvt_pk_bf16_f32 v41, v42, v43
	v_mul_f32_e32 v42, 0xbfb8aa3b, v32
	v_mul_f32_e32 v43, 0xbfb8aa3b, v33
	v_exp_f32_e32 v42, v42
	v_exp_f32_e32 v43, v43
	v_add_f32_e32 v42, 1.0, v42
	v_add_f32_e32 v43, 1.0, v43
	v_rcp_f32_e32 v42, v42
	v_rcp_f32_e32 v43, v43
	s_nop 0
	v_pk_mul_f32 v[32:33], v[32:33], v[42:43]
	s_nop 0
	v_pk_mul_f32 v[32:33], v[36:37], v[32:33]
	v_mul_f32_e32 v36, 0xbfb8aa3b, v34
	v_mul_f32_e32 v37, 0xbfb8aa3b, v35
	v_exp_f32_e32 v36, v36
	v_exp_f32_e32 v37, v37
	v_cvt_pk_bf16_f32 v42, v32, v33
	v_mad_i64_i32 v[32:33], s[0:1], v50, s2, v[136:137]
	v_add_f32_e32 v36, 1.0, v36
	v_add_f32_e32 v37, 1.0, v37
	v_rcp_f32_e32 v36, v36
	v_rcp_f32_e32 v37, v37
	s_nop 0
	v_pk_mul_f32 v[34:35], v[34:35], v[36:37]
	s_nop 0
	v_pk_mul_f32 v[34:35], v[38:39], v[34:35]
	s_nop 0
	v_cvt_pk_bf16_f32 v43, v34, v35
	global_store_dwordx4 v[32:33], v[40:43], off
	v_mul_f32_e32 v32, 0xbfb8aa3b, v24
	v_mul_f32_e32 v33, 0xbfb8aa3b, v25
	v_exp_f32_e32 v32, v32
	v_exp_f32_e32 v33, v33
	v_add_u32_e32 v34, 0xa0, v141
	v_add_f32_e32 v32, 1.0, v32
	v_add_f32_e32 v33, 1.0, v33
	v_rcp_f32_e32 v32, v32
	v_rcp_f32_e32 v33, v33
	s_nop 0
	v_pk_mul_f32 v[24:25], v[24:25], v[32:33]
	s_nop 0
	v_pk_mul_f32 v[24:25], v[28:29], v[24:25]
	v_mul_f32_e32 v28, 0xbfb8aa3b, v26
	v_mul_f32_e32 v29, 0xbfb8aa3b, v27
	v_exp_f32_e32 v28, v28
	v_exp_f32_e32 v29, v29
	v_cvt_pk_bf16_f32 v24, v24, v25
	v_add_f32_e32 v28, 1.0, v28
	v_add_f32_e32 v29, 1.0, v29
	v_rcp_f32_e32 v28, v28
	v_rcp_f32_e32 v29, v29
	s_nop 0
	v_pk_mul_f32 v[26:27], v[26:27], v[28:29]
	s_nop 0
	v_pk_mul_f32 v[26:27], v[30:31], v[26:27]
	s_nop 0
	v_cvt_pk_bf16_f32 v25, v26, v27
	v_mul_f32_e32 v26, 0xbfb8aa3b, v16
	v_mul_f32_e32 v27, 0xbfb8aa3b, v17
	v_exp_f32_e32 v26, v26
	v_exp_f32_e32 v27, v27
	v_add_f32_e32 v26, 1.0, v26
	v_add_f32_e32 v27, 1.0, v27
	v_rcp_f32_e32 v26, v26
	v_rcp_f32_e32 v27, v27
	s_nop 0
	v_pk_mul_f32 v[16:17], v[16:17], v[26:27]
	s_nop 0
	v_pk_mul_f32 v[16:17], v[20:21], v[16:17]
	v_mul_f32_e32 v20, 0xbfb8aa3b, v18
	v_mul_f32_e32 v21, 0xbfb8aa3b, v19
	v_exp_f32_e32 v20, v20
	v_exp_f32_e32 v21, v21
	v_cvt_pk_bf16_f32 v26, v16, v17
	v_mad_i64_i32 v[16:17], s[0:1], v34, s2, v[136:137]
	v_add_f32_e32 v20, 1.0, v20
	v_add_f32_e32 v21, 1.0, v21
	v_rcp_f32_e32 v20, v20
	v_rcp_f32_e32 v21, v21
	s_nop 0
	v_pk_mul_f32 v[18:19], v[18:19], v[20:21]
	s_nop 0
	v_pk_mul_f32 v[18:19], v[22:23], v[18:19]
	s_nop 0
	v_cvt_pk_bf16_f32 v27, v18, v19
	global_store_dwordx4 v[16:17], v[24:27], off
	v_mul_f32_e32 v16, 0xbfb8aa3b, v8
	v_mul_f32_e32 v17, 0xbfb8aa3b, v9
	v_exp_f32_e32 v16, v16
	v_exp_f32_e32 v17, v17
	v_add_u32_e32 v18, 0xb0, v141
	v_add_f32_e32 v16, 1.0, v16
	v_add_f32_e32 v17, 1.0, v17
	v_rcp_f32_e32 v16, v16
	v_rcp_f32_e32 v17, v17
	s_nop 0
	v_pk_mul_f32 v[8:9], v[8:9], v[16:17]
	s_nop 0
	v_pk_mul_f32 v[8:9], v[12:13], v[8:9]
	v_mul_f32_e32 v12, 0xbfb8aa3b, v10
	v_mul_f32_e32 v13, 0xbfb8aa3b, v11
	v_exp_f32_e32 v12, v12
	v_exp_f32_e32 v13, v13
	v_cvt_pk_bf16_f32 v8, v8, v9
	v_add_f32_e32 v12, 1.0, v12
	v_add_f32_e32 v13, 1.0, v13
	v_rcp_f32_e32 v12, v12
	v_rcp_f32_e32 v13, v13
	s_nop 0
	v_pk_mul_f32 v[10:11], v[10:11], v[12:13]
	s_nop 0
	v_pk_mul_f32 v[10:11], v[14:15], v[10:11]
	s_nop 0
	v_cvt_pk_bf16_f32 v9, v10, v11
	v_mul_f32_e32 v10, 0xbfb8aa3b, v0
	v_mul_f32_e32 v11, 0xbfb8aa3b, v1
	v_exp_f32_e32 v10, v10
	v_exp_f32_e32 v11, v11
	v_add_f32_e32 v10, 1.0, v10
	v_add_f32_e32 v11, 1.0, v11
	v_rcp_f32_e32 v10, v10
	v_rcp_f32_e32 v11, v11
	s_nop 0
	v_pk_mul_f32 v[0:1], v[0:1], v[10:11]
	s_nop 0
	v_pk_mul_f32 v[0:1], v[4:5], v[0:1]
	v_mul_f32_e32 v4, 0xbfb8aa3b, v2
	v_mul_f32_e32 v5, 0xbfb8aa3b, v3
	v_exp_f32_e32 v4, v4
	v_exp_f32_e32 v5, v5
	v_cvt_pk_bf16_f32 v10, v0, v1
	v_mad_i64_i32 v[0:1], s[0:1], v18, s2, v[136:137]
	v_add_f32_e32 v4, 1.0, v4
	v_add_f32_e32 v5, 1.0, v5
	v_rcp_f32_e32 v4, v4
	v_rcp_f32_e32 v5, v5
	s_mov_b64 s[2:3], -1
	v_pk_mul_f32 v[2:3], v[2:3], v[4:5]
	s_nop 0
	v_pk_mul_f32 v[2:3], v[6:7], v[2:3]
	s_nop 0
	v_cvt_pk_bf16_f32 v11, v2, v3
	global_store_dwordx4 v[0:1], v[8:11], off
	s_cbranch_vccz .LBB0_316
; __device__ __forceinline__ f32x4 zero4() { float z = 0.f; asm volatile("" : "+v"(z)); return (f32x4){z, z, z, z}; }
; __device__ __forceinline__ void gemm_phase(const Params& p, int l, const bf16_t* __restrict__ A, const bf16_t* __restrict__ Bt, int M, int N, int K,
;                            int epi, bf16_t* __restrict__ outp, char* smem, int wvi) {
;     ...
;       if (!has_next) break;
; #pragma unroll
;       for (int a = 0; a < 2; ++a)
; #pragma unroll
;         for (int b = 0; b < 2; ++b)
; #pragma unroll
;           for (int m = 0; m < 4; ++m)
; #pragma unroll
;             for (int n = 0; n < 2; ++n) acc[a][b][m][n] = zero4();
;       Lw = Ln; pm = npm; pn = npn; cA = nA; cB = nB;
	v_mov_b32_e32 v120, v177
	v_mov_b32_e32 v124, v177
	v_mov_b32_e32 v104, v177
	v_mov_b32_e32 v108, v177
	v_mov_b32_e32 v88, v177
	v_mov_b32_e32 v92, v177
	v_mov_b32_e32 v72, v177
	v_mov_b32_e32 v76, v177
	v_mov_b32_e32 v112, v177
	v_mov_b32_e32 v116, v177
	v_mov_b32_e32 v96, v177
	v_mov_b32_e32 v100, v177
	v_mov_b32_e32 v80, v177
	v_mov_b32_e32 v84, v177
	v_mov_b32_e32 v64, v177
	v_mov_b32_e32 v68, v177
	v_mov_b32_e32 v56, v177
	v_mov_b32_e32 v60, v177
	v_mov_b32_e32 v40, v177
	v_mov_b32_e32 v44, v177
	v_mov_b32_e32 v24, v177
	v_mov_b32_e32 v28, v177
	v_mov_b32_e32 v8, v177
	v_mov_b32_e32 v12, v177
	v_mov_b32_e32 v48, v177
	v_mov_b32_e32 v52, v177
	v_mov_b32_e32 v32, v177
	v_mov_b32_e32 v36, v177
	v_mov_b32_e32 v16, v177
	v_mov_b32_e32 v20, v177
	v_mov_b32_e32 v0, v177
	v_mov_b32_e32 v4, v177
	s_nop 0
	v_mov_b32_e32 v121, v120
	v_mov_b32_e32 v122, v120
	v_mov_b32_e32 v123, v120
	v_mov_b32_e32 v125, v124
	v_mov_b32_e32 v126, v124
	v_mov_b32_e32 v127, v124
	v_mov_b32_e32 v105, v104
	v_mov_b32_e32 v106, v104
	v_mov_b32_e32 v107, v104
	v_mov_b32_e32 v109, v108
	v_mov_b32_e32 v110, v108
	v_mov_b32_e32 v111, v108
	v_mov_b32_e32 v89, v88
	v_mov_b32_e32 v90, v88
	v_mov_b32_e32 v91, v88
	v_mov_b32_e32 v93, v92
	v_mov_b32_e32 v94, v92
	v_mov_b32_e32 v95, v92
	s_nop 0
	v_mov_b32_e32 v73, v72
	v_mov_b32_e32 v74, v72
	v_mov_b32_e32 v75, v72
	v_mov_b32_e32 v77, v76
	v_mov_b32_e32 v78, v76
	v_mov_b32_e32 v79, v76
	v_mov_b32_e32 v113, v112
	v_mov_b32_e32 v114, v112
	v_mov_b32_e32 v115, v112
	v_mov_b32_e32 v117, v116
	v_mov_b32_e32 v118, v116
	v_mov_b32_e32 v119, v116
	v_mov_b32_e32 v97, v96
	v_mov_b32_e32 v98, v96
	v_mov_b32_e32 v99, v96
	v_mov_b32_e32 v101, v100
	v_mov_b32_e32 v102, v100
	v_mov_b32_e32 v103, v100
	s_nop 0
	v_mov_b32_e32 v81, v80
	v_mov_b32_e32 v82, v80
	v_mov_b32_e32 v83, v80
	v_mov_b32_e32 v85, v84
	v_mov_b32_e32 v86, v84
	v_mov_b32_e32 v87, v84
	v_mov_b32_e32 v65, v64
	v_mov_b32_e32 v66, v64
	v_mov_b32_e32 v67, v64
	v_mov_b32_e32 v69, v68
	v_mov_b32_e32 v70, v68
	v_mov_b32_e32 v71, v68
	v_mov_b32_e32 v57, v56
	v_mov_b32_e32 v58, v56
	v_mov_b32_e32 v59, v56
	v_mov_b32_e32 v61, v60
	v_mov_b32_e32 v62, v60
	v_mov_b32_e32 v63, v60
	s_nop 0
	v_mov_b32_e32 v41, v40
	v_mov_b32_e32 v42, v40
	v_mov_b32_e32 v43, v40
	v_mov_b32_e32 v45, v44
	v_mov_b32_e32 v46, v44
	v_mov_b32_e32 v47, v44
	v_mov_b32_e32 v25, v24
	v_mov_b32_e32 v26, v24
	v_mov_b32_e32 v27, v24
	v_mov_b32_e32 v29, v28
	v_mov_b32_e32 v30, v28
	v_mov_b32_e32 v31, v28
	v_mov_b32_e32 v9, v8
	v_mov_b32_e32 v10, v8
	v_mov_b32_e32 v11, v8
	v_mov_b32_e32 v13, v12
	v_mov_b32_e32 v14, v12
	v_mov_b32_e32 v15, v12
	s_nop 0
	v_mov_b32_e32 v49, v48
	v_mov_b32_e32 v50, v48
	v_mov_b32_e32 v51, v48
	v_mov_b32_e32 v53, v52
	v_mov_b32_e32 v54, v52
	v_mov_b32_e32 v55, v52
	v_mov_b32_e32 v33, v32
	v_mov_b32_e32 v34, v32
	v_mov_b32_e32 v35, v32
	v_mov_b32_e32 v37, v36
	v_mov_b32_e32 v38, v36
	v_mov_b32_e32 v39, v36
	v_mov_b32_e32 v17, v16
	v_mov_b32_e32 v18, v16
	v_mov_b32_e32 v19, v16
	v_mov_b32_e32 v21, v20
	v_mov_b32_e32 v22, v20
	v_mov_b32_e32 v23, v20
	s_mov_b64 s[2:3], 0
	v_mov_b32_e32 v1, v0
	v_mov_b32_e32 v2, v0
	v_mov_b32_e32 v3, v0
	v_mov_b32_e32 v5, v4
	v_mov_b32_e32 v6, v4
	v_mov_b32_e32 v7, v4
	s_branch .LBB0_316

; __device__ __forceinline__ f32x4 zero4() { float z = 0.f; asm volatile("" : "+v"(z)); return (f32x4){z, z, z, z}; }
; #define G_STAGE(bufoff, gbase) do { _Pragma("unroll") for (int _i = 0; _i < 2; ++_i) \
;     __builtin_amdgcn_global_load_lds((const unsigned*)((const char*)(gbase) + voff[_i]), (GLAS unsigned*)(lds + (bufoff) + ldsw + _i * 8192), 16, 0, 0); } while (0)
; #define G_WAIT_V(n) asm volatile("s_waitcnt vmcnt(" #n ")" ::: "memory")
; __device__ __forceinline__ void gemm_phase(const Params& p, int l, const bf16_t* __restrict__ A, const bf16_t* __restrict__ Bt, int M, int N, int K,
;                            int epi, bf16_t* __restrict__ outp, char* smem, int wvi) {
;     ...
;   for (int i = 0; i < 2; ++i) { int R, C; stage_rc(tidx * 16 + i * 8192, R, C); voff[i] = (unsigned)(R * K + C) * 2u; }
;   const size_t kstep = (size_t)(GBK * 2), hstep = (size_t)GHALF * K * 2, tstep = 2 * hstep;
;   const unsigned ldsw = (unsigned)wid * 1024u;
;   const int aoff = lds_byte(wr * 64 + fr, fq * 8), boff = lds_byte(wc * 32 + fr, fq * 8);
;   constexpr int HTB = GHT * 2;
;     ...
;   const int nM = M / GBM, nN = N / GBM, nwg = nM * nN;
;   auto tile_of = [&](int Lw, int& pm_, int& pn_) {
;     int wgid = Lw;
;     { const int q = nwg / GNXCD, r = nwg % GNXCD, xcd = wgid % GNXCD, off = wgid / GNXCD; wgid = (xcd < r ? xcd * (q + 1) : r * (q + 1) + (xcd - r) * q) + off; }
;     const int nig = GWGM * nN, gid = wgid / nig, fm = gid * GWGM, gsz = min(nM - fm, GWGM);
;     pm_ = fm + ((wgid % nig) % gsz); pn_ = (wgid % nig) / gsz;
;   };
;   int Lw = blockIdx.x;
;   if (Lw < nwg) {
;     int pm, pn; tile_of(Lw, pm, pn);
;     const char* cA = (const char*)A + (size_t)pm * tstep;
;     const char* cB = (const char*)Bt + (size_t)pn * tstep;
;     f32x4 acc[2][2][4][2];
; #pragma unroll
;     for (int a = 0; a < 2; ++a)
; #pragma unroll
;       for (int b = 0; b < 2; ++b)
; #pragma unroll
;         for (int m = 0; m < 4; ++m)
; #pragma unroll
;           for (int n = 0; n < 2; ++n) acc[a][b][m][n] = zero4();
;     bf16x8 At[4][2], B0[2][2], B1[2][2];
;     G_STAGE(G_SB(0, 0), cB); G_STAGE(G_SA(0, 0), cA); G_STAGE(G_SB(0, 1), cB + hstep); G_STAGE(G_SA(0, 1), cA + hstep);
;     if (wr == 1) G_BAR;
;     G_WAIT_V(4); G_BAR;
;     G_STAGE(G_SB(1, 0), cB + kstep); G_STAGE(G_SA(1, 0), cA + kstep); G_STAGE(G_SB(1, 1), cB + hstep + kstep);
;     G_WAIT_V(6); G_BAR;
.LBB0_368:
	v_lshl_add_u64 v[34:35], s[2:3], 0, v[176:177]
	v_mov_b32_e32 v129, v177
	v_lshl_add_u64 v[38:39], s[2:3], 0, v[128:129]
	v_lshl_add_u64 v[34:35], v[34:35], 0, s[64:65]
	s_add_i32 m0, s9, 0x18000
	v_lshl_add_u64 v[46:47], s[16:17], 0, v[176:177]
	s_waitcnt vmcnt(4)
	s_barrier
	global_load_lds_dwordx4 v[34:35], off
	v_lshl_add_u64 v[34:35], v[38:39], 0, s[64:65]
	s_add_i32 m0, s9, 0x1a000
	s_add_i32 s0, s9, 0x8000
	s_add_i32 s1, s9, 0xa000
	v_lshl_add_u64 v[50:51], s[16:17], 0, v[128:129]
	global_load_lds_dwordx4 v[34:35], off
	v_lshl_add_u64 v[34:35], v[46:47], 0, s[64:65]
	s_mov_b32 m0, s0
	s_add_u32 s2, s2, 0x40080
	global_load_lds_dwordx4 v[34:35], off
	v_lshl_add_u64 v[34:35], v[50:51], 0, s[64:65]
	s_mov_b32 m0, s1
	s_addc_u32 s3, s3, 0
	global_load_lds_dwordx4 v[34:35], off
	v_lshl_add_u64 v[34:35], s[2:3], 0, v[176:177]
	s_add_i32 m0, s9, 0x1c000
	v_and_b32_e32 v131, 15, v130
	global_load_lds_dwordx4 v[34:35], off
	v_lshl_add_u64 v[34:35], s[2:3], 0, v[128:129]
	s_add_i32 m0, s9, 0x1e000
	v_readlane_b32 s2, v248, 10
	global_load_lds_dwordx4 v[34:35], off
	s_nop 0
	v_or_b32_e32 v136, s2, v131
	v_lshlrev_b32_e32 v137, 6, v136
	v_and_b32_e32 v142, 48, v130
	s_movk_i32 s2, 0x3c0
	v_lshlrev_b32_e32 v143, 2, v136
	v_and_or_b32 v137, v137, s2, v142
	v_and_b32_e32 v143, 32, v143
	v_readlane_b32 s2, v248, 11
	v_lshlrev_b32_e32 v130, 2, v130
	v_lshlrev_b32_e32 v133, 13, v133
	v_lshlrev_b32_e32 v134, 13, v134
	v_bitop3_b32 v144, v137, s2, v143 bitop3:0xde
	v_lshl_or_b32 v131, v131, 6, v142
	v_and_b32_e32 v130, 32, v130
	v_readlane_b32 s2, v248, 12
	v_and_b32_e32 v133, 0x7fffc000, v133
	v_and_b32_e32 v134, 0x7fffc000, v134
	v_bitop3_b32 v137, v131, s2, v130 bitop3:0xde
	v_readlane_b32 s2, v248, 15
	v_lshl_add_u32 v132, v132, 10, v133
	v_lshl_add_u32 v134, v135, 10, v134
	s_waitcnt vmcnt(6)
	v_mov_b32_e32 v143, v177
	v_readlane_b32 s3, v248, 16
	v_or_b32_e32 v132, v132, v140
	v_or_b32_e32 v134, v134, v138
	v_lshl_add_u64 v[130:131], s[2:3], 0, v[142:143]
	v_add_lshl_u32 v132, v132, v141, 1
	v_mov_b32_e32 v133, v177
	s_mov_b64 s[2:3], 0x40080
	v_add_lshl_u32 v134, v134, v139, 1
	v_mov_b32_e32 v135, v177
	s_sext_i32_i8 s30, s4
	v_mov_b32_e32 v21, v20
	v_mov_b32_e32 v22, v20
	v_mov_b32_e32 v23, v20
	v_mov_b32_e32 v29, v28
	v_mov_b32_e32 v30, v28
	v_mov_b32_e32 v31, v28
	v_mov_b32_e32 v13, v12
	v_mov_b32_e32 v14, v12
	v_mov_b32_e32 v15, v12
	v_mov_b32_e32 v25, v24
	v_mov_b32_e32 v26, v24
	v_mov_b32_e32 v27, v24
	v_mov_b32_e32 v5, v4
	v_mov_b32_e32 v6, v4
	v_mov_b32_e32 v7, v4
	v_mov_b32_e32 v17, v16
	v_mov_b32_e32 v18, v16
	v_mov_b32_e32 v19, v16
	v_mov_b32_e32 v1, v0
	v_mov_b32_e32 v2, v0
	v_mov_b32_e32 v3, v0
	v_mov_b32_e32 v9, v8
	v_mov_b32_e32 v10, v8
	v_mov_b32_e32 v11, v8
	v_mov_b32_e32 v81, v80
	v_mov_b32_e32 v82, v80
	v_mov_b32_e32 v83, v80
	v_mov_b32_e32 v93, v92
	v_mov_b32_e32 v94, v92
	v_mov_b32_e32 v95, v92
	v_mov_b32_e32 v65, v64
	v_mov_b32_e32 v66, v64
	v_mov_b32_e32 v67, v64
	v_mov_b32_e32 v85, v84
	v_mov_b32_e32 v86, v84
	v_mov_b32_e32 v87, v84
	v_mov_b32_e32 v53, v52
	v_mov_b32_e32 v54, v52
	v_mov_b32_e32 v55, v52
	v_mov_b32_e32 v77, v76
	v_mov_b32_e32 v78, v76
	v_mov_b32_e32 v79, v76
	v_mov_b32_e32 v41, v40
	v_mov_b32_e32 v42, v40
	v_mov_b32_e32 v43, v40
	v_mov_b32_e32 v61, v60
	v_mov_b32_e32 v62, v60
	v_mov_b32_e32 v63, v60
	v_mov_b32_e32 v69, v68
	v_mov_b32_e32 v70, v68
	v_mov_b32_e32 v71, v68
	v_mov_b32_e32 v89, v88
	v_mov_b32_e32 v90, v88
	v_mov_b32_e32 v91, v88
	v_mov_b32_e32 v49, v48
	v_mov_b32_e32 v50, v48
	v_mov_b32_e32 v51, v48
	v_mov_b32_e32 v73, v72
	v_mov_b32_e32 v74, v72
	v_mov_b32_e32 v75, v72
	v_mov_b32_e32 v37, v36
	v_mov_b32_e32 v38, v36
	v_mov_b32_e32 v39, v36
	v_mov_b32_e32 v57, v56
	v_mov_b32_e32 v58, v56
	v_mov_b32_e32 v59, v56
	v_mov_b32_e32 v33, v32
	v_mov_b32_e32 v34, v32
	v_mov_b32_e32 v35, v32
	v_mov_b32_e32 v45, v44
	v_mov_b32_e32 v46, v44
	v_mov_b32_e32 v47, v44
	v_mov_b32_e32 v121, v120
	v_mov_b32_e32 v122, v120
	v_mov_b32_e32 v123, v120
	v_mov_b32_e32 v125, v124
	v_mov_b32_e32 v126, v124
	v_mov_b32_e32 v127, v124
	v_mov_b32_e32 v113, v112
	v_mov_b32_e32 v114, v112
	v_mov_b32_e32 v115, v112
	v_mov_b32_e32 v117, v116
	v_mov_b32_e32 v118, v116
	v_mov_b32_e32 v119, v116
	v_mov_b32_e32 v105, v104
	v_mov_b32_e32 v106, v104
	v_mov_b32_e32 v107, v104
	v_mov_b32_e32 v109, v108
	v_mov_b32_e32 v110, v108
	v_mov_b32_e32 v111, v108
	v_mov_b32_e32 v97, v96
	v_mov_b32_e32 v98, v96
	v_mov_b32_e32 v99, v96
	v_mov_b32_e32 v101, v100
	v_mov_b32_e32 v102, v100
	v_mov_b32_e32 v103, v100
	v_lshl_add_u64 v[132:133], v[132:133], 0, s[2:3]
	v_lshl_add_u64 v[134:135], v[134:135], 0, s[2:3]
	v_add_u32_e32 v138, 0, v144
	v_readlane_b32 s27, v248, 0
	s_barrier
	v_add_u32_e32 v139, 0x10000, v137
	ds_read_b128 v[140:143], v139
	ds_read_b128 v[144:147], v139 offset:1024
	ds_read_b128 v[148:151], v139 offset:2048
	ds_read_b128 v[152:155], v139 offset:3072
	s_branch .LBB0_370

; #define G_STAGE(bufoff, gbase) do { _Pragma("unroll") for (int _i = 0; _i < 2; ++_i) \
;     __builtin_amdgcn_global_load_lds((const unsigned*)((const char*)(gbase) + voff[_i]), (GLAS unsigned*)(lds + (bufoff) + ldsw + _i * 8192), 16, 0, 0); } while (0)
; #define G_LDA(dst, b, h) do { _Pragma("unroll") for (int m = 0; m < 4; ++m) _Pragma("unroll") for (int k = 0; k < 2; ++k) \
;     dst[m][k] = *(const GLAS bf16x8*)(lds + G_SA(b, h) + aoff + m * 2048 + k * 1024); } while (0)
; #define G_LDB(dst, b, h) do { _Pragma("unroll") for (int n = 0; n < 2; ++n) _Pragma("unroll") for (int k = 0; k < 2; ++k) \
;     dst[n][k] = *(const GLAS bf16x8*)(lds + G_SB(b, h) + boff + n * 2048 + k * 1024); } while (0)
; #define G_MMA(ai, bj, At_, Bt_) do { __builtin_amdgcn_s_setprio(1); \
;     _Pragma("unroll") for (int m = 0; m < 4; ++m) _Pragma("unroll") for (int n = 0; n < 2; ++n) _Pragma("unroll") for (int k = 0; k < 2; ++k) \
;       acc[ai][bj][m][n] = __builtin_amdgcn_mfma_f32_16x16x32_bf16(Bt_[n][k], At_[m][k], acc[ai][bj][m][n], 0, 0, 0); \
;     __builtin_amdgcn_s_setprio(0); } while (0)
; #define G_WAIT_V(n) asm volatile("s_waitcnt vmcnt(" #n ")" ::: "memory")
; #define G_WAIT_L(n) asm volatile("s_waitcnt lgkmcnt(" #n ")" ::: "memory")
; #define G_BAR __builtin_amdgcn_s_barrier()
; __device__ __forceinline__ void gemm_phase(const Params& p, int l, const bf16_t* __restrict__ A, const bf16_t* __restrict__ Bt, int M, int N, int K,
;                            int epi, bf16_t* __restrict__ outp, char* smem, int wvi) {
;     ...
;       for (int t = 0; t < nt; t += 2) {
;         const bool lastt = (t == nt - 2);
;         const char* a1 = cA + (size_t)(t + 1) * kstep;
;         const char* a2 = lastt ? nA : cA + (size_t)(t + 2) * kstep; const char* b2 = lastt ? nB : cB + (size_t)(t + 2) * kstep;
;         const char* a3 = a2 + kstep; const char* b3 = b2 + kstep;
;         G_LDB(B0, 0, 0); G_SCHED; G_LDA(At, 0, 0); G_STAGE(G_SA(1, 1), a1 + hstep);
;         G_WAIT_L(8); G_BAR; G_WAIT_L(0); G_MMA(0, 0, At, B0); G_BAR; G_SCHED;
;         G_LDB(B1, 0, 1); G_STAGE(G_SB(0, 0), b2);
;         G_BAR; G_WAIT_L(0); G_MMA(0, 1, At, B1); G_BAR;
;         G_LDA(At, 0, 1); G_STAGE(G_SA(0, 0), a2);
;         G_BAR; G_WAIT_L(0); G_MMA(1, 0, At, B0); G_BAR; G_SCHED;
;         G_STAGE(G_SB(0, 1), b2 + hstep);
;         G_WAIT_V(6); G_BAR; G_MMA(1, 1, At, B1); G_BAR;
.LBB0_373:
	s_add_u32 s2, s16, 0x100
	s_addc_u32 s3, s17, 0
	s_add_i32 s34, 0, 0x10000
	s_cmp_eq_u32 s55, 12
	s_cselect_b32 s29, s11, s3
	s_cselect_b32 s28, s10, s2
	s_cselect_b32 s13, s7, s53
	s_cselect_b32 s12, s5, s31
	v_lshl_add_u64 v[190:191], s[16:17], 0, v[132:133]
	s_add_i32 m0, s9, 0xc000
	ds_read_b128 v[156:159], v138
	ds_read_b128 v[160:163], v138 offset:1024
	ds_read_b128 v[164:167], v138 offset:2048
	ds_read_b128 v[168:171], v138 offset:3072
	ds_read_b128 v[172:175], v138 offset:4096
	ds_read_b128 v[182:185], v138 offset:5120
	ds_read_b128 v[186:189], v138 offset:6144
	ds_read_b128 v[214:217], v138 offset:7168
	global_load_lds_dwordx4 v[190:191], off
	v_lshl_add_u64 v[190:191], s[16:17], 0, v[134:135]
	s_add_i32 m0, s9, 0xe000
	s_nop 0
	global_load_lds_dwordx4 v[190:191], off
	s_waitcnt lgkmcnt(8)
	s_barrier
	s_waitcnt lgkmcnt(0)
	s_waitcnt lgkmcnt(0)
	v_mfma_f32_16x16x32_bf16 v[20:23], v[140:143], v[156:159], v[20:23]
	v_mfma_f32_16x16x32_bf16 v[28:31], v[148:151], v[156:159], v[28:31]
	v_mfma_f32_16x16x32_bf16 v[12:15], v[140:143], v[164:167], v[12:15]
	v_mfma_f32_16x16x32_bf16 v[24:27], v[148:151], v[164:167], v[24:27]
	v_mfma_f32_16x16x32_bf16 v[4:7], v[140:143], v[172:175], v[4:7]
	v_mfma_f32_16x16x32_bf16 v[16:19], v[148:151], v[172:175], v[16:19]
	v_mfma_f32_16x16x32_bf16 v[0:3], v[140:143], v[186:189], v[0:3]
	v_mfma_f32_16x16x32_bf16 v[8:11], v[148:151], v[186:189], v[8:11]
	v_mfma_f32_16x16x32_bf16 v[20:23], v[144:147], v[160:163], v[20:23]
	v_mfma_f32_16x16x32_bf16 v[28:31], v[152:155], v[160:163], v[28:31]
	v_mfma_f32_16x16x32_bf16 v[12:15], v[144:147], v[168:171], v[12:15]
	v_mfma_f32_16x16x32_bf16 v[24:27], v[152:155], v[168:171], v[24:27]
	v_mfma_f32_16x16x32_bf16 v[4:7], v[144:147], v[182:185], v[4:7]
	v_mfma_f32_16x16x32_bf16 v[16:19], v[152:155], v[182:185], v[16:19]
	v_mfma_f32_16x16x32_bf16 v[0:3], v[144:147], v[214:217], v[0:3]
	v_mfma_f32_16x16x32_bf16 v[8:11], v[152:155], v[214:217], v[8:11]
	s_barrier
	s_add_i32 s35, 0, 0x14000
	s_add_i32 s16, s34, s58
	v_add_u32_e32 v139, s35, v137
	v_lshl_add_u64 v[190:191], s[12:13], 0, v[176:177]
	s_mov_b32 m0, s16
	ds_read_b128 v[218:221], v139
	ds_read_b128 v[222:225], v139 offset:1024
	ds_read_b128 v[226:229], v139 offset:2048
	ds_read_b128 v[230:233], v139 offset:3072
	global_load_lds_dwordx4 v[190:191], off
	v_lshl_add_u64 v[234:235], s[12:13], 0, v[128:129]
	s_add_i32 m0, s16, 0x2000
	s_nop 0
	global_load_lds_dwordx4 v[234:235], off
	s_barrier
	s_waitcnt lgkmcnt(0)
	s_waitcnt lgkmcnt(0)
	v_mfma_f32_16x16x32_bf16 v[80:83], v[218:221], v[156:159], v[80:83]
	v_mfma_f32_16x16x32_bf16 v[92:95], v[226:229], v[156:159], v[92:95]
	v_mfma_f32_16x16x32_bf16 v[64:67], v[218:221], v[164:167], v[64:67]
	v_mfma_f32_16x16x32_bf16 v[84:87], v[226:229], v[164:167], v[84:87]
	v_mfma_f32_16x16x32_bf16 v[52:55], v[218:221], v[172:175], v[52:55]
	v_mfma_f32_16x16x32_bf16 v[76:79], v[226:229], v[172:175], v[76:79]
	v_mfma_f32_16x16x32_bf16 v[40:43], v[218:221], v[186:189], v[40:43]
	v_mfma_f32_16x16x32_bf16 v[60:63], v[226:229], v[186:189], v[60:63]
	v_mfma_f32_16x16x32_bf16 v[80:83], v[222:225], v[160:163], v[80:83]
	v_mfma_f32_16x16x32_bf16 v[92:95], v[230:233], v[160:163], v[92:95]
	v_mfma_f32_16x16x32_bf16 v[64:67], v[222:225], v[168:171], v[64:67]
	v_mfma_f32_16x16x32_bf16 v[84:87], v[230:233], v[168:171], v[84:87]
	v_mfma_f32_16x16x32_bf16 v[52:55], v[222:225], v[182:185], v[52:55]
	v_mfma_f32_16x16x32_bf16 v[76:79], v[230:233], v[182:185], v[76:79]
	v_mfma_f32_16x16x32_bf16 v[40:43], v[222:225], v[214:217], v[40:43]
	v_mfma_f32_16x16x32_bf16 v[60:63], v[230:233], v[214:217], v[60:63]
	s_mov_b32 m0, s9
	v_lshl_add_u64 v[236:237], s[28:29], 0, v[176:177]
	s_barrier
	ds_read_b128 v[156:159], v138 offset:16384
	ds_read_b128 v[160:163], v138 offset:17408
	ds_read_b128 v[164:167], v138 offset:18432
	ds_read_b128 v[168:171], v138 offset:19456
	ds_read_b128 v[172:175], v138 offset:20480
	ds_read_b128 v[182:185], v138 offset:21504
	ds_read_b128 v[186:189], v138 offset:22528
	ds_read_b128 v[214:217], v138 offset:23552
	global_load_lds_dwordx4 v[236:237], off
	v_lshl_add_u64 v[238:239], s[28:29], 0, v[128:129]
	s_mov_b32 m0, s24
	s_nop 0
	global_load_lds_dwordx4 v[238:239], off
	s_barrier
	s_waitcnt lgkmcnt(0)
	s_waitcnt lgkmcnt(0)
	v_mfma_f32_16x16x32_bf16 v[68:71], v[140:143], v[156:159], v[68:71]
	v_mfma_f32_16x16x32_bf16 v[88:91], v[148:151], v[156:159], v[88:91]
	v_mfma_f32_16x16x32_bf16 v[48:51], v[140:143], v[164:167], v[48:51]
	v_mfma_f32_16x16x32_bf16 v[72:75], v[148:151], v[164:167], v[72:75]
	v_mfma_f32_16x16x32_bf16 v[36:39], v[140:143], v[172:175], v[36:39]
	v_mfma_f32_16x16x32_bf16 v[56:59], v[148:151], v[172:175], v[56:59]
	v_mfma_f32_16x16x32_bf16 v[32:35], v[140:143], v[186:189], v[32:35]
	v_mfma_f32_16x16x32_bf16 v[44:47], v[148:151], v[186:189], v[44:47]
	v_mfma_f32_16x16x32_bf16 v[68:71], v[144:147], v[160:163], v[68:71]
	v_mfma_f32_16x16x32_bf16 v[88:91], v[152:155], v[160:163], v[88:91]
	v_mfma_f32_16x16x32_bf16 v[48:51], v[144:147], v[168:171], v[48:51]
	v_mfma_f32_16x16x32_bf16 v[72:75], v[152:155], v[168:171], v[72:75]
	v_mfma_f32_16x16x32_bf16 v[36:39], v[144:147], v[182:185], v[36:39]
	v_mfma_f32_16x16x32_bf16 v[56:59], v[152:155], v[182:185], v[56:59]
	v_mfma_f32_16x16x32_bf16 v[32:35], v[144:147], v[214:217], v[32:35]
	v_mfma_f32_16x16x32_bf16 v[44:47], v[152:155], v[214:217], v[44:47]
	s_barrier
	s_add_u32 s16, s12, 0x40000
	s_addc_u32 s17, s13, 0
	s_add_i32 s34, s35, s58
	v_lshl_add_u64 v[140:141], s[16:17], 0, v[176:177]
	s_mov_b32 m0, s34
	s_nop 0
	global_load_lds_dwordx4 v[140:141], off
	v_lshl_add_u64 v[140:141], s[16:17], 0, v[128:129]
	s_add_i32 m0, s34, 0x2000
	s_nop 0
	global_load_lds_dwordx4 v[140:141], off
	s_waitcnt vmcnt(6)
	s_barrier
; #define G_STAGE(bufoff, gbase) do { _Pragma("unroll") for (int _i = 0; _i < 2; ++_i) \
;     __builtin_amdgcn_global_load_lds((const unsigned*)((const char*)(gbase) + voff[_i]), (GLAS unsigned*)(lds + (bufoff) + ldsw + _i * 8192), 16, 0, 0); } while (0)
; #define G_LDA(dst, b, h) do { _Pragma("unroll") for (int m = 0; m < 4; ++m) _Pragma("unroll") for (int k = 0; k < 2; ++k) \
;     dst[m][k] = *(const GLAS bf16x8*)(lds + G_SA(b, h) + aoff + m * 2048 + k * 1024); } while (0)
; #define G_LDB(dst, b, h) do { _Pragma("unroll") for (int n = 0; n < 2; ++n) _Pragma("unroll") for (int k = 0; k < 2; ++k) \
;     dst[n][k] = *(const GLAS bf16x8*)(lds + G_SB(b, h) + boff + n * 2048 + k * 1024); } while (0)
; #define G_MMA(ai, bj, At_, Bt_) do { __builtin_amdgcn_s_setprio(1); \
;     _Pragma("unroll") for (int m = 0; m < 4; ++m) _Pragma("unroll") for (int n = 0; n < 2; ++n) _Pragma("unroll") for (int k = 0; k < 2; ++k) \
;       acc[ai][bj][m][n] = __builtin_amdgcn_mfma_f32_16x16x32_bf16(Bt_[n][k], At_[m][k], acc[ai][bj][m][n], 0, 0, 0); \
;     __builtin_amdgcn_s_setprio(0); } while (0)
; #define G_WAIT_V(n) asm volatile("s_waitcnt vmcnt(" #n ")" ::: "memory")
; #define G_WAIT_L(n) asm volatile("s_waitcnt lgkmcnt(" #n ")" ::: "memory")
; #define G_BAR __builtin_amdgcn_s_barrier()
; #define G_SCHED __builtin_amdgcn_sched_barrier(0)
; __device__ __forceinline__ void gemm_phase(const Params& p, int l, const bf16_t* __restrict__ A, const bf16_t* __restrict__ Bt, int M, int N, int K,
;                            int epi, bf16_t* __restrict__ outp, char* smem, int wvi) {
;     ...
;         G_WAIT_V(6); G_BAR; G_MMA(1, 1, At, B1); G_BAR;
;         G_LDB(B0, 1, 0); G_SCHED; G_LDA(At, 1, 0); G_STAGE(G_SA(0, 1), a2 + hstep);
;         G_WAIT_L(8); G_BAR; G_WAIT_L(0); G_MMA(0, 0, At, B0); G_BAR; G_SCHED;
;         G_LDB(B1, 1, 1); G_STAGE(G_SB(1, 0), b3);
;         G_BAR; G_WAIT_L(0); G_MMA(0, 1, At, B1); G_BAR;
;         G_LDA(At, 1, 1); G_STAGE(G_SA(1, 0), a3);
;         G_BAR; G_WAIT_L(0); G_MMA(1, 0, At, B0); G_BAR; G_SCHED;
	v_mfma_f32_16x16x32_bf16 v[120:123], v[218:221], v[156:159], v[120:123]
	v_mfma_f32_16x16x32_bf16 v[124:127], v[226:229], v[156:159], v[124:127]
	v_mfma_f32_16x16x32_bf16 v[112:115], v[218:221], v[164:167], v[112:115]
	v_mfma_f32_16x16x32_bf16 v[116:119], v[226:229], v[164:167], v[116:119]
	v_mfma_f32_16x16x32_bf16 v[104:107], v[218:221], v[172:175], v[104:107]
	v_mfma_f32_16x16x32_bf16 v[108:111], v[226:229], v[172:175], v[108:111]
	v_mfma_f32_16x16x32_bf16 v[96:99], v[218:221], v[186:189], v[96:99]
	v_mfma_f32_16x16x32_bf16 v[100:103], v[226:229], v[186:189], v[100:103]
	v_mfma_f32_16x16x32_bf16 v[120:123], v[222:225], v[160:163], v[120:123]
	v_mfma_f32_16x16x32_bf16 v[124:127], v[230:233], v[160:163], v[124:127]
	v_mfma_f32_16x16x32_bf16 v[112:115], v[222:225], v[168:171], v[112:115]
	v_mfma_f32_16x16x32_bf16 v[116:119], v[230:233], v[168:171], v[116:119]
	v_mfma_f32_16x16x32_bf16 v[104:107], v[222:225], v[182:185], v[104:107]
	v_mfma_f32_16x16x32_bf16 v[108:111], v[230:233], v[182:185], v[108:111]
	v_mfma_f32_16x16x32_bf16 v[96:99], v[222:225], v[214:217], v[96:99]
	v_mfma_f32_16x16x32_bf16 v[100:103], v[230:233], v[214:217], v[100:103]
	s_add_i32 s34, 0, 0x18000
	v_add_u32_e32 v139, s34, v137
	s_barrier
	ds_read_b128 v[140:143], v139
	ds_read_b128 v[144:147], v139 offset:1024
	ds_read_b128 v[148:151], v139 offset:2048
	ds_read_b128 v[152:155], v139 offset:3072
	s_add_u32 s16, s28, 0x40000
	s_addc_u32 s17, s29, 0
	s_mov_b32 m0, s25
	v_lshl_add_u64 v[218:219], s[16:17], 0, v[176:177]
	ds_read_b128 v[156:159], v138 offset:32768
	ds_read_b128 v[160:163], v138 offset:33792
	ds_read_b128 v[164:167], v138 offset:34816
	ds_read_b128 v[168:171], v138 offset:35840
	ds_read_b128 v[172:175], v138 offset:36864
	ds_read_b128 v[182:185], v138 offset:37888
	ds_read_b128 v[186:189], v138 offset:38912
	ds_read_b128 v[214:217], v138 offset:39936
	global_load_lds_dwordx4 v[218:219], off
	v_lshl_add_u64 v[218:219], s[16:17], 0, v[128:129]
	s_mov_b32 m0, s26
	s_nop 0
	global_load_lds_dwordx4 v[218:219], off
	s_waitcnt lgkmcnt(8)
	s_barrier
	s_waitcnt lgkmcnt(0)
	s_waitcnt lgkmcnt(0)
	v_mfma_f32_16x16x32_bf16 v[20:23], v[140:143], v[156:159], v[20:23]
	v_mfma_f32_16x16x32_bf16 v[28:31], v[148:151], v[156:159], v[28:31]
	v_mfma_f32_16x16x32_bf16 v[12:15], v[140:143], v[164:167], v[12:15]
	v_mfma_f32_16x16x32_bf16 v[24:27], v[148:151], v[164:167], v[24:27]
	v_mfma_f32_16x16x32_bf16 v[4:7], v[140:143], v[172:175], v[4:7]
	v_mfma_f32_16x16x32_bf16 v[16:19], v[148:151], v[172:175], v[16:19]
	v_mfma_f32_16x16x32_bf16 v[0:3], v[140:143], v[186:189], v[0:3]
	v_mfma_f32_16x16x32_bf16 v[8:11], v[148:151], v[186:189], v[8:11]
	v_mfma_f32_16x16x32_bf16 v[20:23], v[144:147], v[160:163], v[20:23]
	v_mfma_f32_16x16x32_bf16 v[28:31], v[152:155], v[160:163], v[28:31]
	v_mfma_f32_16x16x32_bf16 v[12:15], v[144:147], v[168:171], v[12:15]
	v_mfma_f32_16x16x32_bf16 v[24:27], v[152:155], v[168:171], v[24:27]
	v_mfma_f32_16x16x32_bf16 v[4:7], v[144:147], v[182:185], v[4:7]
	v_mfma_f32_16x16x32_bf16 v[16:19], v[152:155], v[182:185], v[16:19]
	v_mfma_f32_16x16x32_bf16 v[0:3], v[144:147], v[214:217], v[0:3]
	v_mfma_f32_16x16x32_bf16 v[8:11], v[152:155], v[214:217], v[8:11]
	s_barrier
	s_add_i32 s16, 0, 0x1c000
	s_add_i32 s17, s34, s58
	v_add_u32_e32 v139, s16, v137
	v_lshl_add_u64 v[190:191], v[190:191], 0, s[64:65]
	s_mov_b32 m0, s17
	ds_read_b128 v[218:221], v139
	ds_read_b128 v[222:225], v139 offset:1024
	ds_read_b128 v[226:229], v139 offset:2048
	ds_read_b128 v[230:233], v139 offset:3072
	global_load_lds_dwordx4 v[190:191], off
	v_lshl_add_u64 v[190:191], v[234:235], 0, s[64:65]
	s_add_i32 m0, s17, 0x2000
	s_nop 0
	global_load_lds_dwordx4 v[190:191], off
	s_barrier
	s_waitcnt lgkmcnt(0)
	s_waitcnt lgkmcnt(0)
	v_mfma_f32_16x16x32_bf16 v[80:83], v[218:221], v[156:159], v[80:83]
	v_mfma_f32_16x16x32_bf16 v[92:95], v[226:229], v[156:159], v[92:95]
	v_mfma_f32_16x16x32_bf16 v[64:67], v[218:221], v[164:167], v[64:67]
	v_mfma_f32_16x16x32_bf16 v[84:87], v[226:229], v[164:167], v[84:87]
	v_mfma_f32_16x16x32_bf16 v[52:55], v[218:221], v[172:175], v[52:55]
	v_mfma_f32_16x16x32_bf16 v[76:79], v[226:229], v[172:175], v[76:79]
	v_mfma_f32_16x16x32_bf16 v[40:43], v[218:221], v[186:189], v[40:43]
	v_mfma_f32_16x16x32_bf16 v[60:63], v[226:229], v[186:189], v[60:63]
	v_mfma_f32_16x16x32_bf16 v[80:83], v[222:225], v[160:163], v[80:83]
	v_mfma_f32_16x16x32_bf16 v[92:95], v[230:233], v[160:163], v[92:95]
	v_mfma_f32_16x16x32_bf16 v[64:67], v[222:225], v[168:171], v[64:67]
	v_mfma_f32_16x16x32_bf16 v[84:87], v[230:233], v[168:171], v[84:87]
	v_mfma_f32_16x16x32_bf16 v[52:55], v[222:225], v[182:185], v[52:55]
	v_mfma_f32_16x16x32_bf16 v[76:79], v[230:233], v[182:185], v[76:79]
	v_mfma_f32_16x16x32_bf16 v[40:43], v[222:225], v[214:217], v[40:43]
	v_mfma_f32_16x16x32_bf16 v[60:63], v[230:233], v[214:217], v[60:63]
	s_mov_b32 m0, s0
	v_lshl_add_u64 v[190:191], v[236:237], 0, s[64:65]
	s_barrier
	ds_read_b128 v[156:159], v138 offset:49152
	ds_read_b128 v[160:163], v138 offset:50176
	ds_read_b128 v[164:167], v138 offset:51200
	ds_read_b128 v[168:171], v138 offset:52224
	ds_read_b128 v[172:175], v138 offset:53248
	ds_read_b128 v[182:185], v138 offset:54272
	ds_read_b128 v[186:189], v138 offset:55296
	ds_read_b128 v[214:217], v138 offset:56320
	global_load_lds_dwordx4 v[190:191], off
	v_lshl_add_u64 v[190:191], v[238:239], 0, s[64:65]
	s_mov_b32 m0, s1
	s_nop 0
	global_load_lds_dwordx4 v[190:191], off
	s_waitcnt vmcnt(10)
	s_barrier
; __device__ __forceinline__ u32x4 mk4(unsigned a, unsigned b, unsigned c, unsigned d) { return (u32x4){a, b, c, d}; }
; #define G_STAGE(bufoff, gbase) do { _Pragma("unroll") for (int _i = 0; _i < 2; ++_i) \
;     __builtin_amdgcn_global_load_lds((const unsigned*)((const char*)(gbase) + voff[_i]), (GLAS unsigned*)(lds + (bufoff) + ldsw + _i * 8192), 16, 0, 0); } while (0)
; #define G_MMA(ai, bj, At_, Bt_) do { __builtin_amdgcn_s_setprio(1); \
;     _Pragma("unroll") for (int m = 0; m < 4; ++m) _Pragma("unroll") for (int n = 0; n < 2; ++n) _Pragma("unroll") for (int k = 0; k < 2; ++k) \
;       acc[ai][bj][m][n] = __builtin_amdgcn_mfma_f32_16x16x32_bf16(Bt_[n][k], At_[m][k], acc[ai][bj][m][n], 0, 0, 0); \
;     __builtin_amdgcn_s_setprio(0); } while (0)
; #define G_WAIT_V(n) asm volatile("s_waitcnt vmcnt(" #n ")" ::: "memory")
; #define G_WAIT_L(n) asm volatile("s_waitcnt lgkmcnt(" #n ")" ::: "memory")
; #define G_BAR __builtin_amdgcn_s_barrier()
; #define G_SCHED __builtin_amdgcn_sched_barrier(0)
; __device__ __forceinline__ void gemm_phase(const Params& p, int l, const bf16_t* __restrict__ A, const bf16_t* __restrict__ Bt, int M, int N, int K,
;                            int epi, bf16_t* __restrict__ outp, char* smem, int wvi) {
;     ...
;         G_BAR; G_WAIT_L(0); G_MMA(1, 0, At, B0); G_BAR; G_SCHED;
;         G_STAGE(G_SB(1, 1), b3 + hstep);
;         G_WAIT_V(6); G_BAR; G_MMA(1, 1, At, B1); G_BAR;
;       }
;       const int brow = pm * GBM, bcol = pn * GBM;
;     const int r0 = brow + wr * 64 + fr;
;     if (epi == EPI_PLAIN) {
; #pragma unroll
;       for (int ai = 0; ai < 2; ++ai)
; #pragma unroll
;         for (int m = 0; m < 4; ++m) {
;           bf16_t* rp = outp + (size_t)(r0 + ai * GHALF + m * 16) * N + bcol + wc * 32 + fq * 8;
; #pragma unroll
;           for (int bj = 0; bj < 2; ++bj) {
;             const f32x4 v0 = acc[ai][bj][m][0], v1 = acc[ai][bj][m][1];
;             *reinterpret_cast<u32x4*>(rp + bj * GHALF) = mk4(pk2(v0[0], v0[1]), pk2(v0[2], v0[3]), pk2(v1[0], v1[1]), pk2(v1[2], v1[3]));
	s_waitcnt lgkmcnt(0)
	s_waitcnt lgkmcnt(0)
	v_mfma_f32_16x16x32_bf16 v[68:71], v[140:143], v[156:159], v[68:71]
	v_mfma_f32_16x16x32_bf16 v[88:91], v[148:151], v[156:159], v[88:91]
	v_mfma_f32_16x16x32_bf16 v[48:51], v[140:143], v[164:167], v[48:51]
	v_mfma_f32_16x16x32_bf16 v[72:75], v[148:151], v[164:167], v[72:75]
	v_mfma_f32_16x16x32_bf16 v[36:39], v[140:143], v[172:175], v[36:39]
	v_mfma_f32_16x16x32_bf16 v[56:59], v[148:151], v[172:175], v[56:59]
	v_mfma_f32_16x16x32_bf16 v[32:35], v[140:143], v[186:189], v[32:35]
	v_mfma_f32_16x16x32_bf16 v[44:47], v[148:151], v[186:189], v[44:47]
	v_mfma_f32_16x16x32_bf16 v[68:71], v[144:147], v[160:163], v[68:71]
	v_mfma_f32_16x16x32_bf16 v[88:91], v[152:155], v[160:163], v[88:91]
	v_mfma_f32_16x16x32_bf16 v[48:51], v[144:147], v[168:171], v[48:51]
	v_mfma_f32_16x16x32_bf16 v[72:75], v[152:155], v[168:171], v[72:75]
	v_mfma_f32_16x16x32_bf16 v[36:39], v[144:147], v[182:185], v[36:39]
	v_mfma_f32_16x16x32_bf16 v[56:59], v[152:155], v[182:185], v[56:59]
	v_mfma_f32_16x16x32_bf16 v[32:35], v[144:147], v[214:217], v[32:35]
	v_mfma_f32_16x16x32_bf16 v[44:47], v[152:155], v[214:217], v[44:47]
	s_barrier
	s_add_u32 s12, s12, 0x40080
	s_addc_u32 s13, s13, 0
	s_add_i32 s16, s16, s58
	v_lshl_add_u64 v[140:141], s[12:13], 0, v[176:177]
	s_mov_b32 m0, s16
	s_nop 0
	global_load_lds_dwordx4 v[140:141], off
	v_lshl_add_u64 v[140:141], s[12:13], 0, v[128:129]
	s_add_i32 m0, s16, 0x2000
	s_nop 0
	global_load_lds_dwordx4 v[140:141], off
	v_add_u32_e32 v139, 0x10000, v137
	ds_read_b128 v[140:143], v139
	ds_read_b128 v[144:147], v139 offset:1024
	ds_read_b128 v[148:151], v139 offset:2048
	ds_read_b128 v[152:155], v139 offset:3072
	s_waitcnt vmcnt(6)
	s_barrier
	v_mfma_f32_16x16x32_bf16 v[120:123], v[218:221], v[156:159], v[120:123]
	v_mfma_f32_16x16x32_bf16 v[124:127], v[226:229], v[156:159], v[124:127]
	v_mfma_f32_16x16x32_bf16 v[112:115], v[218:221], v[164:167], v[112:115]
	v_mfma_f32_16x16x32_bf16 v[116:119], v[226:229], v[164:167], v[116:119]
	v_mfma_f32_16x16x32_bf16 v[104:107], v[218:221], v[172:175], v[104:107]
	v_mfma_f32_16x16x32_bf16 v[108:111], v[226:229], v[172:175], v[108:111]
	v_mfma_f32_16x16x32_bf16 v[96:99], v[218:221], v[186:189], v[96:99]
	v_mfma_f32_16x16x32_bf16 v[100:103], v[226:229], v[186:189], v[100:103]
	v_mfma_f32_16x16x32_bf16 v[120:123], v[222:225], v[160:163], v[120:123]
	v_mfma_f32_16x16x32_bf16 v[124:127], v[230:233], v[160:163], v[124:127]
	v_mfma_f32_16x16x32_bf16 v[112:115], v[222:225], v[168:171], v[112:115]
	v_mfma_f32_16x16x32_bf16 v[116:119], v[230:233], v[168:171], v[116:119]
	v_mfma_f32_16x16x32_bf16 v[104:107], v[222:225], v[182:185], v[104:107]
	v_mfma_f32_16x16x32_bf16 v[108:111], v[230:233], v[182:185], v[108:111]
	v_mfma_f32_16x16x32_bf16 v[96:99], v[222:225], v[214:217], v[96:99]
	v_mfma_f32_16x16x32_bf16 v[100:103], v[230:233], v[214:217], v[100:103]
	s_add_i32 s55, s55, 2
	s_add_u32 s31, s31, 0x100
	s_addc_u32 s53, s53, 0
	s_cmp_gt_u32 s55, 13
	s_mov_b64 s[16:17], s[2:3]
	s_barrier
	s_cbranch_scc0 .LBB0_373
	s_lshl_b32 s2, s30, 8
	v_lshl_add_u32 v250, s8, 8, v136
	s_ashr_i32 s3, s2, 31
	v_ashrrev_i32_e32 v251, 31, v250
	v_lshl_add_u64 v[252:253], s[2:3], 1, v[130:131]
	v_lshlrev_b64 v[254:255], 11, v[250:251]
	v_lshl_add_u64 v[254:255], v[252:253], 0, v[254:255]
	v_cvt_pk_bf16_f32 v20, v20, v21
	v_cvt_pk_bf16_f32 v21, v22, v23
	v_cvt_pk_bf16_f32 v22, v28, v29
	v_cvt_pk_bf16_f32 v23, v30, v31
	global_store_dwordx4 v[254:255], v[20:23], off
	v_cvt_pk_bf16_f32 v12, v12, v13
	v_cvt_pk_bf16_f32 v13, v14, v15
	v_cvt_pk_bf16_f32 v20, v80, v81
	v_cvt_pk_bf16_f32 v21, v82, v83
	v_cvt_pk_bf16_f32 v22, v92, v93
	v_cvt_pk_bf16_f32 v23, v94, v95
	global_store_dwordx4 v[254:255], v[20:23], off offset:256
	v_cvt_pk_bf16_f32 v14, v24, v25
	v_cvt_pk_bf16_f32 v15, v26, v27
	v_or_b32_e32 v20, 16, v250
	v_ashrrev_i32_e32 v21, 31, v20
	v_lshlrev_b64 v[20:21], 11, v[20:21]
	v_lshl_add_u64 v[20:21], v[252:253], 0, v[20:21]
	global_store_dwordx4 v[20:21], v[12:15], off
	v_cvt_pk_bf16_f32 v4, v4, v5
	v_cvt_pk_bf16_f32 v5, v6, v7
	v_cvt_pk_bf16_f32 v12, v64, v65
	v_cvt_pk_bf16_f32 v13, v66, v67
	v_cvt_pk_bf16_f32 v14, v84, v85
	v_cvt_pk_bf16_f32 v15, v86, v87
	global_store_dwordx4 v[20:21], v[12:15], off offset:256
	v_cvt_pk_bf16_f32 v6, v16, v17
	v_cvt_pk_bf16_f32 v7, v18, v19
	v_or_b32_e32 v12, 32, v250
	v_ashrrev_i32_e32 v13, 31, v12
	v_lshlrev_b64 v[12:13], 11, v[12:13]
	v_lshl_add_u64 v[12:13], v[252:253], 0, v[12:13]
	global_store_dwordx4 v[12:13], v[4:7], off
	v_cvt_pk_bf16_f32 v0, v0, v1
	v_cvt_pk_bf16_f32 v1, v2, v3
	v_cvt_pk_bf16_f32 v4, v52, v53
	v_cvt_pk_bf16_f32 v5, v54, v55
	v_cvt_pk_bf16_f32 v6, v76, v77
	v_cvt_pk_bf16_f32 v7, v78, v79
	global_store_dwordx4 v[12:13], v[4:7], off offset:256
	v_cvt_pk_bf16_f32 v2, v8, v9
	v_cvt_pk_bf16_f32 v3, v10, v11
	v_or_b32_e32 v4, 48, v250
	v_ashrrev_i32_e32 v5, 31, v4
	v_lshlrev_b64 v[4:5], 11, v[4:5]
	v_lshl_add_u64 v[4:5], v[252:253], 0, v[4:5]
	global_store_dwordx4 v[4:5], v[0:3], off
	s_mov_b64 s[2:3], 0x40000
	s_movk_i32 s53, 0x440
	v_cvt_pk_bf16_f32 v0, v40, v41
	v_cvt_pk_bf16_f32 v1, v42, v43
	v_cvt_pk_bf16_f32 v2, v60, v61
	v_cvt_pk_bf16_f32 v3, v62, v63
	global_store_dwordx4 v[4:5], v[0:3], off offset:256
	v_lshl_add_u64 v[4:5], v[254:255], 0, s[2:3]
	s_mov_b32 s2, 0x40000
	v_add_co_u32_e32 v6, vcc, s2, v254
; __device__ __forceinline__ u32x4 mk4(unsigned a, unsigned b, unsigned c, unsigned d) { return (u32x4){a, b, c, d}; }
; __device__ __forceinline__ f32x4 zero4() { float z = 0.f; asm volatile("" : "+v"(z)); return (f32x4){z, z, z, z}; }
; __device__ __forceinline__ void gemm_phase(const Params& p, int l, const bf16_t* __restrict__ A, const bf16_t* __restrict__ Bt, int M, int N, int K,
;                            int epi, bf16_t* __restrict__ outp, char* smem, int wvi) {
;     ...
;           bf16_t* rp = outp + (size_t)(r0 + ai * GHALF + m * 16) * N + bcol + wc * 32 + fq * 8;
; #pragma unroll
;           for (int bj = 0; bj < 2; ++bj) {
;             const f32x4 v0 = acc[ai][bj][m][0], v1 = acc[ai][bj][m][1];
;             *reinterpret_cast<u32x4*>(rp + bj * GHALF) = mk4(pk2(v0[0], v0[1]), pk2(v0[2], v0[3]), pk2(v1[0], v1[1]), pk2(v1[2], v1[3]));
;           }
;         }
;     ...
;       if (!has_next) break;
; #pragma unroll
;       for (int a = 0; a < 2; ++a)
; #pragma unroll
;         for (int b = 0; b < 2; ++b)
; #pragma unroll
;           for (int m = 0; m < 4; ++m)
; #pragma unroll
;             for (int n = 0; n < 2; ++n) acc[a][b][m][n] = zero4();
;       Lw = Ln; pm = npm; pn = npn; cA = nA; cB = nB;
	v_cvt_pk_bf16_f32 v0, v68, v69
	v_cvt_pk_bf16_f32 v1, v70, v71
	v_cvt_pk_bf16_f32 v2, v88, v89
	v_cvt_pk_bf16_f32 v3, v90, v91
	v_addc_co_u32_e32 v7, vcc, 0, v255, vcc
	global_store_dwordx4 v[6:7], v[0:3], off
	s_mov_b64 s[2:3], 0x48000
	v_readlane_b32 s55, v244, 31
	v_cvt_pk_bf16_f32 v0, v120, v121
	v_cvt_pk_bf16_f32 v1, v122, v123
	v_cvt_pk_bf16_f32 v2, v124, v125
	v_cvt_pk_bf16_f32 v3, v126, v127
	global_store_dwordx4 v[4:5], v[0:3], off offset:256
	v_lshl_add_u64 v[4:5], v[254:255], 0, s[2:3]
	s_mov_b32 s2, 0x48000
	v_add_co_u32_e32 v6, vcc, s2, v254
	v_cvt_pk_bf16_f32 v0, v48, v49
	v_cvt_pk_bf16_f32 v1, v50, v51
	v_cvt_pk_bf16_f32 v2, v72, v73
	v_cvt_pk_bf16_f32 v3, v74, v75
	v_addc_co_u32_e32 v7, vcc, 0, v255, vcc
	global_store_dwordx4 v[6:7], v[0:3], off
	s_mov_b64 s[2:3], 0x50000
	s_nop 0
	v_cvt_pk_bf16_f32 v0, v112, v113
	v_cvt_pk_bf16_f32 v1, v114, v115
	v_cvt_pk_bf16_f32 v2, v116, v117
	v_cvt_pk_bf16_f32 v3, v118, v119
	global_store_dwordx4 v[4:5], v[0:3], off offset:256
	v_lshl_add_u64 v[4:5], v[254:255], 0, s[2:3]
	s_mov_b32 s2, 0x50000
	v_add_co_u32_e32 v6, vcc, s2, v254
	v_cvt_pk_bf16_f32 v0, v36, v37
	v_cvt_pk_bf16_f32 v1, v38, v39
	v_cvt_pk_bf16_f32 v2, v56, v57
	v_cvt_pk_bf16_f32 v3, v58, v59
	v_addc_co_u32_e32 v7, vcc, 0, v255, vcc
	global_store_dwordx4 v[6:7], v[0:3], off
	s_mov_b64 s[2:3], 0x58000
	s_nop 0
	v_cvt_pk_bf16_f32 v0, v104, v105
	v_cvt_pk_bf16_f32 v1, v106, v107
	v_cvt_pk_bf16_f32 v2, v108, v109
	v_cvt_pk_bf16_f32 v3, v110, v111
	global_store_dwordx4 v[4:5], v[0:3], off offset:256
	v_lshl_add_u64 v[4:5], v[254:255], 0, s[2:3]
	s_mov_b32 s2, 0x58000
	v_add_co_u32_e32 v6, vcc, s2, v254
	v_cvt_pk_bf16_f32 v0, v32, v33
	v_cvt_pk_bf16_f32 v1, v34, v35
	v_cvt_pk_bf16_f32 v2, v44, v45
	v_cvt_pk_bf16_f32 v3, v46, v47
	v_addc_co_u32_e32 v7, vcc, 0, v255, vcc
	global_store_dwordx4 v[6:7], v[0:3], off
	s_mov_b64 s[2:3], -1
	s_and_b64 vcc, exec, s[14:15]
	v_cvt_pk_bf16_f32 v0, v96, v97
	v_cvt_pk_bf16_f32 v1, v98, v99
	v_cvt_pk_bf16_f32 v2, v100, v101
	v_cvt_pk_bf16_f32 v3, v102, v103
	global_store_dwordx4 v[4:5], v[0:3], off offset:256
	s_cbranch_vccz .LBB0_369
	v_mov_b32_e32 v20, v177
	v_mov_b32_e32 v28, v177
	v_mov_b32_e32 v12, v177
	v_mov_b32_e32 v24, v177
	v_mov_b32_e32 v4, v177
	v_mov_b32_e32 v16, v177
	v_mov_b32_e32 v0, v177
	v_mov_b32_e32 v8, v177
	v_mov_b32_e32 v80, v177
	v_mov_b32_e32 v92, v177
	v_mov_b32_e32 v64, v177
	v_mov_b32_e32 v84, v177
	v_mov_b32_e32 v52, v177
	v_mov_b32_e32 v76, v177
	v_mov_b32_e32 v40, v177
	v_mov_b32_e32 v60, v177
	v_mov_b32_e32 v68, v177
	v_mov_b32_e32 v88, v177
	v_mov_b32_e32 v48, v177
	v_mov_b32_e32 v72, v177
	v_mov_b32_e32 v36, v177
	v_mov_b32_e32 v56, v177
	v_mov_b32_e32 v32, v177
	v_mov_b32_e32 v44, v177
	v_mov_b32_e32 v120, v177
	v_mov_b32_e32 v124, v177
	v_mov_b32_e32 v112, v177
	v_mov_b32_e32 v116, v177
	v_mov_b32_e32 v104, v177
	v_mov_b32_e32 v108, v177
	v_mov_b32_e32 v96, v177
	v_mov_b32_e32 v100, v177
	s_nop 0
	v_mov_b32_e32 v21, v20
	v_mov_b32_e32 v22, v20
	v_mov_b32_e32 v23, v20
	v_mov_b32_e32 v29, v28
	v_mov_b32_e32 v30, v28
	v_mov_b32_e32 v31, v28
	v_mov_b32_e32 v13, v12
	v_mov_b32_e32 v14, v12
	v_mov_b32_e32 v15, v12
	v_mov_b32_e32 v25, v24
	v_mov_b32_e32 v26, v24
	v_mov_b32_e32 v27, v24
	v_mov_b32_e32 v5, v4
	v_mov_b32_e32 v6, v4
	v_mov_b32_e32 v7, v4
	v_mov_b32_e32 v17, v16
	v_mov_b32_e32 v18, v16
	v_mov_b32_e32 v19, v16
	s_nop 0
	v_mov_b32_e32 v1, v0
	v_mov_b32_e32 v2, v0
	v_mov_b32_e32 v3, v0
	v_mov_b32_e32 v9, v8
	v_mov_b32_e32 v10, v8
	v_mov_b32_e32 v11, v8
	v_mov_b32_e32 v81, v80
	v_mov_b32_e32 v82, v80
	v_mov_b32_e32 v83, v80
	v_mov_b32_e32 v93, v92
	v_mov_b32_e32 v94, v92
	v_mov_b32_e32 v95, v92
	v_mov_b32_e32 v65, v64
	v_mov_b32_e32 v66, v64
	v_mov_b32_e32 v67, v64
	v_mov_b32_e32 v85, v84
	v_mov_b32_e32 v86, v84
	v_mov_b32_e32 v87, v84
	s_nop 0
	v_mov_b32_e32 v53, v52
	v_mov_b32_e32 v54, v52
	v_mov_b32_e32 v55, v52
	v_mov_b32_e32 v77, v76
	v_mov_b32_e32 v78, v76
	v_mov_b32_e32 v79, v76
	v_mov_b32_e32 v41, v40
	v_mov_b32_e32 v42, v40
	v_mov_b32_e32 v43, v40
	v_mov_b32_e32 v61, v60
	v_mov_b32_e32 v62, v60
	v_mov_b32_e32 v63, v60
	v_mov_b32_e32 v69, v68
	v_mov_b32_e32 v70, v68
	v_mov_b32_e32 v71, v68
	v_mov_b32_e32 v89, v88
	v_mov_b32_e32 v90, v88
	v_mov_b32_e32 v91, v88
	s_nop 0
	v_mov_b32_e32 v49, v48
	v_mov_b32_e32 v50, v48
	v_mov_b32_e32 v51, v48
	v_mov_b32_e32 v73, v72
	v_mov_b32_e32 v74, v72
	v_mov_b32_e32 v75, v72
	v_mov_b32_e32 v37, v36
	v_mov_b32_e32 v38, v36
	v_mov_b32_e32 v39, v36
	v_mov_b32_e32 v57, v56
	v_mov_b32_e32 v58, v56
	v_mov_b32_e32 v59, v56
	v_mov_b32_e32 v33, v32
	v_mov_b32_e32 v34, v32
	v_mov_b32_e32 v35, v32
	v_mov_b32_e32 v45, v44
	v_mov_b32_e32 v46, v44
	v_mov_b32_e32 v47, v44
	s_nop 0
	v_mov_b32_e32 v121, v120
	v_mov_b32_e32 v122, v120
	v_mov_b32_e32 v123, v120
	v_mov_b32_e32 v125, v124
	v_mov_b32_e32 v126, v124
	v_mov_b32_e32 v127, v124
	v_mov_b32_e32 v113, v112
	v_mov_b32_e32 v114, v112
	v_mov_b32_e32 v115, v112
	v_mov_b32_e32 v117, v116
	v_mov_b32_e32 v118, v116
	v_mov_b32_e32 v119, v116
	v_mov_b32_e32 v105, v104
	v_mov_b32_e32 v106, v104
	v_mov_b32_e32 v107, v104
	v_mov_b32_e32 v109, v108
	v_mov_b32_e32 v110, v108
	v_mov_b32_e32 v111, v108
	s_mov_b64 s[2:3], 0
	v_mov_b32_e32 v97, v96
	v_mov_b32_e32 v98, v96
	v_mov_b32_e32 v99, v96
	v_mov_b32_e32 v101, v100
	v_mov_b32_e32 v102, v100
	v_mov_b32_e32 v103, v100
	s_branch .LBB0_369

; __device__ __forceinline__ f32x4 zero4() { float z = 0.f; asm volatile("" : "+v"(z)); return (f32x4){z, z, z, z}; }
; #define G_STAGE(bufoff, gbase) do { _Pragma("unroll") for (int _i = 0; _i < 2; ++_i) \
;     __builtin_amdgcn_global_load_lds((const unsigned*)((const char*)(gbase) + voff[_i]), (GLAS unsigned*)(lds + (bufoff) + ldsw + _i * 8192), 16, 0, 0); } while (0)
; #define G_WAIT_V(n) asm volatile("s_waitcnt vmcnt(" #n ")" ::: "memory")
; __device__ __forceinline__ void gemm_phase(const Params& p, int l, const bf16_t* __restrict__ A, const bf16_t* __restrict__ Bt, int M, int N, int K,
;                            int epi, bf16_t* __restrict__ outp, char* smem, int wvi) {
;     ...
;   for (int i = 0; i < 2; ++i) { int R, C; stage_rc(tidx * 16 + i * 8192, R, C); voff[i] = (unsigned)(R * K + C) * 2u; }
;   const size_t kstep = (size_t)(GBK * 2), hstep = (size_t)GHALF * K * 2, tstep = 2 * hstep;
;   const unsigned ldsw = (unsigned)wid * 1024u;
;   const int aoff = lds_byte(wr * 64 + fr, fq * 8), boff = lds_byte(wc * 32 + fr, fq * 8);
;   constexpr int HTB = GHT * 2;
;     ...
;   const int nM = M / GBM, nN = N / GBM, nwg = nM * nN;
;   auto tile_of = [&](int Lw, int& pm_, int& pn_) {
;     int wgid = Lw;
;     { const int q = nwg / GNXCD, r = nwg % GNXCD, xcd = wgid % GNXCD, off = wgid / GNXCD; wgid = (xcd < r ? xcd * (q + 1) : r * (q + 1) + (xcd - r) * q) + off; }
;     const int nig = GWGM * nN, gid = wgid / nig, fm = gid * GWGM, gsz = min(nM - fm, GWGM);
;     pm_ = fm + ((wgid % nig) % gsz); pn_ = (wgid % nig) / gsz;
;   };
;   int Lw = blockIdx.x;
;   if (Lw < nwg) {
;     int pm, pn; tile_of(Lw, pm, pn);
;     const char* cA = (const char*)A + (size_t)pm * tstep;
;     const char* cB = (const char*)Bt + (size_t)pn * tstep;
;     f32x4 acc[2][2][4][2];
; #pragma unroll
;     for (int a = 0; a < 2; ++a)
; #pragma unroll
;       for (int b = 0; b < 2; ++b)
; #pragma unroll
;         for (int m = 0; m < 4; ++m)
; #pragma unroll
;           for (int n = 0; n < 2; ++n) acc[a][b][m][n] = zero4();
;     bf16x8 At[4][2], B0[2][2], B1[2][2];
;     G_STAGE(G_SB(0, 0), cB); G_STAGE(G_SA(0, 0), cA); G_STAGE(G_SB(0, 1), cB + hstep); G_STAGE(G_SA(0, 1), cA + hstep);
;     if (wr == 1) G_BAR;
;     G_WAIT_V(4); G_BAR;
;     G_STAGE(G_SB(1, 0), cB + kstep); G_STAGE(G_SA(1, 0), cA + kstep); G_STAGE(G_SB(1, 1), cB + hstep + kstep);
;     G_WAIT_V(6); G_BAR;
.LBB0_1034:
	v_readlane_b32 s2, v247, 2
	v_readlane_b32 s3, v247, 3
	v_mov_b32_e32 v129, v177
	v_readlane_b32 s12, v248, 62
	v_lshl_add_u64 v[34:35], s[2:3], 0, v[176:177]
	v_lshl_add_u64 v[38:39], s[2:3], 0, v[128:129]
	v_readlane_b32 s13, v248, 63
	v_lshl_add_u64 v[34:35], v[34:35], 0, s[64:65]
	s_add_i32 m0, s1, 0x18000
	v_lshl_add_u64 v[46:47], s[12:13], 0, v[176:177]
	s_waitcnt vmcnt(4)
	s_barrier
	global_load_lds_dwordx4 v[34:35], off
	v_lshl_add_u64 v[34:35], v[38:39], 0, s[64:65]
	s_add_i32 m0, s1, 0x1a000
	s_add_i32 s0, s1, 0x8000
	v_lshl_add_u64 v[58:59], s[12:13], 0, v[128:129]
	global_load_lds_dwordx4 v[34:35], off
	v_lshl_add_u64 v[34:35], v[46:47], 0, s[64:65]
	s_mov_b32 m0, s0
	s_add_i32 s21, s1, 0xa000
	v_readlane_b32 s2, v247, 4
	global_load_lds_dwordx4 v[34:35], off
	v_lshl_add_u64 v[34:35], v[58:59], 0, s[64:65]
	s_mov_b32 m0, s21
	v_readlane_b32 s3, v247, 5
	global_load_lds_dwordx4 v[34:35], off
	s_nop 0
	v_lshl_add_u64 v[34:35], s[2:3], 0, v[176:177]
	s_add_i32 m0, s1, 0x1c000
	v_and_b32_e32 v131, 15, v130
	global_load_lds_dwordx4 v[34:35], off
	v_lshl_add_u64 v[34:35], s[2:3], 0, v[128:129]
	s_add_i32 m0, s1, 0x1e000
	v_readlane_b32 s2, v248, 10
	global_load_lds_dwordx4 v[34:35], off
	s_nop 0
	v_or_b32_e32 v136, s2, v131
	v_lshlrev_b32_e32 v137, 6, v136
	v_and_b32_e32 v142, 48, v130
	s_movk_i32 s2, 0x3c0
	v_lshlrev_b32_e32 v143, 2, v136
	v_and_or_b32 v137, v137, s2, v142
	v_and_b32_e32 v143, 32, v143
	v_readlane_b32 s2, v248, 11
	v_lshlrev_b32_e32 v130, 2, v130
	v_lshl_or_b32 v131, v131, 6, v142
	v_bitop3_b32 v144, v137, s2, v143 bitop3:0xde
	v_and_b32_e32 v130, 32, v130
	v_readlane_b32 s2, v248, 12
	s_movk_i32 s4, 0xb00
	v_mov_b32_e32 v143, v177
	v_bitop3_b32 v137, v131, s2, v130 bitop3:0xde
	v_readlane_b32 s2, v248, 15
	v_readlane_b32 s3, v248, 16
	v_lshrrev_b32_e32 v133, 1, v133
	v_mul_lo_u32 v132, v132, s4
	s_mov_b32 s5, 0xb000
	v_lshl_add_u64 v[130:131], s[2:3], 0, v[142:143]
	v_mad_u64_u32 v[132:133], s[2:3], v133, s5, v[132:133]
	v_or_b32_e32 v132, v132, v140
	v_lshrrev_b32_e32 v140, 1, v134
	v_mul_lo_u32 v134, v135, s4
	v_mad_u64_u32 v[134:135], s[2:3], v140, s5, v[134:135]
	s_waitcnt vmcnt(6)
	v_or_b32_e32 v134, v134, v138
	v_add_lshl_u32 v132, v132, v141, 1
	v_mov_b32_e32 v133, v177
	s_mov_b64 s[6:7], 0xb0080
	v_add_lshl_u32 v134, v134, v139, 1
	v_mov_b32_e32 v135, v177
	v_readlane_b32 s25, v248, 59
	v_readlane_b32 s26, v248, 56
	v_readlane_b32 s2, v248, 57
	v_mov_b32_e32 v21, v20
	v_mov_b32_e32 v22, v20
	v_mov_b32_e32 v23, v20
	v_mov_b32_e32 v29, v28
	v_mov_b32_e32 v30, v28
	v_mov_b32_e32 v31, v28
	v_mov_b32_e32 v13, v12
	v_mov_b32_e32 v14, v12
	v_mov_b32_e32 v15, v12
	v_mov_b32_e32 v25, v24
	v_mov_b32_e32 v26, v24
	v_mov_b32_e32 v27, v24
	v_mov_b32_e32 v5, v4
	v_mov_b32_e32 v6, v4
	v_mov_b32_e32 v7, v4
	v_mov_b32_e32 v17, v16
	v_mov_b32_e32 v18, v16
	v_mov_b32_e32 v19, v16
	v_mov_b32_e32 v1, v0
	v_mov_b32_e32 v2, v0
	v_mov_b32_e32 v3, v0
	v_mov_b32_e32 v9, v8
	v_mov_b32_e32 v10, v8
	v_mov_b32_e32 v11, v8
	v_mov_b32_e32 v81, v80
	v_mov_b32_e32 v82, v80
	v_mov_b32_e32 v83, v80
	v_mov_b32_e32 v93, v92
	v_mov_b32_e32 v94, v92
	v_mov_b32_e32 v95, v92
	v_mov_b32_e32 v65, v64
	v_mov_b32_e32 v66, v64
	v_mov_b32_e32 v67, v64
	v_mov_b32_e32 v85, v84
	v_mov_b32_e32 v86, v84
	v_mov_b32_e32 v87, v84
	v_mov_b32_e32 v53, v52
	v_mov_b32_e32 v54, v52
	v_mov_b32_e32 v55, v52
	v_mov_b32_e32 v77, v76
	v_mov_b32_e32 v78, v76
	v_mov_b32_e32 v79, v76
	v_mov_b32_e32 v41, v40
	v_mov_b32_e32 v42, v40
	v_mov_b32_e32 v43, v40
	v_mov_b32_e32 v61, v60
	v_mov_b32_e32 v62, v60
	v_mov_b32_e32 v63, v60
	v_mov_b32_e32 v69, v68
	v_mov_b32_e32 v70, v68
	v_mov_b32_e32 v71, v68
	v_mov_b32_e32 v89, v88
	v_mov_b32_e32 v90, v88
	v_mov_b32_e32 v91, v88
	v_mov_b32_e32 v49, v48
	v_mov_b32_e32 v50, v48
	v_mov_b32_e32 v51, v48
	v_mov_b32_e32 v73, v72
	v_mov_b32_e32 v74, v72
	v_mov_b32_e32 v75, v72
	v_mov_b32_e32 v37, v36
	v_mov_b32_e32 v38, v36
	v_mov_b32_e32 v39, v36
	v_mov_b32_e32 v57, v56
	v_mov_b32_e32 v58, v56
	v_mov_b32_e32 v59, v56
	v_mov_b32_e32 v33, v32
	v_mov_b32_e32 v34, v32
	v_mov_b32_e32 v35, v32
	v_mov_b32_e32 v45, v44
	v_mov_b32_e32 v46, v44
	v_mov_b32_e32 v47, v44
	v_mov_b32_e32 v121, v120
	v_mov_b32_e32 v122, v120
	v_mov_b32_e32 v123, v120
	v_mov_b32_e32 v125, v124
	v_mov_b32_e32 v126, v124
	v_mov_b32_e32 v127, v124
	v_mov_b32_e32 v113, v112
	v_mov_b32_e32 v114, v112
	v_mov_b32_e32 v115, v112
	v_mov_b32_e32 v117, v116
	v_mov_b32_e32 v118, v116
	v_mov_b32_e32 v119, v116
	v_mov_b32_e32 v105, v104
	v_mov_b32_e32 v106, v104
	v_mov_b32_e32 v107, v104
	v_mov_b32_e32 v109, v108
	v_mov_b32_e32 v110, v108
	v_mov_b32_e32 v111, v108
	v_mov_b32_e32 v97, v96
	v_mov_b32_e32 v98, v96
	v_mov_b32_e32 v99, v96
	v_mov_b32_e32 v101, v100
	v_mov_b32_e32 v102, v100
	v_mov_b32_e32 v103, v100
	v_lshl_add_u64 v[132:133], v[132:133], 0, s[6:7]
	v_lshl_add_u64 v[134:135], v[134:135], 0, s[6:7]
	v_add_u32_e32 v138, 0, v144
	v_readlane_b32 s3, v248, 58
	v_readlane_b32 s22, v248, 0
	s_mov_b32 s23, s25
	s_mov_b32 s24, s26
	s_barrier
	v_add_u32_e32 v139, 0x10000, v137
	ds_read_b128 v[140:143], v139
	ds_read_b128 v[144:147], v139 offset:1024
	ds_read_b128 v[148:151], v139 offset:2048
	ds_read_b128 v[152:155], v139 offset:3072
	s_branch .LBB0_1036

; #define G_STAGE(bufoff, gbase) do { _Pragma("unroll") for (int _i = 0; _i < 2; ++_i) \
;     __builtin_amdgcn_global_load_lds((const unsigned*)((const char*)(gbase) + voff[_i]), (GLAS unsigned*)(lds + (bufoff) + ldsw + _i * 8192), 16, 0, 0); } while (0)
; #define G_LDA(dst, b, h) do { _Pragma("unroll") for (int m = 0; m < 4; ++m) _Pragma("unroll") for (int k = 0; k < 2; ++k) \
;     dst[m][k] = *(const GLAS bf16x8*)(lds + G_SA(b, h) + aoff + m * 2048 + k * 1024); } while (0)
; #define G_LDB(dst, b, h) do { _Pragma("unroll") for (int n = 0; n < 2; ++n) _Pragma("unroll") for (int k = 0; k < 2; ++k) \
;     dst[n][k] = *(const GLAS bf16x8*)(lds + G_SB(b, h) + boff + n * 2048 + k * 1024); } while (0)
; #define G_MMA(ai, bj, At_, Bt_) do { __builtin_amdgcn_s_setprio(1); \
;     _Pragma("unroll") for (int m = 0; m < 4; ++m) _Pragma("unroll") for (int n = 0; n < 2; ++n) _Pragma("unroll") for (int k = 0; k < 2; ++k) \
;       acc[ai][bj][m][n] = __builtin_amdgcn_mfma_f32_16x16x32_bf16(Bt_[n][k], At_[m][k], acc[ai][bj][m][n], 0, 0, 0); \
;     __builtin_amdgcn_s_setprio(0); } while (0)
; #define G_WAIT_V(n) asm volatile("s_waitcnt vmcnt(" #n ")" ::: "memory")
; #define G_WAIT_L(n) asm volatile("s_waitcnt lgkmcnt(" #n ")" ::: "memory")
; #define G_BAR __builtin_amdgcn_s_barrier()
; __device__ __forceinline__ void gemm_phase(const Params& p, int l, const bf16_t* __restrict__ A, const bf16_t* __restrict__ Bt, int M, int N, int K,
;                            int epi, bf16_t* __restrict__ outp, char* smem, int wvi) {
;     ...
;       for (int t = 0; t < nt; t += 2) {
;         const bool lastt = (t == nt - 2);
;         const char* a1 = cA + (size_t)(t + 1) * kstep;
;         const char* a2 = lastt ? nA : cA + (size_t)(t + 2) * kstep; const char* b2 = lastt ? nB : cB + (size_t)(t + 2) * kstep;
;         const char* a3 = a2 + kstep; const char* b3 = b2 + kstep;
;         G_LDB(B0, 0, 0); G_SCHED; G_LDA(At, 0, 0); G_STAGE(G_SA(1, 1), a1 + hstep);
;         G_WAIT_L(8); G_BAR; G_WAIT_L(0); G_MMA(0, 0, At, B0); G_BAR; G_SCHED;
;         G_LDB(B1, 0, 1); G_STAGE(G_SB(0, 0), b2);
;         G_BAR; G_WAIT_L(0); G_MMA(0, 1, At, B1); G_BAR;
;         G_LDA(At, 0, 1); G_STAGE(G_SA(0, 0), a2);
;         G_BAR; G_WAIT_L(0); G_MMA(1, 0, At, B0); G_BAR; G_SCHED;
;         G_STAGE(G_SB(0, 1), b2 + hstep);
;         G_WAIT_V(6); G_BAR; G_MMA(1, 1, At, B1); G_BAR;
.LBB0_1039:
	s_add_u32 s2, s12, 0x100
	s_addc_u32 s3, s13, 0
	s_add_i32 s53, 0, 0x10000
	s_cmp_eq_u32 s31, 40
	s_cselect_b32 s15, s5, s3
	s_cselect_b32 s14, s4, s2
	s_cselect_b32 s11, s28, s30
	s_cselect_b32 s10, s27, s29
	v_lshl_add_u64 v[190:191], s[12:13], 0, v[132:133]
	s_add_i32 m0, s1, 0xc000
	ds_read_b128 v[156:159], v138
	ds_read_b128 v[160:163], v138 offset:1024
	ds_read_b128 v[164:167], v138 offset:2048
	ds_read_b128 v[168:171], v138 offset:3072
	ds_read_b128 v[172:175], v138 offset:4096
	ds_read_b128 v[182:185], v138 offset:5120
	ds_read_b128 v[186:189], v138 offset:6144
	ds_read_b128 v[214:217], v138 offset:7168
	global_load_lds_dwordx4 v[190:191], off
	v_lshl_add_u64 v[190:191], s[12:13], 0, v[134:135]
	s_add_i32 m0, s1, 0xe000
	s_nop 0
	global_load_lds_dwordx4 v[190:191], off
	s_waitcnt lgkmcnt(8)
	s_barrier
	s_waitcnt lgkmcnt(0)
	s_waitcnt lgkmcnt(0)
	v_mfma_f32_16x16x32_bf16 v[20:23], v[140:143], v[156:159], v[20:23]
	v_mfma_f32_16x16x32_bf16 v[28:31], v[148:151], v[156:159], v[28:31]
	v_mfma_f32_16x16x32_bf16 v[12:15], v[140:143], v[164:167], v[12:15]
	v_mfma_f32_16x16x32_bf16 v[24:27], v[148:151], v[164:167], v[24:27]
	v_mfma_f32_16x16x32_bf16 v[4:7], v[140:143], v[172:175], v[4:7]
	v_mfma_f32_16x16x32_bf16 v[16:19], v[148:151], v[172:175], v[16:19]
	v_mfma_f32_16x16x32_bf16 v[0:3], v[140:143], v[186:189], v[0:3]
	v_mfma_f32_16x16x32_bf16 v[8:11], v[148:151], v[186:189], v[8:11]
	v_mfma_f32_16x16x32_bf16 v[20:23], v[144:147], v[160:163], v[20:23]
	v_mfma_f32_16x16x32_bf16 v[28:31], v[152:155], v[160:163], v[28:31]
	v_mfma_f32_16x16x32_bf16 v[12:15], v[144:147], v[168:171], v[12:15]
	v_mfma_f32_16x16x32_bf16 v[24:27], v[152:155], v[168:171], v[24:27]
	v_mfma_f32_16x16x32_bf16 v[4:7], v[144:147], v[182:185], v[4:7]
	v_mfma_f32_16x16x32_bf16 v[16:19], v[152:155], v[182:185], v[16:19]
	v_mfma_f32_16x16x32_bf16 v[0:3], v[144:147], v[214:217], v[0:3]
	v_mfma_f32_16x16x32_bf16 v[8:11], v[152:155], v[214:217], v[8:11]
	s_barrier
	s_add_i32 s55, 0, 0x14000
	s_add_i32 s12, s53, s58
	v_add_u32_e32 v139, s55, v137
	v_lshl_add_u64 v[190:191], s[10:11], 0, v[176:177]
	s_mov_b32 m0, s12
	ds_read_b128 v[218:221], v139
	ds_read_b128 v[222:225], v139 offset:1024
	ds_read_b128 v[226:229], v139 offset:2048
	ds_read_b128 v[230:233], v139 offset:3072
	global_load_lds_dwordx4 v[190:191], off
	v_lshl_add_u64 v[234:235], s[10:11], 0, v[128:129]
	s_add_i32 m0, s12, 0x2000
	s_nop 0
	global_load_lds_dwordx4 v[234:235], off
	s_barrier
	s_waitcnt lgkmcnt(0)
	s_waitcnt lgkmcnt(0)
	v_mfma_f32_16x16x32_bf16 v[80:83], v[218:221], v[156:159], v[80:83]
	v_mfma_f32_16x16x32_bf16 v[92:95], v[226:229], v[156:159], v[92:95]
	v_mfma_f32_16x16x32_bf16 v[64:67], v[218:221], v[164:167], v[64:67]
	v_mfma_f32_16x16x32_bf16 v[84:87], v[226:229], v[164:167], v[84:87]
	v_mfma_f32_16x16x32_bf16 v[52:55], v[218:221], v[172:175], v[52:55]
	v_mfma_f32_16x16x32_bf16 v[76:79], v[226:229], v[172:175], v[76:79]
	v_mfma_f32_16x16x32_bf16 v[40:43], v[218:221], v[186:189], v[40:43]
	v_mfma_f32_16x16x32_bf16 v[60:63], v[226:229], v[186:189], v[60:63]
	v_mfma_f32_16x16x32_bf16 v[80:83], v[222:225], v[160:163], v[80:83]
	v_mfma_f32_16x16x32_bf16 v[92:95], v[230:233], v[160:163], v[92:95]
	v_mfma_f32_16x16x32_bf16 v[64:67], v[222:225], v[168:171], v[64:67]
	v_mfma_f32_16x16x32_bf16 v[84:87], v[230:233], v[168:171], v[84:87]
	v_mfma_f32_16x16x32_bf16 v[52:55], v[222:225], v[182:185], v[52:55]
	v_mfma_f32_16x16x32_bf16 v[76:79], v[230:233], v[182:185], v[76:79]
	v_mfma_f32_16x16x32_bf16 v[40:43], v[222:225], v[214:217], v[40:43]
	v_mfma_f32_16x16x32_bf16 v[60:63], v[230:233], v[214:217], v[60:63]
	s_mov_b32 m0, s1
	v_lshl_add_u64 v[236:237], s[14:15], 0, v[176:177]
	s_barrier
	ds_read_b128 v[156:159], v138 offset:16384
	ds_read_b128 v[160:163], v138 offset:17408
	ds_read_b128 v[164:167], v138 offset:18432
	ds_read_b128 v[168:171], v138 offset:19456
	ds_read_b128 v[172:175], v138 offset:20480
	ds_read_b128 v[182:185], v138 offset:21504
	ds_read_b128 v[186:189], v138 offset:22528
	ds_read_b128 v[214:217], v138 offset:23552
	global_load_lds_dwordx4 v[236:237], off
	v_lshl_add_u64 v[238:239], s[14:15], 0, v[128:129]
	s_mov_b32 m0, s16
	s_nop 0
	global_load_lds_dwordx4 v[238:239], off
	s_barrier
	s_waitcnt lgkmcnt(0)
	s_waitcnt lgkmcnt(0)
	v_mfma_f32_16x16x32_bf16 v[68:71], v[140:143], v[156:159], v[68:71]
	v_mfma_f32_16x16x32_bf16 v[88:91], v[148:151], v[156:159], v[88:91]
	v_mfma_f32_16x16x32_bf16 v[48:51], v[140:143], v[164:167], v[48:51]
	v_mfma_f32_16x16x32_bf16 v[72:75], v[148:151], v[164:167], v[72:75]
	v_mfma_f32_16x16x32_bf16 v[36:39], v[140:143], v[172:175], v[36:39]
	v_mfma_f32_16x16x32_bf16 v[56:59], v[148:151], v[172:175], v[56:59]
	v_mfma_f32_16x16x32_bf16 v[32:35], v[140:143], v[186:189], v[32:35]
	v_mfma_f32_16x16x32_bf16 v[44:47], v[148:151], v[186:189], v[44:47]
	v_mfma_f32_16x16x32_bf16 v[68:71], v[144:147], v[160:163], v[68:71]
	v_mfma_f32_16x16x32_bf16 v[88:91], v[152:155], v[160:163], v[88:91]
	v_mfma_f32_16x16x32_bf16 v[48:51], v[144:147], v[168:171], v[48:51]
	v_mfma_f32_16x16x32_bf16 v[72:75], v[152:155], v[168:171], v[72:75]
	v_mfma_f32_16x16x32_bf16 v[36:39], v[144:147], v[182:185], v[36:39]
	v_mfma_f32_16x16x32_bf16 v[56:59], v[152:155], v[182:185], v[56:59]
	v_mfma_f32_16x16x32_bf16 v[32:35], v[144:147], v[214:217], v[32:35]
	v_mfma_f32_16x16x32_bf16 v[44:47], v[152:155], v[214:217], v[44:47]
	s_barrier
	s_add_u32 s12, s10, 0xb0000
	s_addc_u32 s13, s11, 0
	s_add_i32 s53, s55, s58
	v_lshl_add_u64 v[140:141], s[12:13], 0, v[176:177]
	s_mov_b32 m0, s53
	s_nop 0
	global_load_lds_dwordx4 v[140:141], off
	v_lshl_add_u64 v[140:141], s[12:13], 0, v[128:129]
	s_add_i32 m0, s53, 0x2000
	s_nop 0
	global_load_lds_dwordx4 v[140:141], off
	s_waitcnt vmcnt(6)
	s_barrier
; #define G_STAGE(bufoff, gbase) do { _Pragma("unroll") for (int _i = 0; _i < 2; ++_i) \
;     __builtin_amdgcn_global_load_lds((const unsigned*)((const char*)(gbase) + voff[_i]), (GLAS unsigned*)(lds + (bufoff) + ldsw + _i * 8192), 16, 0, 0); } while (0)
; #define G_LDA(dst, b, h) do { _Pragma("unroll") for (int m = 0; m < 4; ++m) _Pragma("unroll") for (int k = 0; k < 2; ++k) \
;     dst[m][k] = *(const GLAS bf16x8*)(lds + G_SA(b, h) + aoff + m * 2048 + k * 1024); } while (0)
; #define G_LDB(dst, b, h) do { _Pragma("unroll") for (int n = 0; n < 2; ++n) _Pragma("unroll") for (int k = 0; k < 2; ++k) \
;     dst[n][k] = *(const GLAS bf16x8*)(lds + G_SB(b, h) + boff + n * 2048 + k * 1024); } while (0)
; #define G_MMA(ai, bj, At_, Bt_) do { __builtin_amdgcn_s_setprio(1); \
;     _Pragma("unroll") for (int m = 0; m < 4; ++m) _Pragma("unroll") for (int n = 0; n < 2; ++n) _Pragma("unroll") for (int k = 0; k < 2; ++k) \
;       acc[ai][bj][m][n] = __builtin_amdgcn_mfma_f32_16x16x32_bf16(Bt_[n][k], At_[m][k], acc[ai][bj][m][n], 0, 0, 0); \
;     __builtin_amdgcn_s_setprio(0); } while (0)
; #define G_WAIT_V(n) asm volatile("s_waitcnt vmcnt(" #n ")" ::: "memory")
; #define G_WAIT_L(n) asm volatile("s_waitcnt lgkmcnt(" #n ")" ::: "memory")
; #define G_BAR __builtin_amdgcn_s_barrier()
; #define G_SCHED __builtin_amdgcn_sched_barrier(0)
; __device__ __forceinline__ void gemm_phase(const Params& p, int l, const bf16_t* __restrict__ A, const bf16_t* __restrict__ Bt, int M, int N, int K,
;                            int epi, bf16_t* __restrict__ outp, char* smem, int wvi) {
;     ...
;         G_WAIT_V(6); G_BAR; G_MMA(1, 1, At, B1); G_BAR;
;         G_LDB(B0, 1, 0); G_SCHED; G_LDA(At, 1, 0); G_STAGE(G_SA(0, 1), a2 + hstep);
;         G_WAIT_L(8); G_BAR; G_WAIT_L(0); G_MMA(0, 0, At, B0); G_BAR; G_SCHED;
;         G_LDB(B1, 1, 1); G_STAGE(G_SB(1, 0), b3);
;         G_BAR; G_WAIT_L(0); G_MMA(0, 1, At, B1); G_BAR;
;         G_LDA(At, 1, 1); G_STAGE(G_SA(1, 0), a3);
;         G_BAR; G_WAIT_L(0); G_MMA(1, 0, At, B0); G_BAR; G_SCHED;
	v_mfma_f32_16x16x32_bf16 v[120:123], v[218:221], v[156:159], v[120:123]
	v_mfma_f32_16x16x32_bf16 v[124:127], v[226:229], v[156:159], v[124:127]
	v_mfma_f32_16x16x32_bf16 v[112:115], v[218:221], v[164:167], v[112:115]
	v_mfma_f32_16x16x32_bf16 v[116:119], v[226:229], v[164:167], v[116:119]
	v_mfma_f32_16x16x32_bf16 v[104:107], v[218:221], v[172:175], v[104:107]
	v_mfma_f32_16x16x32_bf16 v[108:111], v[226:229], v[172:175], v[108:111]
	v_mfma_f32_16x16x32_bf16 v[96:99], v[218:221], v[186:189], v[96:99]
	v_mfma_f32_16x16x32_bf16 v[100:103], v[226:229], v[186:189], v[100:103]
	v_mfma_f32_16x16x32_bf16 v[120:123], v[222:225], v[160:163], v[120:123]
	v_mfma_f32_16x16x32_bf16 v[124:127], v[230:233], v[160:163], v[124:127]
	v_mfma_f32_16x16x32_bf16 v[112:115], v[222:225], v[168:171], v[112:115]
	v_mfma_f32_16x16x32_bf16 v[116:119], v[230:233], v[168:171], v[116:119]
	v_mfma_f32_16x16x32_bf16 v[104:107], v[222:225], v[182:185], v[104:107]
	v_mfma_f32_16x16x32_bf16 v[108:111], v[230:233], v[182:185], v[108:111]
	v_mfma_f32_16x16x32_bf16 v[96:99], v[222:225], v[214:217], v[96:99]
	v_mfma_f32_16x16x32_bf16 v[100:103], v[230:233], v[214:217], v[100:103]
	s_add_i32 s53, 0, 0x18000
	v_add_u32_e32 v139, s53, v137
	s_barrier
	ds_read_b128 v[140:143], v139
	ds_read_b128 v[144:147], v139 offset:1024
	ds_read_b128 v[148:151], v139 offset:2048
	ds_read_b128 v[152:155], v139 offset:3072
	s_add_u32 s12, s14, 0xb0000
	s_addc_u32 s13, s15, 0
	s_mov_b32 m0, s17
	v_lshl_add_u64 v[218:219], s[12:13], 0, v[176:177]
	ds_read_b128 v[156:159], v138 offset:32768
	ds_read_b128 v[160:163], v138 offset:33792
	ds_read_b128 v[164:167], v138 offset:34816
	ds_read_b128 v[168:171], v138 offset:35840
	ds_read_b128 v[172:175], v138 offset:36864
	ds_read_b128 v[182:185], v138 offset:37888
	ds_read_b128 v[186:189], v138 offset:38912
	ds_read_b128 v[214:217], v138 offset:39936
	global_load_lds_dwordx4 v[218:219], off
	v_lshl_add_u64 v[218:219], s[12:13], 0, v[128:129]
	s_mov_b32 m0, s20
	s_nop 0
	global_load_lds_dwordx4 v[218:219], off
	s_waitcnt lgkmcnt(8)
	s_barrier
	s_waitcnt lgkmcnt(0)
	s_waitcnt lgkmcnt(0)
	v_mfma_f32_16x16x32_bf16 v[20:23], v[140:143], v[156:159], v[20:23]
	v_mfma_f32_16x16x32_bf16 v[28:31], v[148:151], v[156:159], v[28:31]
	v_mfma_f32_16x16x32_bf16 v[12:15], v[140:143], v[164:167], v[12:15]
	v_mfma_f32_16x16x32_bf16 v[24:27], v[148:151], v[164:167], v[24:27]
	v_mfma_f32_16x16x32_bf16 v[4:7], v[140:143], v[172:175], v[4:7]
	v_mfma_f32_16x16x32_bf16 v[16:19], v[148:151], v[172:175], v[16:19]
	v_mfma_f32_16x16x32_bf16 v[0:3], v[140:143], v[186:189], v[0:3]
	v_mfma_f32_16x16x32_bf16 v[8:11], v[148:151], v[186:189], v[8:11]
	v_mfma_f32_16x16x32_bf16 v[20:23], v[144:147], v[160:163], v[20:23]
	v_mfma_f32_16x16x32_bf16 v[28:31], v[152:155], v[160:163], v[28:31]
	v_mfma_f32_16x16x32_bf16 v[12:15], v[144:147], v[168:171], v[12:15]
	v_mfma_f32_16x16x32_bf16 v[24:27], v[152:155], v[168:171], v[24:27]
	v_mfma_f32_16x16x32_bf16 v[4:7], v[144:147], v[182:185], v[4:7]
	v_mfma_f32_16x16x32_bf16 v[16:19], v[152:155], v[182:185], v[16:19]
	v_mfma_f32_16x16x32_bf16 v[0:3], v[144:147], v[214:217], v[0:3]
	v_mfma_f32_16x16x32_bf16 v[8:11], v[152:155], v[214:217], v[8:11]
	s_barrier
	s_add_i32 s12, 0, 0x1c000
	s_add_i32 s13, s53, s58
	v_add_u32_e32 v139, s12, v137
	v_lshl_add_u64 v[190:191], v[190:191], 0, s[64:65]
	s_mov_b32 m0, s13
	ds_read_b128 v[218:221], v139
	ds_read_b128 v[222:225], v139 offset:1024
	ds_read_b128 v[226:229], v139 offset:2048
	ds_read_b128 v[230:233], v139 offset:3072
	global_load_lds_dwordx4 v[190:191], off
	v_lshl_add_u64 v[190:191], v[234:235], 0, s[64:65]
	s_add_i32 m0, s13, 0x2000
	s_nop 0
	global_load_lds_dwordx4 v[190:191], off
	s_barrier
	s_waitcnt lgkmcnt(0)
	s_waitcnt lgkmcnt(0)
	v_mfma_f32_16x16x32_bf16 v[80:83], v[218:221], v[156:159], v[80:83]
	v_mfma_f32_16x16x32_bf16 v[92:95], v[226:229], v[156:159], v[92:95]
	v_mfma_f32_16x16x32_bf16 v[64:67], v[218:221], v[164:167], v[64:67]
	v_mfma_f32_16x16x32_bf16 v[84:87], v[226:229], v[164:167], v[84:87]
	v_mfma_f32_16x16x32_bf16 v[52:55], v[218:221], v[172:175], v[52:55]
	v_mfma_f32_16x16x32_bf16 v[76:79], v[226:229], v[172:175], v[76:79]
	v_mfma_f32_16x16x32_bf16 v[40:43], v[218:221], v[186:189], v[40:43]
	v_mfma_f32_16x16x32_bf16 v[60:63], v[226:229], v[186:189], v[60:63]
	v_mfma_f32_16x16x32_bf16 v[80:83], v[222:225], v[160:163], v[80:83]
	v_mfma_f32_16x16x32_bf16 v[92:95], v[230:233], v[160:163], v[92:95]
	v_mfma_f32_16x16x32_bf16 v[64:67], v[222:225], v[168:171], v[64:67]
	v_mfma_f32_16x16x32_bf16 v[84:87], v[230:233], v[168:171], v[84:87]
	v_mfma_f32_16x16x32_bf16 v[52:55], v[222:225], v[182:185], v[52:55]
	v_mfma_f32_16x16x32_bf16 v[76:79], v[230:233], v[182:185], v[76:79]
	v_mfma_f32_16x16x32_bf16 v[40:43], v[222:225], v[214:217], v[40:43]
	v_mfma_f32_16x16x32_bf16 v[60:63], v[230:233], v[214:217], v[60:63]
	s_mov_b32 m0, s0
	v_lshl_add_u64 v[190:191], v[236:237], 0, s[64:65]
	s_barrier
	ds_read_b128 v[156:159], v138 offset:49152
	ds_read_b128 v[160:163], v138 offset:50176
	ds_read_b128 v[164:167], v138 offset:51200
	ds_read_b128 v[168:171], v138 offset:52224
	ds_read_b128 v[172:175], v138 offset:53248
	ds_read_b128 v[182:185], v138 offset:54272
	ds_read_b128 v[186:189], v138 offset:55296
	ds_read_b128 v[214:217], v138 offset:56320
	global_load_lds_dwordx4 v[190:191], off
	v_lshl_add_u64 v[190:191], v[238:239], 0, s[64:65]
	s_mov_b32 m0, s21
	s_nop 0
	global_load_lds_dwordx4 v[190:191], off
	s_waitcnt vmcnt(10)
	s_barrier
; __device__ __forceinline__ u32x4 mk4(unsigned a, unsigned b, unsigned c, unsigned d) { return (u32x4){a, b, c, d}; }
; #define G_STAGE(bufoff, gbase) do { _Pragma("unroll") for (int _i = 0; _i < 2; ++_i) \
;     __builtin_amdgcn_global_load_lds((const unsigned*)((const char*)(gbase) + voff[_i]), (GLAS unsigned*)(lds + (bufoff) + ldsw + _i * 8192), 16, 0, 0); } while (0)
; #define G_MMA(ai, bj, At_, Bt_) do { __builtin_amdgcn_s_setprio(1); \
;     _Pragma("unroll") for (int m = 0; m < 4; ++m) _Pragma("unroll") for (int n = 0; n < 2; ++n) _Pragma("unroll") for (int k = 0; k < 2; ++k) \
;       acc[ai][bj][m][n] = __builtin_amdgcn_mfma_f32_16x16x32_bf16(Bt_[n][k], At_[m][k], acc[ai][bj][m][n], 0, 0, 0); \
;     __builtin_amdgcn_s_setprio(0); } while (0)
; #define G_WAIT_V(n) asm volatile("s_waitcnt vmcnt(" #n ")" ::: "memory")
; #define G_WAIT_L(n) asm volatile("s_waitcnt lgkmcnt(" #n ")" ::: "memory")
; #define G_BAR __builtin_amdgcn_s_barrier()
; #define G_SCHED __builtin_amdgcn_sched_barrier(0)
; __device__ __forceinline__ void gemm_phase(const Params& p, int l, const bf16_t* __restrict__ A, const bf16_t* __restrict__ Bt, int M, int N, int K,
;                            int epi, bf16_t* __restrict__ outp, char* smem, int wvi) {
;     ...
;         G_BAR; G_WAIT_L(0); G_MMA(1, 0, At, B0); G_BAR; G_SCHED;
;         G_STAGE(G_SB(1, 1), b3 + hstep);
;         G_WAIT_V(6); G_BAR; G_MMA(1, 1, At, B1); G_BAR;
;       }
;       const int brow = pm * GBM, bcol = pn * GBM;
;     const int r0 = brow + wr * 64 + fr;
;     if (epi == EPI_PLAIN) {
; #pragma unroll
;       for (int ai = 0; ai < 2; ++ai)
; #pragma unroll
;         for (int m = 0; m < 4; ++m) {
;           bf16_t* rp = outp + (size_t)(r0 + ai * GHALF + m * 16) * N + bcol + wc * 32 + fq * 8;
; #pragma unroll
;           for (int bj = 0; bj < 2; ++bj) {
;             const f32x4 v0 = acc[ai][bj][m][0], v1 = acc[ai][bj][m][1];
;             *reinterpret_cast<u32x4*>(rp + bj * GHALF) = mk4(pk2(v0[0], v0[1]), pk2(v0[2], v0[3]), pk2(v1[0], v1[1]), pk2(v1[2], v1[3]));
	s_waitcnt lgkmcnt(0)
	s_waitcnt lgkmcnt(0)
	v_mfma_f32_16x16x32_bf16 v[68:71], v[140:143], v[156:159], v[68:71]
	v_mfma_f32_16x16x32_bf16 v[88:91], v[148:151], v[156:159], v[88:91]
	v_mfma_f32_16x16x32_bf16 v[48:51], v[140:143], v[164:167], v[48:51]
	v_mfma_f32_16x16x32_bf16 v[72:75], v[148:151], v[164:167], v[72:75]
	v_mfma_f32_16x16x32_bf16 v[36:39], v[140:143], v[172:175], v[36:39]
	v_mfma_f32_16x16x32_bf16 v[56:59], v[148:151], v[172:175], v[56:59]
	v_mfma_f32_16x16x32_bf16 v[32:35], v[140:143], v[186:189], v[32:35]
	v_mfma_f32_16x16x32_bf16 v[44:47], v[148:151], v[186:189], v[44:47]
	v_mfma_f32_16x16x32_bf16 v[68:71], v[144:147], v[160:163], v[68:71]
	v_mfma_f32_16x16x32_bf16 v[88:91], v[152:155], v[160:163], v[88:91]
	v_mfma_f32_16x16x32_bf16 v[48:51], v[144:147], v[168:171], v[48:51]
	v_mfma_f32_16x16x32_bf16 v[72:75], v[152:155], v[168:171], v[72:75]
	v_mfma_f32_16x16x32_bf16 v[36:39], v[144:147], v[182:185], v[36:39]
	v_mfma_f32_16x16x32_bf16 v[56:59], v[152:155], v[182:185], v[56:59]
	v_mfma_f32_16x16x32_bf16 v[32:35], v[144:147], v[214:217], v[32:35]
	v_mfma_f32_16x16x32_bf16 v[44:47], v[152:155], v[214:217], v[44:47]
	s_barrier
	s_add_u32 s10, s10, 0xb0080
	s_addc_u32 s11, s11, 0
	s_add_i32 s12, s12, s58
	v_lshl_add_u64 v[140:141], s[10:11], 0, v[176:177]
	s_mov_b32 m0, s12
	s_nop 0
	global_load_lds_dwordx4 v[140:141], off
	v_lshl_add_u64 v[140:141], s[10:11], 0, v[128:129]
	s_add_i32 m0, s12, 0x2000
	s_nop 0
	global_load_lds_dwordx4 v[140:141], off
	v_add_u32_e32 v139, 0x10000, v137
	ds_read_b128 v[140:143], v139
	ds_read_b128 v[144:147], v139 offset:1024
	ds_read_b128 v[148:151], v139 offset:2048
	ds_read_b128 v[152:155], v139 offset:3072
	s_waitcnt vmcnt(6)
	s_barrier
	v_mfma_f32_16x16x32_bf16 v[120:123], v[218:221], v[156:159], v[120:123]
	v_mfma_f32_16x16x32_bf16 v[124:127], v[226:229], v[156:159], v[124:127]
	v_mfma_f32_16x16x32_bf16 v[112:115], v[218:221], v[164:167], v[112:115]
	v_mfma_f32_16x16x32_bf16 v[116:119], v[226:229], v[164:167], v[116:119]
	v_mfma_f32_16x16x32_bf16 v[104:107], v[218:221], v[172:175], v[104:107]
	v_mfma_f32_16x16x32_bf16 v[108:111], v[226:229], v[172:175], v[108:111]
	v_mfma_f32_16x16x32_bf16 v[96:99], v[218:221], v[186:189], v[96:99]
	v_mfma_f32_16x16x32_bf16 v[100:103], v[226:229], v[186:189], v[100:103]
	v_mfma_f32_16x16x32_bf16 v[120:123], v[222:225], v[160:163], v[120:123]
	v_mfma_f32_16x16x32_bf16 v[124:127], v[230:233], v[160:163], v[124:127]
	v_mfma_f32_16x16x32_bf16 v[112:115], v[222:225], v[168:171], v[112:115]
	v_mfma_f32_16x16x32_bf16 v[116:119], v[230:233], v[168:171], v[116:119]
	v_mfma_f32_16x16x32_bf16 v[104:107], v[222:225], v[182:185], v[104:107]
	v_mfma_f32_16x16x32_bf16 v[108:111], v[230:233], v[182:185], v[108:111]
	v_mfma_f32_16x16x32_bf16 v[96:99], v[222:225], v[214:217], v[96:99]
	v_mfma_f32_16x16x32_bf16 v[100:103], v[230:233], v[214:217], v[100:103]
	s_add_i32 s31, s31, 2
	s_add_u32 s29, s29, 0x100
	s_addc_u32 s30, s30, 0
	s_cmp_gt_u32 s31, 41
	s_mov_b64 s[12:13], s[2:3]
	s_barrier
	s_cbranch_scc0 .LBB0_1039
	s_lshl_b32 s2, s26, 8
	v_lshl_add_u32 v250, s25, 8, v136
	s_ashr_i32 s3, s2, 31
	v_ashrrev_i32_e32 v251, 31, v250
	v_lshl_add_u64 v[252:253], s[2:3], 1, v[130:131]
	v_lshlrev_b64 v[254:255], 11, v[250:251]
	v_lshl_add_u64 v[254:255], v[252:253], 0, v[254:255]
	v_cvt_pk_bf16_f32 v20, v20, v21
	v_cvt_pk_bf16_f32 v21, v22, v23
	v_cvt_pk_bf16_f32 v22, v28, v29
	v_cvt_pk_bf16_f32 v23, v30, v31
	global_store_dwordx4 v[254:255], v[20:23], off
	v_cvt_pk_bf16_f32 v12, v12, v13
	v_cvt_pk_bf16_f32 v13, v14, v15
	v_cvt_pk_bf16_f32 v20, v80, v81
	v_cvt_pk_bf16_f32 v21, v82, v83
	v_cvt_pk_bf16_f32 v22, v92, v93
	v_cvt_pk_bf16_f32 v23, v94, v95
	global_store_dwordx4 v[254:255], v[20:23], off offset:256
	v_cvt_pk_bf16_f32 v14, v24, v25
	v_cvt_pk_bf16_f32 v15, v26, v27
	v_or_b32_e32 v20, 16, v250
	v_ashrrev_i32_e32 v21, 31, v20
	v_lshlrev_b64 v[20:21], 11, v[20:21]
	v_lshl_add_u64 v[20:21], v[252:253], 0, v[20:21]
	global_store_dwordx4 v[20:21], v[12:15], off
	v_cvt_pk_bf16_f32 v4, v4, v5
	v_cvt_pk_bf16_f32 v5, v6, v7
	v_cvt_pk_bf16_f32 v12, v64, v65
	v_cvt_pk_bf16_f32 v13, v66, v67
	v_cvt_pk_bf16_f32 v14, v84, v85
	v_cvt_pk_bf16_f32 v15, v86, v87
	global_store_dwordx4 v[20:21], v[12:15], off offset:256
	v_cvt_pk_bf16_f32 v6, v16, v17
	v_cvt_pk_bf16_f32 v7, v18, v19
	v_or_b32_e32 v12, 32, v250
	v_ashrrev_i32_e32 v13, 31, v12
	v_lshlrev_b64 v[12:13], 11, v[12:13]
	v_lshl_add_u64 v[12:13], v[252:253], 0, v[12:13]
	global_store_dwordx4 v[12:13], v[4:7], off
	v_cvt_pk_bf16_f32 v0, v0, v1
	v_cvt_pk_bf16_f32 v1, v2, v3
	v_cvt_pk_bf16_f32 v4, v52, v53
	v_cvt_pk_bf16_f32 v5, v54, v55
	v_cvt_pk_bf16_f32 v6, v76, v77
	v_cvt_pk_bf16_f32 v7, v78, v79
	global_store_dwordx4 v[12:13], v[4:7], off offset:256
	v_cvt_pk_bf16_f32 v2, v8, v9
	v_cvt_pk_bf16_f32 v3, v10, v11
	v_or_b32_e32 v4, 48, v250
	v_ashrrev_i32_e32 v5, 31, v4
	v_lshlrev_b64 v[4:5], 11, v[4:5]
	v_lshl_add_u64 v[4:5], v[252:253], 0, v[4:5]
	global_store_dwordx4 v[4:5], v[0:3], off
	s_mov_b64 s[2:3], 0x40000
	s_nop 0
	v_cvt_pk_bf16_f32 v0, v40, v41
	v_cvt_pk_bf16_f32 v1, v42, v43
	v_cvt_pk_bf16_f32 v2, v60, v61
	v_cvt_pk_bf16_f32 v3, v62, v63
	global_store_dwordx4 v[4:5], v[0:3], off offset:256
	v_lshl_add_u64 v[4:5], v[254:255], 0, s[2:3]
	s_mov_b32 s2, 0x40000
	v_add_co_u32_e32 v6, vcc, s2, v254
	v_cvt_pk_bf16_f32 v0, v68, v69
	v_cvt_pk_bf16_f32 v1, v70, v71
	v_cvt_pk_bf16_f32 v2, v88, v89
	v_cvt_pk_bf16_f32 v3, v90, v91
	v_addc_co_u32_e32 v7, vcc, 0, v255, vcc
	global_store_dwordx4 v[6:7], v[0:3], off
	s_mov_b64 s[2:3], 0x48000
	s_nop 0
	v_cvt_pk_bf16_f32 v0, v120, v121
	v_cvt_pk_bf16_f32 v1, v122, v123
	v_cvt_pk_bf16_f32 v2, v124, v125
	v_cvt_pk_bf16_f32 v3, v126, v127
	global_store_dwordx4 v[4:5], v[0:3], off offset:256
	v_lshl_add_u64 v[4:5], v[254:255], 0, s[2:3]
	s_mov_b32 s2, 0x48000
	v_add_co_u32_e32 v6, vcc, s2, v254
	v_cvt_pk_bf16_f32 v0, v48, v49
	v_cvt_pk_bf16_f32 v1, v50, v51
	v_cvt_pk_bf16_f32 v2, v72, v73
	v_cvt_pk_bf16_f32 v3, v74, v75
	v_addc_co_u32_e32 v7, vcc, 0, v255, vcc
	global_store_dwordx4 v[6:7], v[0:3], off
	s_mov_b64 s[2:3], 0x50000
	s_nop 0
	v_cvt_pk_bf16_f32 v0, v112, v113
	v_cvt_pk_bf16_f32 v1, v114, v115
	v_cvt_pk_bf16_f32 v2, v116, v117
	v_cvt_pk_bf16_f32 v3, v118, v119
	global_store_dwordx4 v[4:5], v[0:3], off offset:256
	v_lshl_add_u64 v[4:5], v[254:255], 0, s[2:3]
	s_mov_b32 s2, 0x50000
	v_add_co_u32_e32 v6, vcc, s2, v254
	v_cvt_pk_bf16_f32 v0, v36, v37
	v_cvt_pk_bf16_f32 v1, v38, v39
	v_cvt_pk_bf16_f32 v2, v56, v57
	v_cvt_pk_bf16_f32 v3, v58, v59
	v_addc_co_u32_e32 v7, vcc, 0, v255, vcc
	global_store_dwordx4 v[6:7], v[0:3], off
	s_mov_b64 s[2:3], 0x58000
	s_nop 0
	v_cvt_pk_bf16_f32 v0, v104, v105
	v_cvt_pk_bf16_f32 v1, v106, v107
	v_cvt_pk_bf16_f32 v2, v108, v109
	v_cvt_pk_bf16_f32 v3, v110, v111
	global_store_dwordx4 v[4:5], v[0:3], off offset:256
	v_lshl_add_u64 v[4:5], v[254:255], 0, s[2:3]
	s_mov_b32 s2, 0x58000
	v_add_co_u32_e32 v6, vcc, s2, v254
	v_cvt_pk_bf16_f32 v0, v32, v33
	v_cvt_pk_bf16_f32 v1, v34, v35
	v_cvt_pk_bf16_f32 v2, v44, v45
	v_cvt_pk_bf16_f32 v3, v46, v47
	v_addc_co_u32_e32 v7, vcc, 0, v255, vcc
	global_store_dwordx4 v[6:7], v[0:3], off
	s_mov_b64 s[2:3], -1
	s_and_b64 vcc, exec, s[8:9]
	v_cvt_pk_bf16_f32 v0, v96, v97
	v_cvt_pk_bf16_f32 v1, v98, v99
	v_cvt_pk_bf16_f32 v2, v100, v101
	v_cvt_pk_bf16_f32 v3, v102, v103
	global_store_dwordx4 v[4:5], v[0:3], off offset:256
	s_cbranch_vccz .LBB0_1035
	v_mov_b32_e32 v20, v177
	v_mov_b32_e32 v28, v177
	v_mov_b32_e32 v12, v177
	v_mov_b32_e32 v24, v177
	v_mov_b32_e32 v4, v177
	v_mov_b32_e32 v16, v177
	v_mov_b32_e32 v0, v177
	v_mov_b32_e32 v8, v177
	v_mov_b32_e32 v80, v177
	v_mov_b32_e32 v92, v177
	v_mov_b32_e32 v64, v177
	v_mov_b32_e32 v84, v177
	v_mov_b32_e32 v52, v177
	v_mov_b32_e32 v76, v177
	v_mov_b32_e32 v40, v177
	v_mov_b32_e32 v60, v177
	v_mov_b32_e32 v68, v177
	v_mov_b32_e32 v88, v177
	v_mov_b32_e32 v48, v177
	v_mov_b32_e32 v72, v177
	v_mov_b32_e32 v36, v177
	v_mov_b32_e32 v56, v177
	v_mov_b32_e32 v32, v177
	v_mov_b32_e32 v44, v177
	v_mov_b32_e32 v120, v177
	v_mov_b32_e32 v124, v177
	v_mov_b32_e32 v112, v177
	v_mov_b32_e32 v116, v177
	v_mov_b32_e32 v104, v177
	v_mov_b32_e32 v108, v177
	v_mov_b32_e32 v96, v177
	v_mov_b32_e32 v100, v177
	s_nop 0
	v_mov_b32_e32 v21, v20
	v_mov_b32_e32 v22, v20
	v_mov_b32_e32 v23, v20
	v_mov_b32_e32 v29, v28
	v_mov_b32_e32 v30, v28
	v_mov_b32_e32 v31, v28
	v_mov_b32_e32 v13, v12
	v_mov_b32_e32 v14, v12
	v_mov_b32_e32 v15, v12
	v_mov_b32_e32 v25, v24
	v_mov_b32_e32 v26, v24
	v_mov_b32_e32 v27, v24
	v_mov_b32_e32 v5, v4
	v_mov_b32_e32 v6, v4
	v_mov_b32_e32 v7, v4
	v_mov_b32_e32 v17, v16
	v_mov_b32_e32 v18, v16
	v_mov_b32_e32 v19, v16
	s_nop 0
	v_mov_b32_e32 v1, v0
	v_mov_b32_e32 v2, v0
	v_mov_b32_e32 v3, v0
	v_mov_b32_e32 v9, v8
	v_mov_b32_e32 v10, v8
	v_mov_b32_e32 v11, v8
	v_mov_b32_e32 v81, v80
	v_mov_b32_e32 v82, v80
	v_mov_b32_e32 v83, v80
	v_mov_b32_e32 v93, v92
	v_mov_b32_e32 v94, v92
	v_mov_b32_e32 v95, v92
	v_mov_b32_e32 v65, v64
	v_mov_b32_e32 v66, v64
	v_mov_b32_e32 v67, v64
	v_mov_b32_e32 v85, v84
	v_mov_b32_e32 v86, v84
	v_mov_b32_e32 v87, v84
	s_nop 0
	v_mov_b32_e32 v53, v52
	v_mov_b32_e32 v54, v52
	v_mov_b32_e32 v55, v52
	v_mov_b32_e32 v77, v76
	v_mov_b32_e32 v78, v76
	v_mov_b32_e32 v79, v76
	v_mov_b32_e32 v41, v40
	v_mov_b32_e32 v42, v40
	v_mov_b32_e32 v43, v40
	v_mov_b32_e32 v61, v60
	v_mov_b32_e32 v62, v60
	v_mov_b32_e32 v63, v60
	v_mov_b32_e32 v69, v68
	v_mov_b32_e32 v70, v68
	v_mov_b32_e32 v71, v68
	v_mov_b32_e32 v89, v88
	v_mov_b32_e32 v90, v88
	v_mov_b32_e32 v91, v88
	s_nop 0
	v_mov_b32_e32 v49, v48
	v_mov_b32_e32 v50, v48
	v_mov_b32_e32 v51, v48
	v_mov_b32_e32 v73, v72
	v_mov_b32_e32 v74, v72
	v_mov_b32_e32 v75, v72
	v_mov_b32_e32 v37, v36
	v_mov_b32_e32 v38, v36
	v_mov_b32_e32 v39, v36
	v_mov_b32_e32 v57, v56
	v_mov_b32_e32 v58, v56
	v_mov_b32_e32 v59, v56
	v_mov_b32_e32 v33, v32
	v_mov_b32_e32 v34, v32
	v_mov_b32_e32 v35, v32
	v_mov_b32_e32 v45, v44
	v_mov_b32_e32 v46, v44
	v_mov_b32_e32 v47, v44
	s_nop 0
	v_mov_b32_e32 v121, v120
	v_mov_b32_e32 v122, v120
	v_mov_b32_e32 v123, v120
	v_mov_b32_e32 v125, v124
	v_mov_b32_e32 v126, v124
	v_mov_b32_e32 v127, v124
	v_mov_b32_e32 v113, v112
	v_mov_b32_e32 v114, v112
	v_mov_b32_e32 v115, v112
	v_mov_b32_e32 v117, v116
	v_mov_b32_e32 v118, v116
	v_mov_b32_e32 v119, v116
	v_mov_b32_e32 v105, v104
	v_mov_b32_e32 v106, v104
	v_mov_b32_e32 v107, v104
	v_mov_b32_e32 v109, v108
	v_mov_b32_e32 v110, v108
	v_mov_b32_e32 v111, v108
	s_mov_b64 s[2:3], 0
	v_mov_b32_e32 v97, v96
	v_mov_b32_e32 v98, v96
	v_mov_b32_e32 v99, v96
	v_mov_b32_e32 v101, v100
	v_mov_b32_e32 v102, v100
	v_mov_b32_e32 v103, v100
	s_branch .LBB0_1035

.LBB0_1194:
	v_readlane_b32 s0, v247, 21
	v_readlane_b32 s1, v247, 22
	v_mov_b32_e32 v129, v177
	v_readlane_b32 s16, v247, 17
	v_lshl_add_u64 v[2:3], s[0:1], 0, v[176:177]
	v_lshl_add_u64 v[6:7], s[0:1], 0, v[128:129]
	v_readlane_b32 s17, v247, 18
	v_lshl_add_u64 v[2:3], v[2:3], 0, s[64:65]
	s_add_i32 m0, s30, 0x18000
	v_lshl_add_u64 v[10:11], s[16:17], 0, v[176:177]
	s_waitcnt vmcnt(4)
	s_barrier
	global_load_lds_dwordx4 v[2:3], off
	v_lshl_add_u64 v[2:3], v[6:7], 0, s[64:65]
	s_add_i32 m0, s30, 0x1a000
	s_add_i32 s89, s30, 0x8000
	v_lshl_add_u64 v[14:15], s[16:17], 0, v[128:129]
	global_load_lds_dwordx4 v[2:3], off
	v_lshl_add_u64 v[2:3], v[10:11], 0, s[64:65]
	s_mov_b32 m0, s89
	s_add_i32 s92, s30, 0xa000
	v_readlane_b32 s0, v247, 23
	global_load_lds_dwordx4 v[2:3], off
	v_lshl_add_u64 v[2:3], v[14:15], 0, s[64:65]
	s_mov_b32 m0, s92
	v_readlane_b32 s1, v247, 24
	global_load_lds_dwordx4 v[2:3], off
	s_nop 0
	v_lshl_add_u64 v[2:3], s[0:1], 0, v[176:177]
	s_add_i32 m0, s30, 0x1c000
	v_and_b32_e32 v131, 15, v130
	global_load_lds_dwordx4 v[2:3], off
	v_lshl_add_u64 v[2:3], s[0:1], 0, v[128:129]
	s_add_i32 m0, s30, 0x1e000
	v_readlane_b32 s0, v248, 10
	global_load_lds_dwordx4 v[2:3], off
	s_nop 0
	v_or_b32_e32 v138, s0, v131
	v_lshlrev_b32_e32 v139, 6, v138
	v_and_b32_e32 v142, 48, v130
	s_movk_i32 s0, 0x3c0
	v_lshlrev_b32_e32 v143, 2, v138
	v_and_or_b32 v139, v139, s0, v142
	v_and_b32_e32 v143, 32, v143
	v_readlane_b32 s0, v248, 11
	v_lshlrev_b32_e32 v130, 2, v130
	v_lshlrev_b32_e32 v133, 13, v133
	v_lshlrev_b32_e32 v134, 13, v134
	v_bitop3_b32 v144, v139, s0, v143 bitop3:0xde
	v_lshl_or_b32 v131, v131, 6, v142
	v_and_b32_e32 v130, 32, v130
	v_readlane_b32 s0, v248, 12
	v_and_b32_e32 v133, 0x7fffc000, v133
	v_and_b32_e32 v134, 0x7fffc000, v134
	v_bitop3_b32 v139, v131, s0, v130 bitop3:0xde
	v_readlane_b32 s0, v248, 21
	v_lshl_add_u32 v132, v132, 10, v133
	v_lshl_add_u32 v134, v135, 10, v134
	v_mov_b32_e32 v143, v177
	v_readlane_b32 s1, v248, 22
	v_or_b32_e32 v132, v132, v140
	v_or_b32_e32 v134, v134, v136
	v_lshl_add_u64 v[130:131], s[0:1], 0, v[142:143]
	v_add_lshl_u32 v132, v132, v141, 1
	v_mov_b32_e32 v133, v177
	s_mov_b64 s[0:1], 0x40080
	v_add_lshl_u32 v134, v134, v137, 1
	v_mov_b32_e32 v135, v177
	s_waitcnt vmcnt(6)
	v_lshl_add_u64 v[132:133], v[132:133], 0, s[0:1]
	v_lshl_add_u64 v[134:135], v[134:135], 0, s[0:1]
	v_readlane_b32 s0, v247, 11
	v_readlane_b32 s1, v247, 12
	v_readlane_b32 s2, v247, 13
	v_mov_b32_e32 v121, v120
	v_mov_b32_e32 v122, v120
	v_mov_b32_e32 v123, v120
	v_mov_b32_e32 v125, v124
	v_mov_b32_e32 v126, v124
	v_mov_b32_e32 v127, v124
	v_mov_b32_e32 v105, v104
	v_mov_b32_e32 v106, v104
	v_mov_b32_e32 v107, v104
	v_mov_b32_e32 v109, v108
	v_mov_b32_e32 v110, v108
	v_mov_b32_e32 v111, v108
	v_mov_b32_e32 v89, v88
	v_mov_b32_e32 v90, v88
	v_mov_b32_e32 v91, v88
	v_mov_b32_e32 v93, v92
	v_mov_b32_e32 v94, v92
	v_mov_b32_e32 v95, v92
	v_mov_b32_e32 v73, v72
	v_mov_b32_e32 v74, v72
	v_mov_b32_e32 v75, v72
	v_mov_b32_e32 v77, v76
	v_mov_b32_e32 v78, v76
	v_mov_b32_e32 v79, v76
	v_mov_b32_e32 v113, v112
	v_mov_b32_e32 v114, v112
	v_mov_b32_e32 v115, v112
	v_mov_b32_e32 v117, v116
	v_mov_b32_e32 v118, v116
	v_mov_b32_e32 v119, v116
	v_mov_b32_e32 v97, v96
	v_mov_b32_e32 v98, v96
	v_mov_b32_e32 v99, v96
	v_mov_b32_e32 v101, v100
	v_mov_b32_e32 v102, v100
	v_mov_b32_e32 v103, v100
	v_mov_b32_e32 v81, v80
	v_mov_b32_e32 v82, v80
	v_mov_b32_e32 v83, v80
	v_mov_b32_e32 v85, v84
	v_mov_b32_e32 v86, v84
	v_mov_b32_e32 v87, v84
	v_mov_b32_e32 v65, v64
	v_mov_b32_e32 v66, v64
	v_mov_b32_e32 v67, v64
	v_mov_b32_e32 v69, v68
	v_mov_b32_e32 v70, v68
	v_mov_b32_e32 v71, v68
	v_mov_b32_e32 v57, v56
	v_mov_b32_e32 v58, v56
	v_mov_b32_e32 v59, v56
	v_mov_b32_e32 v61, v60
	v_mov_b32_e32 v62, v60
	v_mov_b32_e32 v63, v60
	v_mov_b32_e32 v41, v40
	v_mov_b32_e32 v42, v40
	v_mov_b32_e32 v43, v40
	v_mov_b32_e32 v45, v44
	v_mov_b32_e32 v46, v44
	v_mov_b32_e32 v47, v44
	v_mov_b32_e32 v25, v24
	v_mov_b32_e32 v26, v24
	v_mov_b32_e32 v27, v24
	v_mov_b32_e32 v29, v28
	v_mov_b32_e32 v30, v28
	v_mov_b32_e32 v31, v28
	v_mov_b32_e32 v9, v8
	v_mov_b32_e32 v10, v8
	v_mov_b32_e32 v11, v8
	v_mov_b32_e32 v13, v12
	v_mov_b32_e32 v14, v12
	v_mov_b32_e32 v15, v12
	v_mov_b32_e32 v49, v48
	v_mov_b32_e32 v50, v48
	v_mov_b32_e32 v51, v48
	v_mov_b32_e32 v53, v52
	v_mov_b32_e32 v54, v52
	v_mov_b32_e32 v55, v52
	v_mov_b32_e32 v33, v32
	v_mov_b32_e32 v34, v32
	v_mov_b32_e32 v35, v32
	v_mov_b32_e32 v37, v36
	v_mov_b32_e32 v38, v36
	v_mov_b32_e32 v39, v36
	v_mov_b32_e32 v17, v16
	v_mov_b32_e32 v18, v16
	v_mov_b32_e32 v19, v16
	v_mov_b32_e32 v21, v20
	v_mov_b32_e32 v22, v20
	v_mov_b32_e32 v23, v20
	v_mov_b32_e32 v1, v0
	v_mov_b32_e32 v2, v0
	v_mov_b32_e32 v3, v0
	v_mov_b32_e32 v5, v4
	v_mov_b32_e32 v6, v4
	v_mov_b32_e32 v7, v4
	v_add_u32_e32 v140, 0, v144
	v_readlane_b32 s1, v247, 10
	v_readlane_b32 s3, v247, 14
	v_readlane_b32 s20, v248, 0
	s_barrier
	v_add_u32_e32 v136, 0x10000, v139
	ds_read_b128 v[142:145], v136
	ds_read_b128 v[146:149], v136 offset:1024
	ds_read_b128 v[150:153], v136 offset:2048
	ds_read_b128 v[154:157], v136 offset:3072
	s_branch .LBB0_1196

.LBB0_1199:
	s_add_u32 s2, s16, 0x100
	s_addc_u32 s3, s17, 0
	s_add_i32 s24, 0, 0x10000
	s_cmp_eq_u32 s23, 12
	s_cselect_b32 s29, s9, s3
	s_cselect_b32 s28, s8, s2
	s_cselect_b32 s15, s7, s22
	s_cselect_b32 s14, s5, s21
	v_lshl_add_u64 v[136:137], s[16:17], 0, v[132:133]
	s_add_i32 m0, s30, 0xc000
	ds_read_b128 v[158:161], v140
	ds_read_b128 v[162:165], v140 offset:1024
	ds_read_b128 v[166:169], v140 offset:2048
	ds_read_b128 v[170:173], v140 offset:3072
	ds_read_b128 v[182:185], v140 offset:4096
	ds_read_b128 v[186:189], v140 offset:5120
	ds_read_b128 v[214:217], v140 offset:6144
	ds_read_b128 v[218:221], v140 offset:7168
	global_load_lds_dwordx4 v[136:137], off
	v_lshl_add_u64 v[136:137], s[16:17], 0, v[134:135]
	s_add_i32 m0, s30, 0xe000
	s_nop 0
	global_load_lds_dwordx4 v[136:137], off
	s_waitcnt lgkmcnt(8)
	s_barrier
	s_waitcnt lgkmcnt(0)
	s_waitcnt lgkmcnt(0)
	v_mfma_f32_16x16x32_bf16 v[120:123], v[142:145], v[158:161], v[120:123]
	v_mfma_f32_16x16x32_bf16 v[124:127], v[150:153], v[158:161], v[124:127]
	v_mfma_f32_16x16x32_bf16 v[104:107], v[142:145], v[166:169], v[104:107]
	v_mfma_f32_16x16x32_bf16 v[108:111], v[150:153], v[166:169], v[108:111]
	v_mfma_f32_16x16x32_bf16 v[88:91], v[142:145], v[182:185], v[88:91]
	v_mfma_f32_16x16x32_bf16 v[92:95], v[150:153], v[182:185], v[92:95]
	v_mfma_f32_16x16x32_bf16 v[72:75], v[142:145], v[214:217], v[72:75]
	v_mfma_f32_16x16x32_bf16 v[76:79], v[150:153], v[214:217], v[76:79]
	v_mfma_f32_16x16x32_bf16 v[120:123], v[146:149], v[162:165], v[120:123]
	v_mfma_f32_16x16x32_bf16 v[124:127], v[154:157], v[162:165], v[124:127]
	v_mfma_f32_16x16x32_bf16 v[104:107], v[146:149], v[170:173], v[104:107]
	v_mfma_f32_16x16x32_bf16 v[108:111], v[154:157], v[170:173], v[108:111]
	v_mfma_f32_16x16x32_bf16 v[88:91], v[146:149], v[186:189], v[88:91]
	v_mfma_f32_16x16x32_bf16 v[92:95], v[154:157], v[186:189], v[92:95]
	v_mfma_f32_16x16x32_bf16 v[72:75], v[146:149], v[218:221], v[72:75]
	v_mfma_f32_16x16x32_bf16 v[76:79], v[154:157], v[218:221], v[76:79]
	s_barrier
	s_add_i32 s25, 0, 0x14000
	v_add_u32_e32 v136, s25, v139
	s_add_i32 s16, s24, s58
	ds_read_b128 v[222:225], v136
	ds_read_b128 v[226:229], v136 offset:1024
	ds_read_b128 v[230:233], v136 offset:2048
	ds_read_b128 v[234:237], v136 offset:3072
	v_lshl_add_u64 v[136:137], s[14:15], 0, v[176:177]
	s_mov_b32 m0, s16
	v_lshl_add_u64 v[174:175], s[14:15], 0, v[128:129]
	global_load_lds_dwordx4 v[136:137], off
	s_add_i32 m0, s16, 0x2000
	s_nop 0
	global_load_lds_dwordx4 v[174:175], off
	s_barrier
	s_waitcnt lgkmcnt(0)
	s_waitcnt lgkmcnt(0)
	v_mfma_f32_16x16x32_bf16 v[112:115], v[222:225], v[158:161], v[112:115]
	v_mfma_f32_16x16x32_bf16 v[116:119], v[230:233], v[158:161], v[116:119]
	v_mfma_f32_16x16x32_bf16 v[96:99], v[222:225], v[166:169], v[96:99]
	v_mfma_f32_16x16x32_bf16 v[100:103], v[230:233], v[166:169], v[100:103]
	v_mfma_f32_16x16x32_bf16 v[80:83], v[222:225], v[182:185], v[80:83]
	v_mfma_f32_16x16x32_bf16 v[84:87], v[230:233], v[182:185], v[84:87]
	v_mfma_f32_16x16x32_bf16 v[64:67], v[222:225], v[214:217], v[64:67]
	v_mfma_f32_16x16x32_bf16 v[68:71], v[230:233], v[214:217], v[68:71]
	v_mfma_f32_16x16x32_bf16 v[112:115], v[226:229], v[162:165], v[112:115]
	v_mfma_f32_16x16x32_bf16 v[116:119], v[234:237], v[162:165], v[116:119]
	v_mfma_f32_16x16x32_bf16 v[96:99], v[226:229], v[170:173], v[96:99]
	v_mfma_f32_16x16x32_bf16 v[100:103], v[234:237], v[170:173], v[100:103]
	v_mfma_f32_16x16x32_bf16 v[80:83], v[226:229], v[186:189], v[80:83]
	v_mfma_f32_16x16x32_bf16 v[84:87], v[234:237], v[186:189], v[84:87]
	v_mfma_f32_16x16x32_bf16 v[64:67], v[226:229], v[218:221], v[64:67]
	v_mfma_f32_16x16x32_bf16 v[68:71], v[234:237], v[218:221], v[68:71]
	s_mov_b32 m0, s30
	v_lshl_add_u64 v[190:191], s[28:29], 0, v[176:177]
	s_barrier
	ds_read_b128 v[158:161], v140 offset:16384
	ds_read_b128 v[162:165], v140 offset:17408
	ds_read_b128 v[166:169], v140 offset:18432
	ds_read_b128 v[170:173], v140 offset:19456
	ds_read_b128 v[182:185], v140 offset:20480
	ds_read_b128 v[186:189], v140 offset:21504
	ds_read_b128 v[214:217], v140 offset:22528
	ds_read_b128 v[218:221], v140 offset:23552
	global_load_lds_dwordx4 v[190:191], off
	v_lshl_add_u64 v[238:239], s[28:29], 0, v[128:129]
	s_mov_b32 m0, s31
	s_nop 0
	global_load_lds_dwordx4 v[238:239], off
	s_barrier
	s_waitcnt lgkmcnt(0)
	s_waitcnt lgkmcnt(0)
	v_mfma_f32_16x16x32_bf16 v[56:59], v[142:145], v[158:161], v[56:59]
	v_mfma_f32_16x16x32_bf16 v[60:63], v[150:153], v[158:161], v[60:63]
	v_mfma_f32_16x16x32_bf16 v[40:43], v[142:145], v[166:169], v[40:43]
	v_mfma_f32_16x16x32_bf16 v[44:47], v[150:153], v[166:169], v[44:47]
	v_mfma_f32_16x16x32_bf16 v[24:27], v[142:145], v[182:185], v[24:27]
	v_mfma_f32_16x16x32_bf16 v[28:31], v[150:153], v[182:185], v[28:31]
	v_mfma_f32_16x16x32_bf16 v[8:11], v[142:145], v[214:217], v[8:11]
	v_mfma_f32_16x16x32_bf16 v[12:15], v[150:153], v[214:217], v[12:15]
	v_mfma_f32_16x16x32_bf16 v[56:59], v[146:149], v[162:165], v[56:59]
	v_mfma_f32_16x16x32_bf16 v[60:63], v[154:157], v[162:165], v[60:63]
	v_mfma_f32_16x16x32_bf16 v[40:43], v[146:149], v[170:173], v[40:43]
	v_mfma_f32_16x16x32_bf16 v[44:47], v[154:157], v[170:173], v[44:47]
	v_mfma_f32_16x16x32_bf16 v[24:27], v[146:149], v[186:189], v[24:27]
	v_mfma_f32_16x16x32_bf16 v[28:31], v[154:157], v[186:189], v[28:31]
	v_mfma_f32_16x16x32_bf16 v[8:11], v[146:149], v[218:221], v[8:11]
	v_mfma_f32_16x16x32_bf16 v[12:15], v[154:157], v[218:221], v[12:15]
	s_barrier
	s_add_u32 s16, s14, 0x40000
	s_addc_u32 s17, s15, 0
	s_add_i32 s24, s25, s58
	v_lshl_add_u64 v[142:143], s[16:17], 0, v[176:177]
	s_mov_b32 m0, s24
	s_nop 0
	global_load_lds_dwordx4 v[142:143], off
	v_lshl_add_u64 v[142:143], s[16:17], 0, v[128:129]
	s_add_i32 m0, s24, 0x2000
	s_nop 0
	global_load_lds_dwordx4 v[142:143], off
	s_waitcnt vmcnt(6)
	s_barrier
	v_mfma_f32_16x16x32_bf16 v[48:51], v[222:225], v[158:161], v[48:51]
	v_mfma_f32_16x16x32_bf16 v[52:55], v[230:233], v[158:161], v[52:55]
	v_mfma_f32_16x16x32_bf16 v[32:35], v[222:225], v[166:169], v[32:35]
	v_mfma_f32_16x16x32_bf16 v[36:39], v[230:233], v[166:169], v[36:39]
	v_mfma_f32_16x16x32_bf16 v[16:19], v[222:225], v[182:185], v[16:19]
	v_mfma_f32_16x16x32_bf16 v[20:23], v[230:233], v[182:185], v[20:23]
	v_mfma_f32_16x16x32_bf16 v[0:3], v[222:225], v[214:217], v[0:3]
	v_mfma_f32_16x16x32_bf16 v[4:7], v[230:233], v[214:217], v[4:7]
	v_mfma_f32_16x16x32_bf16 v[48:51], v[226:229], v[162:165], v[48:51]
	v_mfma_f32_16x16x32_bf16 v[52:55], v[234:237], v[162:165], v[52:55]
	v_mfma_f32_16x16x32_bf16 v[32:35], v[226:229], v[170:173], v[32:35]
	v_mfma_f32_16x16x32_bf16 v[36:39], v[234:237], v[170:173], v[36:39]
	v_mfma_f32_16x16x32_bf16 v[16:19], v[226:229], v[186:189], v[16:19]
	v_mfma_f32_16x16x32_bf16 v[20:23], v[234:237], v[186:189], v[20:23]
	v_mfma_f32_16x16x32_bf16 v[0:3], v[226:229], v[218:221], v[0:3]
	v_mfma_f32_16x16x32_bf16 v[4:7], v[234:237], v[218:221], v[4:7]
	s_add_i32 s24, 0, 0x18000
	v_add_u32_e32 v141, s24, v139
	s_barrier
	ds_read_b128 v[142:145], v141
	ds_read_b128 v[146:149], v141 offset:1024
	ds_read_b128 v[150:153], v141 offset:2048
	ds_read_b128 v[154:157], v141 offset:3072
	s_add_u32 s16, s28, 0x40000
	s_addc_u32 s17, s29, 0
	s_mov_b32 m0, s55
	v_lshl_add_u64 v[222:223], s[16:17], 0, v[176:177]
	ds_read_b128 v[158:161], v140 offset:32768
	ds_read_b128 v[162:165], v140 offset:33792
	ds_read_b128 v[166:169], v140 offset:34816
	ds_read_b128 v[170:173], v140 offset:35840
	ds_read_b128 v[182:185], v140 offset:36864
	ds_read_b128 v[186:189], v140 offset:37888
	ds_read_b128 v[214:217], v140 offset:38912
	ds_read_b128 v[218:221], v140 offset:39936
	global_load_lds_dwordx4 v[222:223], off
	v_lshl_add_u64 v[222:223], s[16:17], 0, v[128:129]
	s_mov_b32 m0, s88
	s_nop 0
	global_load_lds_dwordx4 v[222:223], off
	s_waitcnt lgkmcnt(8)
	s_barrier
	s_waitcnt lgkmcnt(0)
	s_waitcnt lgkmcnt(0)
	v_mfma_f32_16x16x32_bf16 v[120:123], v[142:145], v[158:161], v[120:123]
	v_mfma_f32_16x16x32_bf16 v[124:127], v[150:153], v[158:161], v[124:127]
	v_mfma_f32_16x16x32_bf16 v[104:107], v[142:145], v[166:169], v[104:107]
	v_mfma_f32_16x16x32_bf16 v[108:111], v[150:153], v[166:169], v[108:111]
	v_mfma_f32_16x16x32_bf16 v[88:91], v[142:145], v[182:185], v[88:91]
	v_mfma_f32_16x16x32_bf16 v[92:95], v[150:153], v[182:185], v[92:95]
	v_mfma_f32_16x16x32_bf16 v[72:75], v[142:145], v[214:217], v[72:75]
	v_mfma_f32_16x16x32_bf16 v[76:79], v[150:153], v[214:217], v[76:79]
	v_mfma_f32_16x16x32_bf16 v[120:123], v[146:149], v[162:165], v[120:123]
	v_mfma_f32_16x16x32_bf16 v[124:127], v[154:157], v[162:165], v[124:127]
	v_mfma_f32_16x16x32_bf16 v[104:107], v[146:149], v[170:173], v[104:107]
	v_mfma_f32_16x16x32_bf16 v[108:111], v[154:157], v[170:173], v[108:111]
	v_mfma_f32_16x16x32_bf16 v[88:91], v[146:149], v[186:189], v[88:91]
	v_mfma_f32_16x16x32_bf16 v[92:95], v[154:157], v[186:189], v[92:95]
	v_mfma_f32_16x16x32_bf16 v[72:75], v[146:149], v[218:221], v[72:75]
	v_mfma_f32_16x16x32_bf16 v[76:79], v[154:157], v[218:221], v[76:79]
	s_barrier
	s_add_i32 s16, 0, 0x1c000
	s_add_i32 s17, s24, s58
	v_add_u32_e32 v141, s16, v139
	v_lshl_add_u64 v[136:137], v[136:137], 0, s[64:65]
	s_mov_b32 m0, s17
	ds_read_b128 v[222:225], v141
	ds_read_b128 v[226:229], v141 offset:1024
	ds_read_b128 v[230:233], v141 offset:2048
	ds_read_b128 v[234:237], v141 offset:3072
	global_load_lds_dwordx4 v[136:137], off
	v_lshl_add_u64 v[136:137], v[174:175], 0, s[64:65]
	s_add_i32 m0, s17, 0x2000
	s_nop 0
	global_load_lds_dwordx4 v[136:137], off
	s_barrier
	s_waitcnt lgkmcnt(0)
	s_waitcnt lgkmcnt(0)
	v_mfma_f32_16x16x32_bf16 v[112:115], v[222:225], v[158:161], v[112:115]
	v_mfma_f32_16x16x32_bf16 v[116:119], v[230:233], v[158:161], v[116:119]
	v_mfma_f32_16x16x32_bf16 v[96:99], v[222:225], v[166:169], v[96:99]
	v_mfma_f32_16x16x32_bf16 v[100:103], v[230:233], v[166:169], v[100:103]
	v_mfma_f32_16x16x32_bf16 v[80:83], v[222:225], v[182:185], v[80:83]
	v_mfma_f32_16x16x32_bf16 v[84:87], v[230:233], v[182:185], v[84:87]
	v_mfma_f32_16x16x32_bf16 v[64:67], v[222:225], v[214:217], v[64:67]
	v_mfma_f32_16x16x32_bf16 v[68:71], v[230:233], v[214:217], v[68:71]
	v_mfma_f32_16x16x32_bf16 v[112:115], v[226:229], v[162:165], v[112:115]
	v_mfma_f32_16x16x32_bf16 v[116:119], v[234:237], v[162:165], v[116:119]
	v_mfma_f32_16x16x32_bf16 v[96:99], v[226:229], v[170:173], v[96:99]
	v_mfma_f32_16x16x32_bf16 v[100:103], v[234:237], v[170:173], v[100:103]
	v_mfma_f32_16x16x32_bf16 v[80:83], v[226:229], v[186:189], v[80:83]
	v_mfma_f32_16x16x32_bf16 v[84:87], v[234:237], v[186:189], v[84:87]
	v_mfma_f32_16x16x32_bf16 v[64:67], v[226:229], v[218:221], v[64:67]
	v_mfma_f32_16x16x32_bf16 v[68:71], v[234:237], v[218:221], v[68:71]
	s_mov_b32 m0, s89
	v_lshl_add_u64 v[136:137], v[190:191], 0, s[64:65]
	s_barrier
	ds_read_b128 v[158:161], v140 offset:49152
	ds_read_b128 v[162:165], v140 offset:50176
	ds_read_b128 v[166:169], v140 offset:51200
	ds_read_b128 v[170:173], v140 offset:52224
	ds_read_b128 v[182:185], v140 offset:53248
	ds_read_b128 v[186:189], v140 offset:54272
	ds_read_b128 v[214:217], v140 offset:55296
	ds_read_b128 v[218:221], v140 offset:56320
	global_load_lds_dwordx4 v[136:137], off
	v_lshl_add_u64 v[136:137], v[238:239], 0, s[64:65]
	s_mov_b32 m0, s92
	s_nop 0
	global_load_lds_dwordx4 v[136:137], off
	s_waitcnt vmcnt(10)
	s_barrier
	s_waitcnt lgkmcnt(0)
	s_waitcnt lgkmcnt(0)
	v_mfma_f32_16x16x32_bf16 v[56:59], v[142:145], v[158:161], v[56:59]
	v_mfma_f32_16x16x32_bf16 v[60:63], v[150:153], v[158:161], v[60:63]
	v_mfma_f32_16x16x32_bf16 v[40:43], v[142:145], v[166:169], v[40:43]
	v_mfma_f32_16x16x32_bf16 v[44:47], v[150:153], v[166:169], v[44:47]
	v_mfma_f32_16x16x32_bf16 v[24:27], v[142:145], v[182:185], v[24:27]
	v_mfma_f32_16x16x32_bf16 v[28:31], v[150:153], v[182:185], v[28:31]
	v_mfma_f32_16x16x32_bf16 v[8:11], v[142:145], v[214:217], v[8:11]
	v_mfma_f32_16x16x32_bf16 v[12:15], v[150:153], v[214:217], v[12:15]
	v_mfma_f32_16x16x32_bf16 v[56:59], v[146:149], v[162:165], v[56:59]
	v_mfma_f32_16x16x32_bf16 v[60:63], v[154:157], v[162:165], v[60:63]
	v_mfma_f32_16x16x32_bf16 v[40:43], v[146:149], v[170:173], v[40:43]
	v_mfma_f32_16x16x32_bf16 v[44:47], v[154:157], v[170:173], v[44:47]
	v_mfma_f32_16x16x32_bf16 v[24:27], v[146:149], v[186:189], v[24:27]
	v_mfma_f32_16x16x32_bf16 v[28:31], v[154:157], v[186:189], v[28:31]
	v_mfma_f32_16x16x32_bf16 v[8:11], v[146:149], v[218:221], v[8:11]
	v_mfma_f32_16x16x32_bf16 v[12:15], v[154:157], v[218:221], v[12:15]
	s_barrier
	s_add_u32 s14, s14, 0x40080
	s_addc_u32 s15, s15, 0
	s_add_i32 s16, s16, s58
	v_lshl_add_u64 v[136:137], s[14:15], 0, v[176:177]
	s_mov_b32 m0, s16
	s_nop 0
	global_load_lds_dwordx4 v[136:137], off
	v_lshl_add_u64 v[136:137], s[14:15], 0, v[128:129]
	s_add_i32 m0, s16, 0x2000
	s_nop 0
	global_load_lds_dwordx4 v[136:137], off
	v_add_u32_e32 v136, 0x10000, v139
	ds_read_b128 v[142:145], v136
	ds_read_b128 v[146:149], v136 offset:1024
	ds_read_b128 v[150:153], v136 offset:2048
	ds_read_b128 v[154:157], v136 offset:3072
	s_waitcnt vmcnt(6)
	s_barrier
	v_mfma_f32_16x16x32_bf16 v[48:51], v[222:225], v[158:161], v[48:51]
	v_mfma_f32_16x16x32_bf16 v[52:55], v[230:233], v[158:161], v[52:55]
	v_mfma_f32_16x16x32_bf16 v[32:35], v[222:225], v[166:169], v[32:35]
	v_mfma_f32_16x16x32_bf16 v[36:39], v[230:233], v[166:169], v[36:39]
	v_mfma_f32_16x16x32_bf16 v[16:19], v[222:225], v[182:185], v[16:19]
	v_mfma_f32_16x16x32_bf16 v[20:23], v[230:233], v[182:185], v[20:23]
	v_mfma_f32_16x16x32_bf16 v[0:3], v[222:225], v[214:217], v[0:3]
	v_mfma_f32_16x16x32_bf16 v[4:7], v[230:233], v[214:217], v[4:7]
	v_mfma_f32_16x16x32_bf16 v[48:51], v[226:229], v[162:165], v[48:51]
	v_mfma_f32_16x16x32_bf16 v[52:55], v[234:237], v[162:165], v[52:55]
	v_mfma_f32_16x16x32_bf16 v[32:35], v[226:229], v[170:173], v[32:35]
	v_mfma_f32_16x16x32_bf16 v[36:39], v[234:237], v[170:173], v[36:39]
	v_mfma_f32_16x16x32_bf16 v[16:19], v[226:229], v[186:189], v[16:19]
	v_mfma_f32_16x16x32_bf16 v[20:23], v[234:237], v[186:189], v[20:23]
	v_mfma_f32_16x16x32_bf16 v[0:3], v[226:229], v[218:221], v[0:3]
	v_mfma_f32_16x16x32_bf16 v[4:7], v[234:237], v[218:221], v[4:7]
	s_add_i32 s23, s23, 2
	s_add_u32 s21, s21, 0x100
	s_addc_u32 s22, s22, 0
	s_cmp_gt_u32 s23, 13
	s_mov_b64 s[16:17], s[2:3]
	s_barrier
	s_cbranch_scc0 .LBB0_1199
	v_mul_f32_e32 v252, 0xbfb8aa3b, v120
	v_mul_f32_e32 v253, 0xbfb8aa3b, v121
	v_exp_f32_e32 v252, v252
	v_exp_f32_e32 v253, v253
	v_lshl_add_u32 v141, s0, 8, v138
	s_lshl_b32 s0, s1, 7
	v_add_f32_e32 v252, 1.0, v252
	v_add_f32_e32 v253, 1.0, v253
	v_rcp_f32_e32 v252, v252
	v_rcp_f32_e32 v253, v253
	s_ashr_i32 s1, s0, 31
	v_lshl_add_u64 v[136:137], s[0:1], 1, v[130:131]
	s_movk_i32 s2, 0x1600
	v_pk_mul_f32 v[120:121], v[120:121], v[252:253]
	s_and_b64 vcc, exec, s[12:13]
	v_pk_mul_f32 v[120:121], v[124:125], v[120:121]
	v_mul_f32_e32 v124, 0xbfb8aa3b, v122
	v_mul_f32_e32 v125, 0xbfb8aa3b, v123
	v_exp_f32_e32 v124, v124
	v_exp_f32_e32 v125, v125
	v_cvt_pk_bf16_f32 v120, v120, v121
	v_add_f32_e32 v124, 1.0, v124
	v_add_f32_e32 v125, 1.0, v125
	v_rcp_f32_e32 v124, v124
	v_rcp_f32_e32 v125, v125
	s_nop 0
	v_pk_mul_f32 v[122:123], v[122:123], v[124:125]
	s_nop 0
	v_pk_mul_f32 v[122:123], v[126:127], v[122:123]
	s_nop 0
	v_cvt_pk_bf16_f32 v121, v122, v123
	v_mul_f32_e32 v122, 0xbfb8aa3b, v112
	v_mul_f32_e32 v123, 0xbfb8aa3b, v113
	v_exp_f32_e32 v122, v122
	v_exp_f32_e32 v123, v123
	v_add_f32_e32 v122, 1.0, v122
	v_add_f32_e32 v123, 1.0, v123
	v_rcp_f32_e32 v122, v122
	v_rcp_f32_e32 v123, v123
	s_nop 0
	v_pk_mul_f32 v[112:113], v[112:113], v[122:123]
	s_nop 0
	v_pk_mul_f32 v[112:113], v[116:117], v[112:113]
	v_mul_f32_e32 v116, 0xbfb8aa3b, v114
	v_mul_f32_e32 v117, 0xbfb8aa3b, v115
	v_exp_f32_e32 v116, v116
	v_exp_f32_e32 v117, v117
	v_cvt_pk_bf16_f32 v122, v112, v113
	v_mad_i64_i32 v[112:113], s[0:1], v141, s2, v[136:137]
	v_add_f32_e32 v116, 1.0, v116
	v_add_f32_e32 v117, 1.0, v117
	v_rcp_f32_e32 v116, v116
	v_rcp_f32_e32 v117, v117
	s_nop 0
	v_pk_mul_f32 v[114:115], v[114:115], v[116:117]
	s_nop 0
	v_pk_mul_f32 v[114:115], v[118:119], v[114:115]
	s_nop 0
	v_cvt_pk_bf16_f32 v123, v114, v115
	global_store_dwordx4 v[112:113], v[120:123], off
	v_mul_f32_e32 v112, 0xbfb8aa3b, v104
	v_mul_f32_e32 v113, 0xbfb8aa3b, v105
	v_exp_f32_e32 v112, v112
	v_exp_f32_e32 v113, v113
	v_or_b32_e32 v114, 16, v141
	v_add_f32_e32 v112, 1.0, v112
	v_add_f32_e32 v113, 1.0, v113
	v_rcp_f32_e32 v112, v112
	v_rcp_f32_e32 v113, v113
	s_nop 0
	v_pk_mul_f32 v[104:105], v[104:105], v[112:113]
	s_nop 0
	v_pk_mul_f32 v[104:105], v[108:109], v[104:105]
	v_mul_f32_e32 v108, 0xbfb8aa3b, v106
	v_mul_f32_e32 v109, 0xbfb8aa3b, v107
	v_exp_f32_e32 v108, v108
	v_exp_f32_e32 v109, v109
	v_cvt_pk_bf16_f32 v104, v104, v105
	v_add_f32_e32 v108, 1.0, v108
	v_add_f32_e32 v109, 1.0, v109
	v_rcp_f32_e32 v108, v108
	v_rcp_f32_e32 v109, v109
	s_nop 0
	v_pk_mul_f32 v[106:107], v[106:107], v[108:109]
	s_nop 0
	v_pk_mul_f32 v[106:107], v[110:111], v[106:107]
	s_nop 0
	v_cvt_pk_bf16_f32 v105, v106, v107
	v_mul_f32_e32 v106, 0xbfb8aa3b, v96
	v_mul_f32_e32 v107, 0xbfb8aa3b, v97
	v_exp_f32_e32 v106, v106
	v_exp_f32_e32 v107, v107
	v_add_f32_e32 v106, 1.0, v106
	v_add_f32_e32 v107, 1.0, v107
	v_rcp_f32_e32 v106, v106
	v_rcp_f32_e32 v107, v107
	s_nop 0
	v_pk_mul_f32 v[96:97], v[96:97], v[106:107]
	s_nop 0
	v_pk_mul_f32 v[96:97], v[100:101], v[96:97]
	v_mul_f32_e32 v100, 0xbfb8aa3b, v98
	v_mul_f32_e32 v101, 0xbfb8aa3b, v99
	v_exp_f32_e32 v100, v100
	v_exp_f32_e32 v101, v101
	v_cvt_pk_bf16_f32 v106, v96, v97
	v_mad_i64_i32 v[96:97], s[0:1], v114, s2, v[136:137]
	v_add_f32_e32 v100, 1.0, v100
	v_add_f32_e32 v101, 1.0, v101
	v_rcp_f32_e32 v100, v100
	v_rcp_f32_e32 v101, v101
	s_nop 0
	v_pk_mul_f32 v[98:99], v[98:99], v[100:101]
	s_nop 0
	v_pk_mul_f32 v[98:99], v[102:103], v[98:99]
	s_nop 0
	v_cvt_pk_bf16_f32 v107, v98, v99
	global_store_dwordx4 v[96:97], v[104:107], off
	v_mul_f32_e32 v96, 0xbfb8aa3b, v88
	v_mul_f32_e32 v97, 0xbfb8aa3b, v89
	v_exp_f32_e32 v96, v96
	v_exp_f32_e32 v97, v97
	v_or_b32_e32 v98, 32, v141
	v_add_f32_e32 v96, 1.0, v96
	v_add_f32_e32 v97, 1.0, v97
	v_rcp_f32_e32 v96, v96
	v_rcp_f32_e32 v97, v97
	s_nop 0
	v_pk_mul_f32 v[88:89], v[88:89], v[96:97]
	s_nop 0
	v_pk_mul_f32 v[88:89], v[92:93], v[88:89]
	v_mul_f32_e32 v92, 0xbfb8aa3b, v90
	v_mul_f32_e32 v93, 0xbfb8aa3b, v91
	v_exp_f32_e32 v92, v92
	v_exp_f32_e32 v93, v93
	v_cvt_pk_bf16_f32 v88, v88, v89
	v_add_f32_e32 v92, 1.0, v92
	v_add_f32_e32 v93, 1.0, v93
	v_rcp_f32_e32 v92, v92
	v_rcp_f32_e32 v93, v93
	s_nop 0
	v_pk_mul_f32 v[90:91], v[90:91], v[92:93]
	s_nop 0
	v_pk_mul_f32 v[90:91], v[94:95], v[90:91]
	s_nop 0
	v_cvt_pk_bf16_f32 v89, v90, v91
	v_mul_f32_e32 v90, 0xbfb8aa3b, v80
	v_mul_f32_e32 v91, 0xbfb8aa3b, v81
	v_exp_f32_e32 v90, v90
	v_exp_f32_e32 v91, v91
	v_add_f32_e32 v90, 1.0, v90
	v_add_f32_e32 v91, 1.0, v91
	v_rcp_f32_e32 v90, v90
	v_rcp_f32_e32 v91, v91
	s_nop 0
	v_pk_mul_f32 v[80:81], v[80:81], v[90:91]
	s_nop 0
	v_pk_mul_f32 v[80:81], v[84:85], v[80:81]
	v_mul_f32_e32 v84, 0xbfb8aa3b, v82
	v_mul_f32_e32 v85, 0xbfb8aa3b, v83
	v_exp_f32_e32 v84, v84
	v_exp_f32_e32 v85, v85
	v_cvt_pk_bf16_f32 v90, v80, v81
	v_mad_i64_i32 v[80:81], s[0:1], v98, s2, v[136:137]
	v_add_f32_e32 v84, 1.0, v84
	v_add_f32_e32 v85, 1.0, v85
	v_rcp_f32_e32 v84, v84
	v_rcp_f32_e32 v85, v85
	s_nop 0
	v_pk_mul_f32 v[82:83], v[82:83], v[84:85]
	s_nop 0
	v_pk_mul_f32 v[82:83], v[86:87], v[82:83]
	s_nop 0
	v_cvt_pk_bf16_f32 v91, v82, v83
	global_store_dwordx4 v[80:81], v[88:91], off
	v_mul_f32_e32 v80, 0xbfb8aa3b, v72
	v_mul_f32_e32 v81, 0xbfb8aa3b, v73
	v_exp_f32_e32 v80, v80
	v_exp_f32_e32 v81, v81
	v_or_b32_e32 v82, 48, v141
	v_add_f32_e32 v80, 1.0, v80
	v_add_f32_e32 v81, 1.0, v81
	v_rcp_f32_e32 v80, v80
	v_rcp_f32_e32 v81, v81
	s_nop 0
	v_pk_mul_f32 v[72:73], v[72:73], v[80:81]
	s_nop 0
	v_pk_mul_f32 v[72:73], v[76:77], v[72:73]
	v_mul_f32_e32 v76, 0xbfb8aa3b, v74
	v_mul_f32_e32 v77, 0xbfb8aa3b, v75
	v_exp_f32_e32 v76, v76
	v_exp_f32_e32 v77, v77
	v_cvt_pk_bf16_f32 v72, v72, v73
	v_add_f32_e32 v76, 1.0, v76
	v_add_f32_e32 v77, 1.0, v77
	v_rcp_f32_e32 v76, v76
	v_rcp_f32_e32 v77, v77
	s_nop 0
	v_pk_mul_f32 v[74:75], v[74:75], v[76:77]
	s_nop 0
	v_pk_mul_f32 v[74:75], v[78:79], v[74:75]
	s_nop 0
	v_cvt_pk_bf16_f32 v73, v74, v75
	v_mul_f32_e32 v74, 0xbfb8aa3b, v64
	v_mul_f32_e32 v75, 0xbfb8aa3b, v65
	v_exp_f32_e32 v74, v74
	v_exp_f32_e32 v75, v75
	v_add_f32_e32 v74, 1.0, v74
	v_add_f32_e32 v75, 1.0, v75
	v_rcp_f32_e32 v74, v74
	v_rcp_f32_e32 v75, v75
	s_nop 0
	v_pk_mul_f32 v[64:65], v[64:65], v[74:75]
	s_nop 0
	v_pk_mul_f32 v[64:65], v[68:69], v[64:65]
	v_mul_f32_e32 v68, 0xbfb8aa3b, v66
	v_mul_f32_e32 v69, 0xbfb8aa3b, v67
	v_exp_f32_e32 v68, v68
	v_exp_f32_e32 v69, v69
	v_cvt_pk_bf16_f32 v74, v64, v65
	v_mad_i64_i32 v[64:65], s[0:1], v82, s2, v[136:137]
	v_add_f32_e32 v68, 1.0, v68
	v_add_f32_e32 v69, 1.0, v69
	v_rcp_f32_e32 v68, v68
	v_rcp_f32_e32 v69, v69
	s_nop 0
	v_pk_mul_f32 v[66:67], v[66:67], v[68:69]
	s_nop 0
	v_pk_mul_f32 v[66:67], v[70:71], v[66:67]
	s_nop 0
	v_cvt_pk_bf16_f32 v75, v66, v67
	global_store_dwordx4 v[64:65], v[72:75], off
	v_mul_f32_e32 v64, 0xbfb8aa3b, v56
	v_mul_f32_e32 v65, 0xbfb8aa3b, v57
	v_exp_f32_e32 v64, v64
	v_exp_f32_e32 v65, v65
	v_add_u32_e32 v66, 0x80, v141
	v_add_f32_e32 v64, 1.0, v64
	v_add_f32_e32 v65, 1.0, v65
	v_rcp_f32_e32 v64, v64
	v_rcp_f32_e32 v65, v65
	s_nop 0
	v_pk_mul_f32 v[56:57], v[56:57], v[64:65]
	s_nop 0
	v_pk_mul_f32 v[56:57], v[60:61], v[56:57]
	v_mul_f32_e32 v60, 0xbfb8aa3b, v58
	v_mul_f32_e32 v61, 0xbfb8aa3b, v59
	v_exp_f32_e32 v60, v60
	v_exp_f32_e32 v61, v61
	v_cvt_pk_bf16_f32 v56, v56, v57
	v_add_f32_e32 v60, 1.0, v60
	v_add_f32_e32 v61, 1.0, v61
	v_rcp_f32_e32 v60, v60
	v_rcp_f32_e32 v61, v61
	s_nop 0
	v_pk_mul_f32 v[58:59], v[58:59], v[60:61]
	s_nop 0
	v_pk_mul_f32 v[58:59], v[62:63], v[58:59]
	s_nop 0
	v_cvt_pk_bf16_f32 v57, v58, v59
	v_mul_f32_e32 v58, 0xbfb8aa3b, v48
	v_mul_f32_e32 v59, 0xbfb8aa3b, v49
	v_exp_f32_e32 v58, v58
	v_exp_f32_e32 v59, v59
	v_add_f32_e32 v58, 1.0, v58
	v_add_f32_e32 v59, 1.0, v59
	v_rcp_f32_e32 v58, v58
	v_rcp_f32_e32 v59, v59
	s_nop 0
	v_pk_mul_f32 v[48:49], v[48:49], v[58:59]
	s_nop 0
	v_pk_mul_f32 v[48:49], v[52:53], v[48:49]
	v_mul_f32_e32 v52, 0xbfb8aa3b, v50
	v_mul_f32_e32 v53, 0xbfb8aa3b, v51
	v_exp_f32_e32 v52, v52
	v_exp_f32_e32 v53, v53
	v_cvt_pk_bf16_f32 v58, v48, v49
	v_mad_i64_i32 v[48:49], s[0:1], v66, s2, v[136:137]
	v_add_f32_e32 v52, 1.0, v52
	v_add_f32_e32 v53, 1.0, v53
	v_rcp_f32_e32 v52, v52
	v_rcp_f32_e32 v53, v53
	s_nop 0
	v_pk_mul_f32 v[50:51], v[50:51], v[52:53]
	s_nop 0
	v_pk_mul_f32 v[50:51], v[54:55], v[50:51]
	s_nop 0
	v_cvt_pk_bf16_f32 v59, v50, v51
	global_store_dwordx4 v[48:49], v[56:59], off
	v_mul_f32_e32 v48, 0xbfb8aa3b, v40
	v_mul_f32_e32 v49, 0xbfb8aa3b, v41
	v_exp_f32_e32 v48, v48
	v_exp_f32_e32 v49, v49
	v_add_u32_e32 v50, 0x90, v141
	v_add_f32_e32 v48, 1.0, v48
	v_add_f32_e32 v49, 1.0, v49
	v_rcp_f32_e32 v48, v48
	v_rcp_f32_e32 v49, v49
	s_nop 0
	v_pk_mul_f32 v[40:41], v[40:41], v[48:49]
	s_nop 0
	v_pk_mul_f32 v[40:41], v[44:45], v[40:41]
	v_mul_f32_e32 v44, 0xbfb8aa3b, v42
	v_mul_f32_e32 v45, 0xbfb8aa3b, v43
	v_exp_f32_e32 v44, v44
	v_exp_f32_e32 v45, v45
	v_cvt_pk_bf16_f32 v40, v40, v41
	v_add_f32_e32 v44, 1.0, v44
	v_add_f32_e32 v45, 1.0, v45
	v_rcp_f32_e32 v44, v44
	v_rcp_f32_e32 v45, v45
	s_nop 0
	v_pk_mul_f32 v[42:43], v[42:43], v[44:45]
	s_nop 0
	v_pk_mul_f32 v[42:43], v[46:47], v[42:43]
	s_nop 0
	v_cvt_pk_bf16_f32 v41, v42, v43
	v_mul_f32_e32 v42, 0xbfb8aa3b, v32
	v_mul_f32_e32 v43, 0xbfb8aa3b, v33
	v_exp_f32_e32 v42, v42
	v_exp_f32_e32 v43, v43
	v_add_f32_e32 v42, 1.0, v42
	v_add_f32_e32 v43, 1.0, v43
	v_rcp_f32_e32 v42, v42
	v_rcp_f32_e32 v43, v43
	s_nop 0
	v_pk_mul_f32 v[32:33], v[32:33], v[42:43]
	s_nop 0
	v_pk_mul_f32 v[32:33], v[36:37], v[32:33]
	v_mul_f32_e32 v36, 0xbfb8aa3b, v34
	v_mul_f32_e32 v37, 0xbfb8aa3b, v35
	v_exp_f32_e32 v36, v36
	v_exp_f32_e32 v37, v37
	v_cvt_pk_bf16_f32 v42, v32, v33
	v_mad_i64_i32 v[32:33], s[0:1], v50, s2, v[136:137]
	v_add_f32_e32 v36, 1.0, v36
	v_add_f32_e32 v37, 1.0, v37
	v_rcp_f32_e32 v36, v36
	v_rcp_f32_e32 v37, v37
	s_nop 0
	v_pk_mul_f32 v[34:35], v[34:35], v[36:37]
	s_nop 0
	v_pk_mul_f32 v[34:35], v[38:39], v[34:35]
	s_nop 0
	v_cvt_pk_bf16_f32 v43, v34, v35
	global_store_dwordx4 v[32:33], v[40:43], off
	v_mul_f32_e32 v32, 0xbfb8aa3b, v24
	v_mul_f32_e32 v33, 0xbfb8aa3b, v25
	v_exp_f32_e32 v32, v32
	v_exp_f32_e32 v33, v33
	v_add_u32_e32 v34, 0xa0, v141
	v_add_f32_e32 v32, 1.0, v32
	v_add_f32_e32 v33, 1.0, v33
	v_rcp_f32_e32 v32, v32
	v_rcp_f32_e32 v33, v33
	s_nop 0
	v_pk_mul_f32 v[24:25], v[24:25], v[32:33]
	s_nop 0
	v_pk_mul_f32 v[24:25], v[28:29], v[24:25]
	v_mul_f32_e32 v28, 0xbfb8aa3b, v26
	v_mul_f32_e32 v29, 0xbfb8aa3b, v27
	v_exp_f32_e32 v28, v28
	v_exp_f32_e32 v29, v29
	v_cvt_pk_bf16_f32 v24, v24, v25
	v_add_f32_e32 v28, 1.0, v28
	v_add_f32_e32 v29, 1.0, v29
	v_rcp_f32_e32 v28, v28
	v_rcp_f32_e32 v29, v29
	s_nop 0
	v_pk_mul_f32 v[26:27], v[26:27], v[28:29]
	s_nop 0
	v_pk_mul_f32 v[26:27], v[30:31], v[26:27]
	s_nop 0
	v_cvt_pk_bf16_f32 v25, v26, v27
	v_mul_f32_e32 v26, 0xbfb8aa3b, v16
	v_mul_f32_e32 v27, 0xbfb8aa3b, v17
	v_exp_f32_e32 v26, v26
	v_exp_f32_e32 v27, v27
	v_add_f32_e32 v26, 1.0, v26
	v_add_f32_e32 v27, 1.0, v27
	v_rcp_f32_e32 v26, v26
	v_rcp_f32_e32 v27, v27
	s_nop 0
	v_pk_mul_f32 v[16:17], v[16:17], v[26:27]
	s_nop 0
	v_pk_mul_f32 v[16:17], v[20:21], v[16:17]
	v_mul_f32_e32 v20, 0xbfb8aa3b, v18
	v_mul_f32_e32 v21, 0xbfb8aa3b, v19
	v_exp_f32_e32 v20, v20
	v_exp_f32_e32 v21, v21
	v_cvt_pk_bf16_f32 v26, v16, v17
	v_mad_i64_i32 v[16:17], s[0:1], v34, s2, v[136:137]
	v_add_f32_e32 v20, 1.0, v20
	v_add_f32_e32 v21, 1.0, v21
	v_rcp_f32_e32 v20, v20
	v_rcp_f32_e32 v21, v21
	s_nop 0
	v_pk_mul_f32 v[18:19], v[18:19], v[20:21]
	s_nop 0
	v_pk_mul_f32 v[18:19], v[22:23], v[18:19]
	s_nop 0
	v_cvt_pk_bf16_f32 v27, v18, v19
	global_store_dwordx4 v[16:17], v[24:27], off
	v_mul_f32_e32 v16, 0xbfb8aa3b, v8
	v_mul_f32_e32 v17, 0xbfb8aa3b, v9
	v_exp_f32_e32 v16, v16
	v_exp_f32_e32 v17, v17
	v_add_u32_e32 v18, 0xb0, v141
	v_add_f32_e32 v16, 1.0, v16
	v_add_f32_e32 v17, 1.0, v17
	v_rcp_f32_e32 v16, v16
	v_rcp_f32_e32 v17, v17
	s_nop 0
	v_pk_mul_f32 v[8:9], v[8:9], v[16:17]
	s_nop 0
	v_pk_mul_f32 v[8:9], v[12:13], v[8:9]
	v_mul_f32_e32 v12, 0xbfb8aa3b, v10
	v_mul_f32_e32 v13, 0xbfb8aa3b, v11
	v_exp_f32_e32 v12, v12
	v_exp_f32_e32 v13, v13
	v_cvt_pk_bf16_f32 v8, v8, v9
	v_add_f32_e32 v12, 1.0, v12
	v_add_f32_e32 v13, 1.0, v13
	v_rcp_f32_e32 v12, v12
	v_rcp_f32_e32 v13, v13
	s_nop 0
	v_pk_mul_f32 v[10:11], v[10:11], v[12:13]
	s_nop 0
	v_pk_mul_f32 v[10:11], v[14:15], v[10:11]
	s_nop 0
	v_cvt_pk_bf16_f32 v9, v10, v11
	v_mul_f32_e32 v10, 0xbfb8aa3b, v0
	v_mul_f32_e32 v11, 0xbfb8aa3b, v1
	v_exp_f32_e32 v10, v10
	v_exp_f32_e32 v11, v11
	v_add_f32_e32 v10, 1.0, v10
	v_add_f32_e32 v11, 1.0, v11
	v_rcp_f32_e32 v10, v10
	v_rcp_f32_e32 v11, v11
	s_nop 0
	v_pk_mul_f32 v[0:1], v[0:1], v[10:11]
	s_nop 0
	v_pk_mul_f32 v[0:1], v[4:5], v[0:1]
	v_mul_f32_e32 v4, 0xbfb8aa3b, v2
	v_mul_f32_e32 v5, 0xbfb8aa3b, v3
	v_exp_f32_e32 v4, v4
	v_exp_f32_e32 v5, v5
	v_cvt_pk_bf16_f32 v10, v0, v1
	v_mad_i64_i32 v[0:1], s[0:1], v18, s2, v[136:137]
	v_add_f32_e32 v4, 1.0, v4
	v_add_f32_e32 v5, 1.0, v5
	v_rcp_f32_e32 v4, v4
	v_rcp_f32_e32 v5, v5
	s_mov_b64 s[2:3], -1
	v_pk_mul_f32 v[2:3], v[2:3], v[4:5]
	s_nop 0
	v_pk_mul_f32 v[2:3], v[6:7], v[2:3]
	s_nop 0
	v_cvt_pk_bf16_f32 v11, v2, v3
	global_store_dwordx4 v[0:1], v[8:11], off
	s_cbranch_vccz .LBB0_1195
	v_mov_b32_e32 v120, v177
	v_mov_b32_e32 v124, v177
	v_mov_b32_e32 v104, v177
	v_mov_b32_e32 v108, v177
	v_mov_b32_e32 v88, v177
	v_mov_b32_e32 v92, v177
	v_mov_b32_e32 v72, v177
	v_mov_b32_e32 v76, v177
	v_mov_b32_e32 v112, v177
	v_mov_b32_e32 v116, v177
	v_mov_b32_e32 v96, v177
	v_mov_b32_e32 v100, v177
	v_mov_b32_e32 v80, v177
	v_mov_b32_e32 v84, v177
	v_mov_b32_e32 v64, v177
	v_mov_b32_e32 v68, v177
	v_mov_b32_e32 v56, v177
	v_mov_b32_e32 v60, v177
	v_mov_b32_e32 v40, v177
	v_mov_b32_e32 v44, v177
	v_mov_b32_e32 v24, v177
	v_mov_b32_e32 v28, v177
	v_mov_b32_e32 v8, v177
	v_mov_b32_e32 v12, v177
	v_mov_b32_e32 v48, v177
	v_mov_b32_e32 v52, v177
	v_mov_b32_e32 v32, v177
	v_mov_b32_e32 v36, v177
	v_mov_b32_e32 v16, v177
	v_mov_b32_e32 v20, v177
	v_mov_b32_e32 v0, v177
	v_mov_b32_e32 v4, v177
	s_nop 0
	v_mov_b32_e32 v121, v120
	v_mov_b32_e32 v122, v120
	v_mov_b32_e32 v123, v120
	v_mov_b32_e32 v125, v124
	v_mov_b32_e32 v126, v124
	v_mov_b32_e32 v127, v124
	v_mov_b32_e32 v105, v104
	v_mov_b32_e32 v106, v104
	v_mov_b32_e32 v107, v104
	v_mov_b32_e32 v109, v108
	v_mov_b32_e32 v110, v108
	v_mov_b32_e32 v111, v108
	v_mov_b32_e32 v89, v88
	v_mov_b32_e32 v90, v88
	v_mov_b32_e32 v91, v88
	v_mov_b32_e32 v93, v92
	v_mov_b32_e32 v94, v92
	v_mov_b32_e32 v95, v92
	s_nop 0
	v_mov_b32_e32 v73, v72
	v_mov_b32_e32 v74, v72
	v_mov_b32_e32 v75, v72
	v_mov_b32_e32 v77, v76
	v_mov_b32_e32 v78, v76
	v_mov_b32_e32 v79, v76
	v_mov_b32_e32 v113, v112
	v_mov_b32_e32 v114, v112
	v_mov_b32_e32 v115, v112
	v_mov_b32_e32 v117, v116
	v_mov_b32_e32 v118, v116
	v_mov_b32_e32 v119, v116
	v_mov_b32_e32 v97, v96
	v_mov_b32_e32 v98, v96
	v_mov_b32_e32 v99, v96
	v_mov_b32_e32 v101, v100
	v_mov_b32_e32 v102, v100
	v_mov_b32_e32 v103, v100
	s_nop 0
	v_mov_b32_e32 v81, v80
	v_mov_b32_e32 v82, v80
	v_mov_b32_e32 v83, v80
	v_mov_b32_e32 v85, v84
	v_mov_b32_e32 v86, v84
	v_mov_b32_e32 v87, v84
	v_mov_b32_e32 v65, v64
	v_mov_b32_e32 v66, v64
	v_mov_b32_e32 v67, v64
	v_mov_b32_e32 v69, v68
	v_mov_b32_e32 v70, v68
	v_mov_b32_e32 v71, v68
	v_mov_b32_e32 v57, v56
	v_mov_b32_e32 v58, v56
	v_mov_b32_e32 v59, v56
	v_mov_b32_e32 v61, v60
	v_mov_b32_e32 v62, v60
	v_mov_b32_e32 v63, v60
	s_nop 0
	v_mov_b32_e32 v41, v40
	v_mov_b32_e32 v42, v40
	v_mov_b32_e32 v43, v40
	v_mov_b32_e32 v45, v44
	v_mov_b32_e32 v46, v44
	v_mov_b32_e32 v47, v44
	v_mov_b32_e32 v25, v24
	v_mov_b32_e32 v26, v24
	v_mov_b32_e32 v27, v24
	v_mov_b32_e32 v29, v28
	v_mov_b32_e32 v30, v28
	v_mov_b32_e32 v31, v28
	v_mov_b32_e32 v9, v8
	v_mov_b32_e32 v10, v8
	v_mov_b32_e32 v11, v8
	v_mov_b32_e32 v13, v12
	v_mov_b32_e32 v14, v12
	v_mov_b32_e32 v15, v12
	s_nop 0
	v_mov_b32_e32 v49, v48
	v_mov_b32_e32 v50, v48
	v_mov_b32_e32 v51, v48
	v_mov_b32_e32 v53, v52
	v_mov_b32_e32 v54, v52
	v_mov_b32_e32 v55, v52
	v_mov_b32_e32 v33, v32
	v_mov_b32_e32 v34, v32
	v_mov_b32_e32 v35, v32
	v_mov_b32_e32 v37, v36
	v_mov_b32_e32 v38, v36
	v_mov_b32_e32 v39, v36
	v_mov_b32_e32 v17, v16
	v_mov_b32_e32 v18, v16
	v_mov_b32_e32 v19, v16
	v_mov_b32_e32 v21, v20
	v_mov_b32_e32 v22, v20
	v_mov_b32_e32 v23, v20
	s_mov_b64 s[2:3], 0
	v_mov_b32_e32 v1, v0
	v_mov_b32_e32 v2, v0
	v_mov_b32_e32 v3, v0
	v_mov_b32_e32 v5, v4
	v_mov_b32_e32 v6, v4
	v_mov_b32_e32 v7, v4
	s_branch .LBB0_1195

	.amdhsa_kernel _Z4mega6Params
		.amdhsa_group_segment_fixed_size 0
		.amdhsa_private_segment_fixed_size 0
		.amdhsa_kernarg_size 632
		.amdhsa_user_sgpr_count 2
		.amdhsa_user_sgpr_dispatch_ptr 0
		.amdhsa_user_sgpr_queue_ptr 0
		.amdhsa_user_sgpr_kernarg_segment_ptr 1
		.amdhsa_user_sgpr_dispatch_id 0
		.amdhsa_user_sgpr_kernarg_preload_length 0
		.amdhsa_user_sgpr_kernarg_preload_offset 0
		.amdhsa_user_sgpr_private_segment_size 0
		.amdhsa_uses_dynamic_stack 0
		.amdhsa_enable_private_segment 0
		.amdhsa_system_sgpr_workgroup_id_x 1
		.amdhsa_system_sgpr_workgroup_id_y 0
		.amdhsa_system_sgpr_workgroup_id_z 0
		.amdhsa_system_sgpr_workgroup_info 0
		.amdhsa_system_vgpr_workitem_id 2
		.amdhsa_next_free_vgpr 256
		.amdhsa_next_free_sgpr 100
		.amdhsa_accum_offset 256
		.amdhsa_reserve_vcc 1
		.amdhsa_float_round_mode_32 0
		.amdhsa_float_round_mode_16_64 0
		.amdhsa_float_denorm_mode_32 3
		.amdhsa_float_denorm_mode_16_64 3
		.amdhsa_dx10_clamp 1
		.amdhsa_ieee_mode 1
		.amdhsa_fp16_overflow 0
		.amdhsa_tg_split 0
		.amdhsa_exception_fp_ieee_invalid_op 0
		.amdhsa_exception_fp_denorm_src 0
		.amdhsa_exception_fp_ieee_div_zero 0
		.amdhsa_exception_fp_ieee_overflow 0
		.amdhsa_exception_fp_ieee_underflow 0
		.amdhsa_exception_fp_ieee_inexact 0
		.amdhsa_exception_int_div_zero 0
	.end_amdhsa_kernel

amdhsa.kernels:
  - .agpr_count:     0
    .args:
      - .offset:         0
        .size:           376
        .value_kind:     by_value
      - .offset:         376
        .size:           4
        .value_kind:     hidden_block_count_x
      - .offset:         380
        .size:           4
        .value_kind:     hidden_block_count_y
      - .offset:         384
        .size:           4
        .value_kind:     hidden_block_count_z
      - .offset:         388
        .size:           2
        .value_kind:     hidden_group_size_x
      - .offset:         390
        .size:           2
        .value_kind:     hidden_group_size_y
      - .offset:         392
        .size:           2
        .value_kind:     hidden_group_size_z
      - .offset:         394
        .size:           2
        .value_kind:     hidden_remainder_x
      - .offset:         396
        .size:           2
        .value_kind:     hidden_remainder_y
      - .offset:         398
        .size:           2
        .value_kind:     hidden_remainder_z
      - .offset:         416
        .size:           8
        .value_kind:     hidden_global_offset_x
      - .offset:         424
        .size:           8
        .value_kind:     hidden_global_offset_y
      - .offset:         432
        .size:           8
        .value_kind:     hidden_global_offset_z
      - .offset:         440
        .size:           2
        .value_kind:     hidden_grid_dims
      - .offset:         464
        .size:           8
        .value_kind:     hidden_multigrid_sync_arg
      - .offset:         496
        .size:           4
        .value_kind:     hidden_dynamic_lds_size
    .group_segment_fixed_size: 0
    .kernarg_segment_align: 8
    .kernarg_segment_size: 632
    .language:       OpenCL C
    .language_version:
      - 2
      - 0
    .max_flat_workgroup_size: 512
    .name:           _Z4mega6Params
    .private_segment_fixed_size: 0
    .sgpr_count:     106
    .sgpr_spill_count: 316
    .symbol:         _Z4mega6Params.kd
    .uniform_work_group_size: 1
    .uses_dynamic_stack: false
    .vgpr_count:     256
    .vgpr_spill_count: 0
    .wavefront_size: 64
